# combo7: loop-edge edit - counter/pointer/exit-test SALU moved from after the last MFMA block into the preceding read slot (on combo3)
# baseline (speedup 1.0000x reference)
; #define PG8_STAGE(bufoff, gbase, voff) do { _Pragma("unroll") for (int _i = 0; _i < 2; ++_i) \
;     __builtin_amdgcn_global_load_lds((const unsigned*)((const char*)(gbase) + (voff)[_i]), (LAS unsigned*)(lds + (bufoff) + ldsw + _i * 8192), 16, 0, 0); } while (0)
; #define PG8_LDA(dst, b, h) do { _Pragma("unroll") for (int m = 0; m < 4; ++m) _Pragma("unroll") for (int k = 0; k < 2; ++k) dst[m][k] = *(const LAS bf16x8*)(lds + PG8_SA(b, h) + aoff + m * 2048 + k * 1024); } while (0)
; #define PG8_LDB(dst, b, h) do { _Pragma("unroll") for (int n = 0; n < 2; ++n) _Pragma("unroll") for (int k = 0; k < 2; ++k) dst[n][k] = *(const LAS bf16x8*)(lds + PG8_SB(b, h) + boff + n * 2048 + k * 1024); } while (0)
; #define PG8_MMA(ai, bj, At, Bt) do { __builtin_amdgcn_s_setprio(1); _Pragma("unroll") for (int m = 0; m < 4; ++m) _Pragma("unroll") for (int n = 0; n < 2; ++n) _Pragma("unroll") for (int k = 0; k < 2; ++k) \
;     acc[ai][bj][m][n] = __builtin_amdgcn_mfma_f32_16x16x32_bf16(Bt[n][k], At[m][k], acc[ai][bj][m][n], 0, 0, 0); __builtin_amdgcn_s_setprio(0); } while (0)
; #define PG8_WAIT_V(n) asm volatile("s_waitcnt vmcnt(" #n ")" ::: "memory")
; #define PG8_WAIT_L(n) asm volatile("s_waitcnt lgkmcnt(" #n ")" ::: "memory")
; #define PG8_BAR __builtin_amdgcn_s_barrier()
; #define PG8_SCHED __builtin_amdgcn_sched_barrier(0)
; template <class Epi, class Sched = StaticOrder>
; DI void gemm_phase(LAS unsigned char* lds, const Gemm g, const Sched& S, const Epi& E) {
;     ...
;       PG8_LDB(B0, 0, 0); PG8_SCHED; PG8_LDA(At, 0, 0); PG8_STAGE(PG8_SA(1, 1), a1 + hstep, voffA);
;       PG8_WAIT_L(8); PG8_BAR; PG8_WAIT_L(0); PG8_MMA(0, 0, At, B0); PG8_BAR; PG8_SCHED;
;       PG8_LDB(B1, 0, 1); PG8_STAGE(PG8_SB(0, 0), b2, voffB);
;       PG8_BAR; PG8_WAIT_L(0); PG8_MMA(0, 1, At, B1); PG8_BAR;
;       PG8_LDA(At, 0, 1); PG8_STAGE(PG8_SA(0, 0), a2, voffA);
;       PG8_BAR; PG8_WAIT_L(0); PG8_MMA(1, 0, At, B0); PG8_BAR; PG8_SCHED;
;       PG8_STAGE(PG8_SB(0, 1), b2 + hstep, voffB);
;       PG8_WAIT_V(6); PG8_BAR; PG8_MMA(1, 1, At, B1); PG8_BAR;
;       PG8_LDB(B0, 1, 0); PG8_SCHED; PG8_LDA(At, 1, 0); PG8_STAGE(PG8_SA(0, 1), a2 + hstep, voffA);
;       PG8_WAIT_L(8); PG8_BAR; PG8_WAIT_L(0); PG8_MMA(0, 0, At, B0); PG8_BAR; PG8_SCHED;
;       PG8_LDB(B1, 1, 1); PG8_STAGE(PG8_SB(1, 0), b3, voffB);
;       PG8_BAR; PG8_WAIT_L(0); PG8_MMA(0, 1, At, B1); PG8_BAR;
.LBB0_346:
	s_add_u32 s8, s6, 0xfff80080
	s_addc_u32 s9, s7, -1
	s_cmp_eq_u32 s52, 28
	s_cselect_b32 s11, s31, s9
	s_cselect_b32 s10, s42, s8
	s_cselect_b32 s9, s29, s45
	s_cselect_b32 s8, s43, s44
	s_add_i32 m0, s48, 0xc000
	ds_read_b128 v[162:165], v174
	ds_read_b128 v[166:169], v174 offset:1024
	ds_read_b128 v[178:181], v174 offset:2048
	ds_read_b128 v[182:185], v174 offset:3072
	ds_read_b128 v[186:189], v174 offset:4096
	ds_read_b128 v[190:193], v174 offset:5120
	ds_read_b128 v[194:197], v174 offset:6144
	ds_read_b128 v[198:201], v174 offset:7168
	global_load_lds_dwordx4 v146, s[6:7]
	s_add_i32 m0, s48, 0xe000
	s_nop 0
	global_load_lds_dwordx4 v148, s[6:7]
	s_waitcnt lgkmcnt(0)
	s_setprio 1
	s_barrier
	v_mfma_f32_16x16x32_bf16 v[124:127], v[128:131], v[162:165], v[124:127]
	v_mfma_f32_16x16x32_bf16 v[120:123], v[154:157], v[162:165], v[120:123]
	v_mfma_f32_16x16x32_bf16 v[108:111], v[128:131], v[178:181], v[108:111]
	v_mfma_f32_16x16x32_bf16 v[104:107], v[154:157], v[178:181], v[104:107]
	v_mfma_f32_16x16x32_bf16 v[100:103], v[128:131], v[186:189], v[100:103]
	v_mfma_f32_16x16x32_bf16 v[92:95], v[154:157], v[186:189], v[92:95]
	v_mfma_f32_16x16x32_bf16 v[84:87], v[128:131], v[194:197], v[84:87]
	v_mfma_f32_16x16x32_bf16 v[76:79], v[154:157], v[194:197], v[76:79]
	v_mfma_f32_16x16x32_bf16 v[124:127], v[132:135], v[166:169], v[124:127]
	v_mfma_f32_16x16x32_bf16 v[120:123], v[158:161], v[166:169], v[120:123]
	v_mfma_f32_16x16x32_bf16 v[108:111], v[132:135], v[182:185], v[108:111]
	v_mfma_f32_16x16x32_bf16 v[104:107], v[158:161], v[182:185], v[104:107]
	v_mfma_f32_16x16x32_bf16 v[100:103], v[132:135], v[190:193], v[100:103]
	v_mfma_f32_16x16x32_bf16 v[92:95], v[158:161], v[190:193], v[92:95]
	v_mfma_f32_16x16x32_bf16 v[84:87], v[132:135], v[198:201], v[84:87]
	v_mfma_f32_16x16x32_bf16 v[76:79], v[158:161], v[198:201], v[76:79]
	s_barrier
	s_setprio 0
	s_add_i32 s53, s65, s41
	s_add_u32 s98, s8, 0x80
	s_addc_u32 s99, s9, 0
	s_mov_b32 m0, s53
	ds_read_b128 v[202:205], v175
	ds_read_b128 v[206:209], v175 offset:1024
	ds_read_b128 v[212:215], v175 offset:2048
	ds_read_b128 v[216:219], v175 offset:3072
	global_load_lds_dwordx4 v140, s[8:9]
	s_add_i32 m0, s53, 0x2000
	s_nop 0
	global_load_lds_dwordx4 v136, s[8:9]
	s_waitcnt lgkmcnt(0)
	s_setprio 1
	s_barrier
	v_mfma_f32_16x16x32_bf16 v[116:119], v[202:205], v[162:165], v[116:119]
	v_mfma_f32_16x16x32_bf16 v[112:115], v[212:215], v[162:165], v[112:115]
	v_mfma_f32_16x16x32_bf16 v[96:99], v[202:205], v[178:181], v[96:99]
	v_mfma_f32_16x16x32_bf16 v[88:91], v[212:215], v[178:181], v[88:91]
	v_mfma_f32_16x16x32_bf16 v[80:83], v[202:205], v[186:189], v[80:83]
	v_mfma_f32_16x16x32_bf16 v[72:75], v[212:215], v[186:189], v[72:75]
	v_mfma_f32_16x16x32_bf16 v[68:71], v[202:205], v[194:197], v[68:71]
	v_mfma_f32_16x16x32_bf16 v[64:67], v[212:215], v[194:197], v[64:67]
	v_mfma_f32_16x16x32_bf16 v[116:119], v[206:209], v[166:169], v[116:119]
	v_mfma_f32_16x16x32_bf16 v[112:115], v[216:219], v[166:169], v[112:115]
	v_mfma_f32_16x16x32_bf16 v[96:99], v[206:209], v[182:185], v[96:99]
	v_mfma_f32_16x16x32_bf16 v[88:91], v[216:219], v[182:185], v[88:91]
	v_mfma_f32_16x16x32_bf16 v[80:83], v[206:209], v[190:193], v[80:83]
	v_mfma_f32_16x16x32_bf16 v[72:75], v[216:219], v[190:193], v[72:75]
	v_mfma_f32_16x16x32_bf16 v[68:71], v[206:209], v[198:201], v[68:71]
	v_mfma_f32_16x16x32_bf16 v[64:67], v[216:219], v[198:201], v[64:67]
	s_barrier
	s_setprio 0
	s_mov_b32 m0, s48
	s_add_u32 s100, s10, 0x80
	s_addc_u32 s101, s11, 0
	ds_read_b128 v[162:165], v174 offset:16384
	ds_read_b128 v[166:169], v174 offset:17408
	ds_read_b128 v[178:181], v174 offset:18432
	ds_read_b128 v[182:185], v174 offset:19456
	ds_read_b128 v[186:189], v174 offset:20480
	ds_read_b128 v[190:193], v174 offset:21504
	ds_read_b128 v[194:197], v174 offset:22528
	ds_read_b128 v[198:201], v174 offset:23552
	global_load_lds_dwordx4 v142, s[10:11]
	s_mov_b32 m0, s49
	s_nop 0
	global_load_lds_dwordx4 v138, s[10:11]
	s_waitcnt vmcnt(10)
	s_waitcnt lgkmcnt(0)
	s_setprio 1
	s_barrier
	v_mfma_f32_16x16x32_bf16 v[60:63], v[128:131], v[162:165], v[60:63]
	v_mfma_f32_16x16x32_bf16 v[56:59], v[154:157], v[162:165], v[56:59]
	v_mfma_f32_16x16x32_bf16 v[52:55], v[128:131], v[178:181], v[52:55]
	v_mfma_f32_16x16x32_bf16 v[44:47], v[154:157], v[178:181], v[44:47]
	v_mfma_f32_16x16x32_bf16 v[36:39], v[128:131], v[186:189], v[36:39]
	v_mfma_f32_16x16x32_bf16 v[28:31], v[154:157], v[186:189], v[28:31]
	v_mfma_f32_16x16x32_bf16 v[20:23], v[128:131], v[194:197], v[20:23]
	v_mfma_f32_16x16x32_bf16 v[12:15], v[154:157], v[194:197], v[12:15]
	v_mfma_f32_16x16x32_bf16 v[60:63], v[132:135], v[166:169], v[60:63]
	v_mfma_f32_16x16x32_bf16 v[56:59], v[158:161], v[166:169], v[56:59]
	v_mfma_f32_16x16x32_bf16 v[52:55], v[132:135], v[182:185], v[52:55]
	v_mfma_f32_16x16x32_bf16 v[44:47], v[158:161], v[182:185], v[44:47]
	v_mfma_f32_16x16x32_bf16 v[36:39], v[132:135], v[190:193], v[36:39]
	v_mfma_f32_16x16x32_bf16 v[28:31], v[158:161], v[190:193], v[28:31]
	v_mfma_f32_16x16x32_bf16 v[20:23], v[132:135], v[198:201], v[20:23]
	v_mfma_f32_16x16x32_bf16 v[12:15], v[158:161], v[198:201], v[12:15]
	s_barrier
	s_setprio 0
	s_add_u32 s54, s8, 0x80000
	s_addc_u32 s55, s9, 0
	s_add_i32 s53, s72, s41
	s_mov_b32 m0, s53
	s_nop 0
	global_load_lds_dwordx4 v140, s[54:55]
	s_add_i32 m0, s53, 0x2000
	s_nop 0
	global_load_lds_dwordx4 v136, s[54:55]
	s_add_i32 s53, 0, 0x18000
	v_add_u32_e32 v158, s53, v171
	ds_read_b128 v[128:131], v158
	ds_read_b128 v[132:135], v158 offset:1024
	ds_read_b128 v[154:157], v158 offset:2048
	ds_read_b128 v[158:161], v158 offset:3072
	s_waitcnt vmcnt(6)
	s_setprio 1
	s_barrier
; #define PG8_STAGE(bufoff, gbase, voff) do { _Pragma("unroll") for (int _i = 0; _i < 2; ++_i) \
;     __builtin_amdgcn_global_load_lds((const unsigned*)((const char*)(gbase) + (voff)[_i]), (LAS unsigned*)(lds + (bufoff) + ldsw + _i * 8192), 16, 0, 0); } while (0)
; #define PG8_LDA(dst, b, h) do { _Pragma("unroll") for (int m = 0; m < 4; ++m) _Pragma("unroll") for (int k = 0; k < 2; ++k) dst[m][k] = *(const LAS bf16x8*)(lds + PG8_SA(b, h) + aoff + m * 2048 + k * 1024); } while (0)
; #define PG8_LDB(dst, b, h) do { _Pragma("unroll") for (int n = 0; n < 2; ++n) _Pragma("unroll") for (int k = 0; k < 2; ++k) dst[n][k] = *(const LAS bf16x8*)(lds + PG8_SB(b, h) + boff + n * 2048 + k * 1024); } while (0)
; #define PG8_MMA(ai, bj, At, Bt) do { __builtin_amdgcn_s_setprio(1); _Pragma("unroll") for (int m = 0; m < 4; ++m) _Pragma("unroll") for (int n = 0; n < 2; ++n) _Pragma("unroll") for (int k = 0; k < 2; ++k) \
;     acc[ai][bj][m][n] = __builtin_amdgcn_mfma_f32_16x16x32_bf16(Bt[n][k], At[m][k], acc[ai][bj][m][n], 0, 0, 0); __builtin_amdgcn_s_setprio(0); } while (0)
; #define PG8_WAIT_V(n) asm volatile("s_waitcnt vmcnt(" #n ")" ::: "memory")
; #define PG8_WAIT_L(n) asm volatile("s_waitcnt lgkmcnt(" #n ")" ::: "memory")
; #define PG8_BAR __builtin_amdgcn_s_barrier()
; #define PG8_SCHED __builtin_amdgcn_sched_barrier(0)
; template <class Epi, class Sched = StaticOrder>
; DI void gemm_phase(LAS unsigned char* lds, const Gemm g, const Sched& S, const Epi& E) {
;     ...
;       PG8_LDA(At, 0, 1); PG8_STAGE(PG8_SA(0, 0), a2, voffA);
;       PG8_BAR; PG8_WAIT_L(0); PG8_MMA(1, 0, At, B0); PG8_BAR; PG8_SCHED;
;       PG8_STAGE(PG8_SB(0, 1), b2 + hstep, voffB);
;       PG8_WAIT_V(6); PG8_BAR; PG8_MMA(1, 1, At, B1); PG8_BAR;
;       PG8_LDB(B0, 1, 0); PG8_SCHED; PG8_LDA(At, 1, 0); PG8_STAGE(PG8_SA(0, 1), a2 + hstep, voffA);
;       PG8_WAIT_L(8); PG8_BAR; PG8_WAIT_L(0); PG8_MMA(0, 0, At, B0); PG8_BAR; PG8_SCHED;
;       PG8_LDB(B1, 1, 1); PG8_STAGE(PG8_SB(1, 0), b3, voffB);
;       PG8_BAR; PG8_WAIT_L(0); PG8_MMA(0, 1, At, B1); PG8_BAR;
;       PG8_LDA(At, 1, 1); PG8_STAGE(PG8_SA(1, 0), a3, voffA);
;       PG8_BAR; PG8_WAIT_L(0); PG8_MMA(1, 0, At, B0); PG8_BAR; PG8_SCHED;
	v_mfma_f32_16x16x32_bf16 v[48:51], v[202:205], v[162:165], v[48:51]
	v_mfma_f32_16x16x32_bf16 v[40:43], v[212:215], v[162:165], v[40:43]
	v_mfma_f32_16x16x32_bf16 v[32:35], v[202:205], v[178:181], v[32:35]
	v_mfma_f32_16x16x32_bf16 v[24:27], v[212:215], v[178:181], v[24:27]
	v_mfma_f32_16x16x32_bf16 v[16:19], v[202:205], v[186:189], v[16:19]
	v_mfma_f32_16x16x32_bf16 v[8:11], v[212:215], v[186:189], v[8:11]
	v_mfma_f32_16x16x32_bf16 v[4:7], v[202:205], v[194:197], v[4:7]
	v_mfma_f32_16x16x32_bf16 v[0:3], v[212:215], v[194:197], v[0:3]
	v_mfma_f32_16x16x32_bf16 v[48:51], v[206:209], v[166:169], v[48:51]
	v_mfma_f32_16x16x32_bf16 v[40:43], v[216:219], v[166:169], v[40:43]
	v_mfma_f32_16x16x32_bf16 v[32:35], v[206:209], v[182:185], v[32:35]
	v_mfma_f32_16x16x32_bf16 v[24:27], v[216:219], v[182:185], v[24:27]
	v_mfma_f32_16x16x32_bf16 v[16:19], v[206:209], v[190:193], v[16:19]
	v_mfma_f32_16x16x32_bf16 v[8:11], v[216:219], v[190:193], v[8:11]
	v_mfma_f32_16x16x32_bf16 v[4:7], v[206:209], v[198:201], v[4:7]
	v_mfma_f32_16x16x32_bf16 v[0:3], v[216:219], v[198:201], v[0:3]
	s_barrier
	s_setprio 0
	s_add_u32 s10, s10, 0x80000
	s_addc_u32 s11, s11, 0
	s_mov_b32 m0, s50
	ds_read_b128 v[162:165], v174 offset:32768
	ds_read_b128 v[166:169], v174 offset:33792
	ds_read_b128 v[178:181], v174 offset:34816
	ds_read_b128 v[182:185], v174 offset:35840
	ds_read_b128 v[186:189], v174 offset:36864
	ds_read_b128 v[190:193], v174 offset:37888
	ds_read_b128 v[194:197], v174 offset:38912
	ds_read_b128 v[198:201], v174 offset:39936
	global_load_lds_dwordx4 v142, s[10:11]
	s_mov_b32 m0, s51
	s_nop 0
	global_load_lds_dwordx4 v138, s[10:11]
	s_waitcnt lgkmcnt(0)
	s_setprio 1
	s_barrier
	v_mfma_f32_16x16x32_bf16 v[124:127], v[128:131], v[162:165], v[124:127]
	v_mfma_f32_16x16x32_bf16 v[120:123], v[154:157], v[162:165], v[120:123]
	v_mfma_f32_16x16x32_bf16 v[108:111], v[128:131], v[178:181], v[108:111]
	v_mfma_f32_16x16x32_bf16 v[104:107], v[154:157], v[178:181], v[104:107]
	v_mfma_f32_16x16x32_bf16 v[100:103], v[128:131], v[186:189], v[100:103]
	v_mfma_f32_16x16x32_bf16 v[92:95], v[154:157], v[186:189], v[92:95]
	v_mfma_f32_16x16x32_bf16 v[84:87], v[128:131], v[194:197], v[84:87]
	v_mfma_f32_16x16x32_bf16 v[76:79], v[154:157], v[194:197], v[76:79]
	v_mfma_f32_16x16x32_bf16 v[124:127], v[132:135], v[166:169], v[124:127]
	v_mfma_f32_16x16x32_bf16 v[120:123], v[158:161], v[166:169], v[120:123]
	v_mfma_f32_16x16x32_bf16 v[108:111], v[132:135], v[182:185], v[108:111]
	v_mfma_f32_16x16x32_bf16 v[104:107], v[158:161], v[182:185], v[104:107]
	v_mfma_f32_16x16x32_bf16 v[100:103], v[132:135], v[190:193], v[100:103]
	v_mfma_f32_16x16x32_bf16 v[92:95], v[158:161], v[190:193], v[92:95]
	v_mfma_f32_16x16x32_bf16 v[84:87], v[132:135], v[198:201], v[84:87]
	v_mfma_f32_16x16x32_bf16 v[76:79], v[158:161], v[198:201], v[76:79]
	s_barrier
	s_setprio 0
	s_add_i32 s10, 0, 0x1c000
	s_add_i32 s11, s53, s41
	v_add_u32_e32 v177, s10, v171
	s_mov_b32 m0, s11
	ds_read_b128 v[202:205], v177
	ds_read_b128 v[206:209], v177 offset:1024
	ds_read_b128 v[212:215], v177 offset:2048
	ds_read_b128 v[216:219], v177 offset:3072
	global_load_lds_dwordx4 v140, s[98:99]
	s_add_i32 m0, s11, 0x2000
	s_nop 0
	global_load_lds_dwordx4 v136, s[98:99]
	s_waitcnt lgkmcnt(0)
	s_setprio 1
	s_barrier
	v_mfma_f32_16x16x32_bf16 v[116:119], v[202:205], v[162:165], v[116:119]
	v_mfma_f32_16x16x32_bf16 v[112:115], v[212:215], v[162:165], v[112:115]
	v_mfma_f32_16x16x32_bf16 v[96:99], v[202:205], v[178:181], v[96:99]
	v_mfma_f32_16x16x32_bf16 v[88:91], v[212:215], v[178:181], v[88:91]
	v_mfma_f32_16x16x32_bf16 v[80:83], v[202:205], v[186:189], v[80:83]
	v_mfma_f32_16x16x32_bf16 v[72:75], v[212:215], v[186:189], v[72:75]
	v_mfma_f32_16x16x32_bf16 v[68:71], v[202:205], v[194:197], v[68:71]
	v_mfma_f32_16x16x32_bf16 v[64:67], v[212:215], v[194:197], v[64:67]
	v_mfma_f32_16x16x32_bf16 v[116:119], v[206:209], v[166:169], v[116:119]
	v_mfma_f32_16x16x32_bf16 v[112:115], v[216:219], v[166:169], v[112:115]
	v_mfma_f32_16x16x32_bf16 v[96:99], v[206:209], v[182:185], v[96:99]
	v_mfma_f32_16x16x32_bf16 v[88:91], v[216:219], v[182:185], v[88:91]
	v_mfma_f32_16x16x32_bf16 v[80:83], v[206:209], v[190:193], v[80:83]
	v_mfma_f32_16x16x32_bf16 v[72:75], v[216:219], v[190:193], v[72:75]
	v_mfma_f32_16x16x32_bf16 v[68:71], v[206:209], v[198:201], v[68:71]
	v_mfma_f32_16x16x32_bf16 v[64:67], v[216:219], v[198:201], v[64:67]
	s_barrier
	s_setprio 0
	s_mov_b32 m0, s56
	ds_read_b128 v[162:165], v174 offset:49152
	ds_read_b128 v[166:169], v174 offset:50176
	ds_read_b128 v[178:181], v174 offset:51200
	ds_read_b128 v[182:185], v174 offset:52224
	ds_read_b128 v[186:189], v174 offset:53248
	ds_read_b128 v[190:193], v174 offset:54272
	ds_read_b128 v[194:197], v174 offset:55296
	ds_read_b128 v[198:201], v174 offset:56320
	global_load_lds_dwordx4 v142, s[100:101]
	s_mov_b32 m0, s57
	s_nop 0
	global_load_lds_dwordx4 v138, s[100:101]
	s_waitcnt vmcnt(10)
	s_waitcnt lgkmcnt(0)
	s_setprio 1
	s_barrier
	v_mfma_f32_16x16x32_bf16 v[60:63], v[128:131], v[162:165], v[60:63]
	v_mfma_f32_16x16x32_bf16 v[56:59], v[154:157], v[162:165], v[56:59]
	v_mfma_f32_16x16x32_bf16 v[52:55], v[128:131], v[178:181], v[52:55]
	v_mfma_f32_16x16x32_bf16 v[44:47], v[154:157], v[178:181], v[44:47]
	v_mfma_f32_16x16x32_bf16 v[36:39], v[128:131], v[186:189], v[36:39]
	v_mfma_f32_16x16x32_bf16 v[28:31], v[154:157], v[186:189], v[28:31]
	v_mfma_f32_16x16x32_bf16 v[20:23], v[128:131], v[194:197], v[20:23]
	v_mfma_f32_16x16x32_bf16 v[12:15], v[154:157], v[194:197], v[12:15]
	v_mfma_f32_16x16x32_bf16 v[60:63], v[132:135], v[166:169], v[60:63]
	v_mfma_f32_16x16x32_bf16 v[56:59], v[158:161], v[166:169], v[56:59]
	v_mfma_f32_16x16x32_bf16 v[52:55], v[132:135], v[182:185], v[52:55]
	v_mfma_f32_16x16x32_bf16 v[44:47], v[158:161], v[182:185], v[44:47]
	v_mfma_f32_16x16x32_bf16 v[36:39], v[132:135], v[190:193], v[36:39]
	v_mfma_f32_16x16x32_bf16 v[28:31], v[158:161], v[190:193], v[28:31]
	v_mfma_f32_16x16x32_bf16 v[20:23], v[132:135], v[198:201], v[20:23]
	v_mfma_f32_16x16x32_bf16 v[12:15], v[158:161], v[198:201], v[12:15]
	s_barrier
; #define PG8_STAGE(bufoff, gbase, voff) do { _Pragma("unroll") for (int _i = 0; _i < 2; ++_i) \
;     __builtin_amdgcn_global_load_lds((const unsigned*)((const char*)(gbase) + (voff)[_i]), (LAS unsigned*)(lds + (bufoff) + ldsw + _i * 8192), 16, 0, 0); } while (0)
; #define PG8_LDA(dst, b, h) do { _Pragma("unroll") for (int m = 0; m < 4; ++m) _Pragma("unroll") for (int k = 0; k < 2; ++k) dst[m][k] = *(const LAS bf16x8*)(lds + PG8_SA(b, h) + aoff + m * 2048 + k * 1024); } while (0)
; #define PG8_LDB(dst, b, h) do { _Pragma("unroll") for (int n = 0; n < 2; ++n) _Pragma("unroll") for (int k = 0; k < 2; ++k) dst[n][k] = *(const LAS bf16x8*)(lds + PG8_SB(b, h) + boff + n * 2048 + k * 1024); } while (0)
; #define PG8_MMA(ai, bj, At, Bt) do { __builtin_amdgcn_s_setprio(1); _Pragma("unroll") for (int m = 0; m < 4; ++m) _Pragma("unroll") for (int n = 0; n < 2; ++n) _Pragma("unroll") for (int k = 0; k < 2; ++k) \
;     acc[ai][bj][m][n] = __builtin_amdgcn_mfma_f32_16x16x32_bf16(Bt[n][k], At[m][k], acc[ai][bj][m][n], 0, 0, 0); __builtin_amdgcn_s_setprio(0); } while (0)
; #define PG8_WAIT_V(n) asm volatile("s_waitcnt vmcnt(" #n ")" ::: "memory")
; #define PG8_WAIT_L(n) asm volatile("s_waitcnt lgkmcnt(" #n ")" ::: "memory")
; #define PG8_BAR __builtin_amdgcn_s_barrier()
; #define PG8_SCHED __builtin_amdgcn_sched_barrier(0)
; DI float row_rstd(const float* ssq, int row, int fq) {
;   const f32x4 a = *(const f32x4*)(ssq + (size_t)row * 32 + fq * 8), b = *(const f32x4*)(ssq + (size_t)row * 32 + fq * 8 + 4);
;   float sm = ((a[0] + a[1]) + (a[2] + a[3])) + ((b[0] + b[1]) + (b[2] + b[3]));
;   sm += __shfl_xor(sm, 16); sm += __shfl_xor(sm, 32);
;   return rsqrtf(sm * (1.0f / 2048.f) + 1e-6f);
; }
; template <class Epi, class Sched = StaticOrder>
; DI void gemm_phase(LAS unsigned char* lds, const Gemm g, const Sched& S, const Epi& E) {
;     ...
;       PG8_LDB(B1, 1, 1); PG8_STAGE(PG8_SB(1, 0), b3, voffB);
;       PG8_BAR; PG8_WAIT_L(0); PG8_MMA(0, 1, At, B1); PG8_BAR;
;       PG8_LDA(At, 1, 1); PG8_STAGE(PG8_SA(1, 0), a3, voffA);
;       PG8_BAR; PG8_WAIT_L(0); PG8_MMA(1, 0, At, B0); PG8_BAR; PG8_SCHED;
;       PG8_STAGE(PG8_SB(1, 1), b3 + hstep, voffB);
;       PG8_WAIT_V(6); PG8_BAR; PG8_MMA(1, 1, At, B1); PG8_BAR;
	s_setprio 0
	s_add_u32 s8, s8, 0x80080
	s_addc_u32 s9, s9, 0
	s_add_i32 s10, s10, s41
	s_mov_b32 m0, s10
	s_nop 0
	global_load_lds_dwordx4 v140, s[8:9]
	s_add_i32 m0, s10, 0x2000
	s_nop 0
	global_load_lds_dwordx4 v136, s[8:9]
	ds_read_b128 v[128:131], v173
	ds_read_b128 v[132:135], v173 offset:1024
	ds_read_b128 v[154:157], v173 offset:2048
	ds_read_b128 v[158:161], v173 offset:3072
	s_waitcnt vmcnt(6)
	s_add_i32 s52, s52, 2
	s_add_u32 s6, s6, 0x100
	s_addc_u32 s7, s7, 0
	s_add_u32 s44, s44, 0x100
	s_addc_u32 s45, s45, 0
	s_cmp_gt_u32 s52, 29
	s_setprio 1
	s_barrier
	v_mfma_f32_16x16x32_bf16 v[48:51], v[202:205], v[162:165], v[48:51]
	v_mfma_f32_16x16x32_bf16 v[40:43], v[212:215], v[162:165], v[40:43]
	v_mfma_f32_16x16x32_bf16 v[32:35], v[202:205], v[178:181], v[32:35]
	v_mfma_f32_16x16x32_bf16 v[24:27], v[212:215], v[178:181], v[24:27]
	v_mfma_f32_16x16x32_bf16 v[16:19], v[202:205], v[186:189], v[16:19]
	v_mfma_f32_16x16x32_bf16 v[8:11], v[212:215], v[186:189], v[8:11]
	v_mfma_f32_16x16x32_bf16 v[4:7], v[202:205], v[194:197], v[4:7]
	v_mfma_f32_16x16x32_bf16 v[0:3], v[212:215], v[194:197], v[0:3]
	v_mfma_f32_16x16x32_bf16 v[48:51], v[206:209], v[166:169], v[48:51]
	v_mfma_f32_16x16x32_bf16 v[40:43], v[216:219], v[166:169], v[40:43]
	v_mfma_f32_16x16x32_bf16 v[32:35], v[206:209], v[182:185], v[32:35]
	v_mfma_f32_16x16x32_bf16 v[24:27], v[216:219], v[182:185], v[24:27]
	v_mfma_f32_16x16x32_bf16 v[16:19], v[206:209], v[190:193], v[16:19]
	v_mfma_f32_16x16x32_bf16 v[8:11], v[216:219], v[190:193], v[8:11]
	v_mfma_f32_16x16x32_bf16 v[4:7], v[206:209], v[198:201], v[4:7]
	v_mfma_f32_16x16x32_bf16 v[0:3], v[216:219], v[198:201], v[0:3]
	s_barrier
	s_setprio 0
	s_cbranch_scc0 .LBB0_346
	s_waitcnt lgkmcnt(0)
	v_lshl_add_u32 v168, s4, 8, v170
	v_ashrrev_i32_e32 v169, 31, v168
	v_or_b32_e32 v154, 16, v168
	v_lshlrev_b64 v[128:129], 7, v[168:169]
	v_ashrrev_i32_e32 v155, 31, v154
	v_lshl_add_u64 v[128:129], v[144:145], 0, v[128:129]
	v_lshlrev_b64 v[156:157], 7, v[154:155]
	global_load_dwordx4 v[132:135], v[128:129], off
	s_nop 0
	global_load_dwordx4 v[128:131], v[128:129], off offset:16
	v_lshl_add_u64 v[156:157], v[144:145], 0, v[156:157]
	global_load_dwordx4 v[178:181], v[156:157], off
	global_load_dwordx4 v[182:185], v[156:157], off offset:16
	v_or_b32_e32 v160, 32, v168
	v_ashrrev_i32_e32 v161, 31, v160
	v_lshlrev_b64 v[156:157], 7, v[160:161]
	v_lshl_add_u64 v[156:157], v[144:145], 0, v[156:157]
	global_load_dwordx4 v[186:189], v[156:157], off
	global_load_dwordx4 v[190:193], v[156:157], off offset:16
	v_or_b32_e32 v156, 48, v168
	v_ashrrev_i32_e32 v157, 31, v156
	v_lshlrev_b64 v[158:159], 7, v[156:157]
	v_lshl_add_u64 v[158:159], v[144:145], 0, v[158:159]
	global_load_dwordx4 v[194:197], v[158:159], off
	global_load_dwordx4 v[198:201], v[158:159], off offset:16
	v_add_u32_e32 v164, 0x80, v168
	v_ashrrev_i32_e32 v165, 31, v164
	v_lshlrev_b64 v[158:159], 7, v[164:165]
	v_lshl_add_u64 v[158:159], v[144:145], 0, v[158:159]
	global_load_dwordx4 v[202:205], v[158:159], off
	global_load_dwordx4 v[206:209], v[158:159], off offset:16
	v_add_u32_e32 v158, 0x90, v168
	v_ashrrev_i32_e32 v159, 31, v158
	v_lshlrev_b64 v[162:163], 7, v[158:159]
	v_lshl_add_u64 v[162:163], v[144:145], 0, v[162:163]
	global_load_dwordx4 v[212:215], v[162:163], off
	global_load_dwordx4 v[216:219], v[162:163], off offset:16
	v_add_u32_e32 v166, 0xa0, v168
	v_ashrrev_i32_e32 v167, 31, v166
	v_lshlrev_b64 v[162:163], 7, v[166:167]
	v_lshl_add_u64 v[162:163], v[144:145], 0, v[162:163]
	global_load_dwordx4 v[220:223], v[162:163], off
	global_load_dwordx4 v[224:227], v[162:163], off offset:16
	v_add_u32_e32 v162, 0xb0, v168
	v_ashrrev_i32_e32 v163, 31, v162
	v_lshlrev_b64 v[228:229], 7, v[162:163]
	v_lshl_add_u64 v[232:233], v[144:145], 0, v[228:229]
	global_load_dwordx4 v[228:231], v[232:233], off
	s_nop 0
	global_load_dwordx4 v[232:235], v[232:233], off offset:16
	s_waitcnt vmcnt(0)
	v_mov_b32_e32 v236, v132
	v_mov_b32_e32 v237, v128
	v_mov_b32_e32 v128, v133
	v_mov_b32_e32 v132, v134
	v_mov_b32_e32 v133, v130
	v_mov_b32_e32 v130, v135
	v_pk_add_f32 v[130:131], v[132:133], v[130:131]
	v_mov_b32_e32 v132, v178
	v_mov_b32_e32 v133, v182
	v_mov_b32_e32 v182, v179
	v_mov_b32_e32 v134, v180
	v_mov_b32_e32 v135, v184
	v_mov_b32_e32 v184, v181
	v_pk_add_f32 v[128:129], v[236:237], v[128:129]
	v_pk_add_f32 v[132:133], v[132:133], v[182:183]
	v_pk_add_f32 v[134:135], v[134:135], v[184:185]
	v_pk_add_f32 v[128:129], v[128:129], v[130:131]
	v_pk_add_f32 v[130:131], v[132:133], v[134:135]
	v_mov_b32_e32 v133, v128
	v_mov_b32_e32 v132, v130
	v_and_b32_e32 v130, 64, v176
	v_add_u32_e32 v155, 64, v130
	v_xor_b32_e32 v130, 16, v176
	v_cmp_lt_i32_e32 vcc, v130, v155
	v_mov_b32_e32 v128, v131
	v_pk_add_f32 v[128:129], v[132:133], v[128:129]
	v_cndmask_b32_e32 v130, v176, v130, vcc
	v_lshlrev_b32_e32 v157, 2, v130
	ds_bpermute_b32 v131, v157, v129
	ds_bpermute_b32 v130, v157, v128
	v_mov_b32_e32 v178, v186
	v_mov_b32_e32 v179, v190
	v_mov_b32_e32 v190, v187
	v_mov_b32_e32 v186, v194
	s_waitcnt lgkmcnt(0)
	v_pk_add_f32 v[128:129], v[128:129], v[130:131]
	v_xor_b32_e32 v130, 32, v176
	v_cmp_lt_i32_e32 vcc, v130, v155
	v_mov_b32_e32 v187, v198
	v_mov_b32_e32 v198, v195
	v_cndmask_b32_e32 v130, v176, v130, vcc
	v_lshlrev_b32_e32 v155, 2, v130
	ds_bpermute_b32 v131, v155, v129
	ds_bpermute_b32 v130, v155, v128
	v_pk_add_f32 v[182:183], v[186:187], v[198:199]
	v_mov_b32_e32 v180, v188
	v_mov_b32_e32 v181, v192
	v_mov_b32_e32 v192, v189
	s_waitcnt lgkmcnt(0)
; DI unsigned pack2(float lo, float hi) { f32x2 v = {lo, hi}; bf16v2 r = __builtin_convertvector(v, bf16v2); return __builtin_bit_cast(unsigned, r); }
; DI float row_rstd(const float* ssq, int row, int fq) {
;   const f32x4 a = *(const f32x4*)(ssq + (size_t)row * 32 + fq * 8), b = *(const f32x4*)(ssq + (size_t)row * 32 + fq * 8 + 4);
;   float sm = ((a[0] + a[1]) + (a[2] + a[3])) + ((b[0] + b[1]) + (b[2] + b[3]));
;   sm += __shfl_xor(sm, 16); sm += __shfl_xor(sm, 32);
;   return rsqrtf(sm * (1.0f / 2048.f) + 1e-6f);
; }
;   DI void operator()(const f32x4 (&acc)[2][2][4][2], const Unit& u, int wr, int wc, int fr, int fq) const {
;     const int row0 = u.pm * BM + wr * 64 + fr, col0 = u.pn * BM + wc * 32 + 8 * fq;
;     float rsv[2][4];
; #pragma unroll
;     for (int ai = 0; ai < 2; ++ai)
; #pragma unroll
;       for (int m = 0; m < 4; ++m) rsv[ai][m] = row_rstd(ssq, row0 + ai * HALF + m * 16, fq);
; #pragma unroll
;     for (int ai = 0; ai < 2; ++ai)
; #pragma unroll
;       for (int m = 0; m < 4; ++m) {
;         const int row = row0 + ai * HALF + m * 16;
;         const float rs = rsv[ai][m];
;         bf16_t* rowp = O + (size_t)row * ldc + col0;
; #pragma unroll
;         for (int bj = 0; bj < 2; ++bj) {
;           const f32x4 v0 = acc[ai][bj][m][0] * rs, v1 = acc[ai][bj][m][1] * rs;
;           u32x4 w; w.x = pack2(v0[0], v0[1]); w.y = pack2(v0[2], v0[3]); w.z = pack2(v1[0], v1[1]); w.w = pack2(v1[2], v1[3]);
;           *(u32x4*)(rowp + bj * HALF) = w;
;         }
;       }
	v_pk_add_f32 v[128:129], v[128:129], v[130:131]
	v_mov_b64_e32 v[130:131], s[26:27]
	v_pk_fma_f32 v[128:129], v[128:129], s[24:25], v[130:131] op_sel_hi:[1,0,0]
	v_mov_b32_e32 v188, v196
	v_mul_f32_e32 v159, 0x4b800000, v129
	v_cmp_gt_f32_e32 vcc, s73, v129
	v_mov_b32_e32 v189, v200
	v_mov_b32_e32 v200, v197
	v_cndmask_b32_e32 v129, v129, v159, vcc
	v_rsq_f32_e32 v129, v129
	v_pk_add_f32 v[178:179], v[178:179], v[190:191]
	v_pk_add_f32 v[180:181], v[180:181], v[192:193]
	v_pk_add_f32 v[184:185], v[188:189], v[200:201]
	v_mul_f32_e32 v159, 0x45800000, v129
	v_cndmask_b32_e32 v198, v129, v159, vcc
	v_pk_mul_f32 v[126:127], v[126:127], v[198:199] op_sel_hi:[1,0]
	v_pk_mul_f32 v[124:125], v[124:125], v[198:199] op_sel_hi:[1,0]
	v_pk_mul_f32 v[122:123], v[122:123], v[198:199] op_sel_hi:[1,0]
	v_pk_mul_f32 v[120:121], v[120:121], v[198:199] op_sel_hi:[1,0]
	v_cvt_pk_bf16_f32 v124, v124, v125
	v_cvt_pk_bf16_f32 v125, v126, v127
	v_cvt_pk_bf16_f32 v127, v122, v123
	v_lshl_or_b32 v122, s5, 8, v172
	v_cvt_pk_bf16_f32 v126, v120, v121
	v_ashrrev_i32_e32 v123, 31, v122
	v_mov_b64_e32 v[120:121], s[2:3]
	v_mad_i64_i32 v[168:169], s[4:5], v168, s76, v[120:121]
	v_lshlrev_b64 v[122:123], 1, v[122:123]
	v_lshl_add_u64 v[168:169], v[168:169], 0, v[122:123]
	global_store_dwordx4 v[168:169], v[124:127], off
	v_mov_b32_e32 v194, v202
	v_mov_b32_e32 v195, v206
	v_pk_add_f32 v[124:125], v[178:179], v[180:181]
	v_pk_add_f32 v[126:127], v[182:183], v[184:185]
	v_mov_b32_e32 v179, v124
	v_mov_b32_e32 v178, v126
	v_mov_b32_e32 v124, v127
	v_pk_add_f32 v[124:125], v[178:179], v[124:125]
	ds_bpermute_b32 v127, v157, v125
	ds_bpermute_b32 v126, v157, v124
	v_mov_b32_e32 v206, v203
	v_mov_b32_e32 v196, v204
	v_mov_b32_e32 v197, v208
	v_mov_b32_e32 v208, v205
	v_mov_b32_e32 v202, v212
	v_mov_b32_e32 v203, v216
	v_mov_b32_e32 v216, v213
	v_mov_b32_e32 v204, v214
	v_mov_b32_e32 v205, v218
	v_mov_b32_e32 v218, v215
	v_pk_add_f32 v[186:187], v[194:195], v[206:207]
	v_pk_add_f32 v[188:189], v[196:197], v[208:209]
	v_pk_add_f32 v[190:191], v[202:203], v[216:217]
	v_pk_add_f32 v[192:193], v[204:205], v[218:219]
	v_pk_mul_f32 v[178:179], v[114:115], v[198:199] op_sel_hi:[1,0]
	s_waitcnt lgkmcnt(0)
	v_pk_add_f32 v[114:115], v[124:125], v[126:127]
	v_pk_add_f32 v[126:127], v[186:187], v[188:189]
	v_pk_add_f32 v[180:181], v[190:191], v[192:193]
	v_mov_b32_e32 v183, v126
	v_mov_b32_e32 v182, v180
	v_mov_b32_e32 v126, v181
	v_pk_add_f32 v[126:127], v[182:183], v[126:127]
	ds_bpermute_b32 v125, v155, v115
	ds_bpermute_b32 v124, v155, v114
	ds_bpermute_b32 v181, v157, v127
	ds_bpermute_b32 v180, v157, v126
	v_mul_f32_e32 v129, 0x4b800000, v128
	v_cmp_gt_f32_e32 vcc, s73, v128
	s_waitcnt lgkmcnt(2)
	v_pk_add_f32 v[114:115], v[114:115], v[124:125]
	v_mov_b32_e32 v194, v220
	s_waitcnt lgkmcnt(0)
	v_pk_add_f32 v[124:125], v[126:127], v[180:181]
	ds_bpermute_b32 v127, v155, v125
	ds_bpermute_b32 v126, v155, v124
	v_pk_fma_f32 v[114:115], v[114:115], s[24:25], v[130:131] op_sel_hi:[1,0,0]
	v_cndmask_b32_e32 v159, v128, v129, vcc
	v_mul_f32_e32 v128, 0x4b800000, v115
	v_cmp_gt_f32_e64 s[4:5], s73, v115
	v_cmp_gt_f32_e64 s[6:7], s73, v114
	v_mov_b32_e32 v195, v224
	v_cndmask_b32_e64 v161, v115, v128, s[4:5]
	v_mul_f32_e32 v115, 0x4b800000, v114
	v_mov_b32_e32 v224, v221
	v_mov_b32_e32 v196, v222
	v_mov_b32_e32 v197, v226
	v_mov_b32_e32 v226, v223
	v_cndmask_b32_e64 v163, v114, v115, s[6:7]
	s_waitcnt lgkmcnt(0)
	v_pk_add_f32 v[114:115], v[124:125], v[126:127]
	v_pk_add_f32 v[132:133], v[194:195], v[224:225]
	v_pk_add_f32 v[134:135], v[196:197], v[226:227]
	v_mov_b32_e32 v194, v228
	v_mov_b32_e32 v195, v232
	v_mov_b32_e32 v232, v229
	v_mov_b32_e32 v196, v230
	v_mov_b32_e32 v197, v234
	v_mov_b32_e32 v234, v231
	v_pk_fma_f32 v[114:115], v[114:115], s[24:25], v[130:131] op_sel_hi:[1,0,0]
	v_pk_add_f32 v[194:195], v[194:195], v[232:233]
	v_pk_add_f32 v[196:197], v[196:197], v[234:235]
	v_mul_f32_e32 v124, 0x4b800000, v115
	v_cmp_gt_f32_e64 s[8:9], s73, v115
	v_pk_add_f32 v[126:127], v[194:195], v[196:197]
	v_cmp_gt_f32_e64 s[10:11], s73, v114
	v_cndmask_b32_e64 v165, v115, v124, s[8:9]
	v_pk_add_f32 v[124:125], v[132:133], v[134:135]
	v_mov_b32_e32 v128, v126
	v_mov_b32_e32 v129, v124
	v_mov_b32_e32 v124, v127
	v_pk_add_f32 v[124:125], v[128:129], v[124:125]
	ds_bpermute_b32 v127, v157, v125
	ds_bpermute_b32 v126, v157, v124
	v_rsq_f32_e32 v128, v159
	v_mul_f32_e32 v115, 0x4b800000, v114
	v_cndmask_b32_e64 v129, v114, v115, s[10:11]
	v_pk_mul_f32 v[116:117], v[116:117], v[198:199] op_sel_hi:[1,0]
	s_waitcnt lgkmcnt(0)
	v_pk_add_f32 v[114:115], v[124:125], v[126:127]
	ds_bpermute_b32 v125, v155, v115
	ds_bpermute_b32 v124, v155, v114
	v_mul_f32_e32 v126, 0x45800000, v128
	v_rsq_f32_e32 v127, v161
	v_cndmask_b32_e32 v126, v128, v126, vcc
	v_rsq_f32_e32 v128, v163
	s_waitcnt lgkmcnt(0)
; DI unsigned pack2(float lo, float hi) { f32x2 v = {lo, hi}; bf16v2 r = __builtin_convertvector(v, bf16v2); return __builtin_bit_cast(unsigned, r); }
;   DI void operator()(const f32x4 (&acc)[2][2][4][2], const Unit& u, int wr, int wc, int fr, int fq) const {
;     ...
;     for (int ai = 0; ai < 2; ++ai)
; #pragma unroll
;       for (int m = 0; m < 4; ++m) {
;         const int row = row0 + ai * HALF + m * 16;
;         const float rs = rsv[ai][m];
;         bf16_t* rowp = O + (size_t)row * ldc + col0;
; #pragma unroll
;         for (int bj = 0; bj < 2; ++bj) {
;           const f32x4 v0 = acc[ai][bj][m][0] * rs, v1 = acc[ai][bj][m][1] * rs;
;           u32x4 w; w.x = pack2(v0[0], v0[1]); w.y = pack2(v0[2], v0[3]); w.z = pack2(v1[0], v1[1]); w.w = pack2(v1[2], v1[3]);
;           *(u32x4*)(rowp + bj * HALF) = w;
;         }
;       }
	v_pk_add_f32 v[114:115], v[114:115], v[124:125]
	v_mul_f32_e32 v124, 0x45800000, v127
	v_cndmask_b32_e64 v124, v127, v124, s[4:5]
	v_mul_f32_e32 v127, 0x45800000, v128
	v_pk_fma_f32 v[114:115], v[114:115], s[24:25], v[130:131] op_sel_hi:[1,0,0]
	v_rsq_f32_e32 v125, v165
	v_cndmask_b32_e64 v128, v128, v127, s[6:7]
	v_rsq_f32_e32 v127, v129
	v_mul_f32_e32 v129, 0x4b800000, v115
	v_cmp_gt_f32_e32 vcc, s73, v115
	v_cmp_gt_f32_e64 s[4:5], s73, v114
	v_pk_mul_f32 v[118:119], v[118:119], v[198:199] op_sel_hi:[1,0]
	v_cndmask_b32_e32 v129, v115, v129, vcc
	v_mul_f32_e32 v115, 0x4b800000, v114
	v_cndmask_b32_e64 v131, v114, v115, s[4:5]
	v_cvt_pk_bf16_f32 v114, v116, v117
	v_rsq_f32_e32 v117, v129
	v_cvt_pk_bf16_f32 v115, v118, v119
	v_rsq_f32_e32 v119, v131
	v_mul_f32_e32 v116, 0x45800000, v125
	v_pk_mul_f32 v[112:113], v[112:113], v[198:199] op_sel_hi:[1,0]
	v_cndmask_b32_e64 v118, v125, v116, s[8:9]
	v_mul_f32_e32 v116, 0x45800000, v127
	v_cndmask_b32_e64 v130, v127, v116, s[10:11]
	v_cvt_pk_bf16_f32 v116, v112, v113
	v_mul_f32_e32 v112, 0x45800000, v117
	v_cndmask_b32_e32 v132, v117, v112, vcc
	v_mul_f32_e32 v112, 0x45800000, v119
	v_cvt_pk_bf16_f32 v117, v178, v179
	v_cndmask_b32_e64 v112, v119, v112, s[4:5]
	global_store_dwordx4 v[168:169], v[114:117], off offset:256
	v_pk_mul_f32 v[110:111], v[110:111], v[126:127] op_sel_hi:[1,0]
	v_pk_mul_f32 v[108:109], v[108:109], v[126:127] op_sel_hi:[1,0]
	v_mad_i64_i32 v[114:115], s[4:5], v154, s76, v[120:121]
	v_pk_mul_f32 v[116:117], v[106:107], v[126:127] op_sel_hi:[1,0]
	v_pk_mul_f32 v[106:107], v[104:105], v[126:127] op_sel_hi:[1,0]
	v_lshl_add_u64 v[114:115], v[114:115], 0, v[122:123]
	v_cvt_pk_bf16_f32 v104, v108, v109
	v_cvt_pk_bf16_f32 v105, v110, v111
	v_cvt_pk_bf16_f32 v106, v106, v107
	v_cvt_pk_bf16_f32 v107, v116, v117
	global_store_dwordx4 v[114:115], v[104:107], off
	v_pk_mul_f32 v[98:99], v[98:99], v[126:127] op_sel_hi:[1,0]
	v_pk_mul_f32 v[96:97], v[96:97], v[126:127] op_sel_hi:[1,0]
	v_pk_mul_f32 v[104:105], v[90:91], v[126:127] op_sel_hi:[1,0]
	v_pk_mul_f32 v[90:91], v[88:89], v[126:127] op_sel_hi:[1,0]
	v_cvt_pk_bf16_f32 v88, v96, v97
	v_cvt_pk_bf16_f32 v89, v98, v99
	v_cvt_pk_bf16_f32 v90, v90, v91
	v_cvt_pk_bf16_f32 v91, v104, v105
	global_store_dwordx4 v[114:115], v[88:91], off offset:256
	v_pk_mul_f32 v[94:95], v[94:95], v[124:125] op_sel_hi:[1,0]
	v_pk_mul_f32 v[92:93], v[92:93], v[124:125] op_sel_hi:[1,0]
	v_mad_i64_i32 v[88:89], s[4:5], v160, s76, v[120:121]
	v_lshl_add_u64 v[96:97], v[88:89], 0, v[122:123]
	v_pk_mul_f32 v[90:91], v[102:103], v[124:125] op_sel_hi:[1,0]
	v_pk_mul_f32 v[88:89], v[100:101], v[124:125] op_sel_hi:[1,0]
	v_pk_mul_f32 v[82:83], v[82:83], v[124:125] op_sel_hi:[1,0]
	v_cvt_pk_bf16_f32 v88, v88, v89
	v_cvt_pk_bf16_f32 v89, v90, v91
	v_cvt_pk_bf16_f32 v90, v92, v93
	v_cvt_pk_bf16_f32 v91, v94, v95
	global_store_dwordx4 v[96:97], v[88:91], off
	v_pk_mul_f32 v[80:81], v[80:81], v[124:125] op_sel_hi:[1,0]
	v_pk_mul_f32 v[78:79], v[78:79], v[128:129] op_sel_hi:[1,0]
	v_pk_mul_f32 v[88:89], v[74:75], v[124:125] op_sel_hi:[1,0]
	v_pk_mul_f32 v[74:75], v[72:73], v[124:125] op_sel_hi:[1,0]
	v_cvt_pk_bf16_f32 v72, v80, v81
	v_cvt_pk_bf16_f32 v73, v82, v83
	v_cvt_pk_bf16_f32 v74, v74, v75
	v_cvt_pk_bf16_f32 v75, v88, v89
	global_store_dwordx4 v[96:97], v[72:75], off offset:256
	v_pk_mul_f32 v[76:77], v[76:77], v[128:129] op_sel_hi:[1,0]
	v_pk_mul_f32 v[70:71], v[70:71], v[128:129] op_sel_hi:[1,0]
	v_mad_i64_i32 v[72:73], s[4:5], v156, s76, v[120:121]
	v_lshl_add_u64 v[80:81], v[72:73], 0, v[122:123]
	v_pk_mul_f32 v[74:75], v[86:87], v[128:129] op_sel_hi:[1,0]
	v_pk_mul_f32 v[72:73], v[84:85], v[128:129] op_sel_hi:[1,0]
	v_pk_mul_f32 v[68:69], v[68:69], v[128:129] op_sel_hi:[1,0]
	v_cvt_pk_bf16_f32 v72, v72, v73
	v_cvt_pk_bf16_f32 v73, v74, v75
	v_cvt_pk_bf16_f32 v74, v76, v77
	v_cvt_pk_bf16_f32 v75, v78, v79
	global_store_dwordx4 v[80:81], v[72:75], off
	v_pk_mul_f32 v[62:63], v[62:63], v[118:119] op_sel_hi:[1,0]
	v_pk_mul_f32 v[60:61], v[60:61], v[118:119] op_sel_hi:[1,0]
	v_pk_mul_f32 v[72:73], v[66:67], v[128:129] op_sel_hi:[1,0]
	v_pk_mul_f32 v[66:67], v[64:65], v[128:129] op_sel_hi:[1,0]
; DI unsigned pack2(float lo, float hi) { f32x2 v = {lo, hi}; bf16v2 r = __builtin_convertvector(v, bf16v2); return __builtin_bit_cast(unsigned, r); }
; #define PG8_WAIT_V(n) asm volatile("s_waitcnt vmcnt(" #n ")" ::: "memory")
; #define PG8_BAR __builtin_amdgcn_s_barrier()
;   DI void operator()(const f32x4 (&acc)[2][2][4][2], const Unit& u, int wr, int wc, int fr, int fq) const {
;     ...
;     for (int ai = 0; ai < 2; ++ai)
; #pragma unroll
;       for (int m = 0; m < 4; ++m) {
;         const int row = row0 + ai * HALF + m * 16;
;         const float rs = rsv[ai][m];
;         bf16_t* rowp = O + (size_t)row * ldc + col0;
; #pragma unroll
;         for (int bj = 0; bj < 2; ++bj) {
;           const f32x4 v0 = acc[ai][bj][m][0] * rs, v1 = acc[ai][bj][m][1] * rs;
;           u32x4 w; w.x = pack2(v0[0], v0[1]); w.y = pack2(v0[2], v0[3]); w.z = pack2(v1[0], v1[1]); w.w = pack2(v1[2], v1[3]);
;           *(u32x4*)(rowp + bj * HALF) = w;
;         }
;       }
; template <class Epi, class Sched = StaticOrder>
; DI void gemm_phase(LAS unsigned char* lds, const Gemm g, const Sched& S, const Epi& E) {
;     ...
;     E(acc, cur, wr, wc, fr, fq);
;     if (!has_next) break;
; #pragma unroll
;     for (int a = 0; a < 2; ++a)
; #pragma unroll
;       for (int b = 0; b < 2; ++b)
; #pragma unroll
;         for (int m = 0; m < 4; ++m)
; #pragma unroll
;           for (int n = 0; n < 2; ++n) acc[a][b][m][n] = (f32x4){0.f, 0.f, 0.f, 0.f};
;     cur = nxt; cA = nA; cB = nB; ++ui;
;   }
;   PG8_WAIT_V(0);
;   if (wr == 0) PG8_BAR;
;   PG8_BAR;
	v_cvt_pk_bf16_f32 v64, v68, v69
	v_cvt_pk_bf16_f32 v65, v70, v71
	v_cvt_pk_bf16_f32 v66, v66, v67
	v_cvt_pk_bf16_f32 v67, v72, v73
	global_store_dwordx4 v[80:81], v[64:67], off offset:256
	v_pk_mul_f32 v[50:51], v[50:51], v[118:119] op_sel_hi:[1,0]
	v_pk_mul_f32 v[48:49], v[48:49], v[118:119] op_sel_hi:[1,0]
	v_mad_i64_i32 v[64:65], s[4:5], v164, s76, v[120:121]
	v_pk_mul_f32 v[66:67], v[58:59], v[118:119] op_sel_hi:[1,0]
	v_pk_mul_f32 v[58:59], v[56:57], v[118:119] op_sel_hi:[1,0]
	v_lshl_add_u64 v[64:65], v[64:65], 0, v[122:123]
	v_cvt_pk_bf16_f32 v56, v60, v61
	v_cvt_pk_bf16_f32 v57, v62, v63
	v_cvt_pk_bf16_f32 v58, v58, v59
	v_cvt_pk_bf16_f32 v59, v66, v67
	global_store_dwordx4 v[64:65], v[56:59], off
	v_pk_mul_f32 v[46:47], v[46:47], v[130:131] op_sel_hi:[1,0]
	v_pk_mul_f32 v[44:45], v[44:45], v[130:131] op_sel_hi:[1,0]
	v_pk_mul_f32 v[56:57], v[42:43], v[118:119] op_sel_hi:[1,0]
	v_pk_mul_f32 v[42:43], v[40:41], v[118:119] op_sel_hi:[1,0]
	v_cvt_pk_bf16_f32 v40, v48, v49
	v_cvt_pk_bf16_f32 v41, v50, v51
	v_cvt_pk_bf16_f32 v42, v42, v43
	v_cvt_pk_bf16_f32 v43, v56, v57
	global_store_dwordx4 v[64:65], v[40:43], off offset:256
	v_pk_mul_f32 v[34:35], v[34:35], v[130:131] op_sel_hi:[1,0]
	v_pk_mul_f32 v[32:33], v[32:33], v[130:131] op_sel_hi:[1,0]
	v_mad_i64_i32 v[40:41], s[4:5], v158, s76, v[120:121]
	v_lshl_add_u64 v[48:49], v[40:41], 0, v[122:123]
	v_pk_mul_f32 v[42:43], v[54:55], v[130:131] op_sel_hi:[1,0]
	v_pk_mul_f32 v[40:41], v[52:53], v[130:131] op_sel_hi:[1,0]
	v_pk_mul_f32 v[30:31], v[30:31], v[132:133] op_sel_hi:[1,0]
	v_cvt_pk_bf16_f32 v40, v40, v41
	v_cvt_pk_bf16_f32 v41, v42, v43
	v_cvt_pk_bf16_f32 v42, v44, v45
	v_cvt_pk_bf16_f32 v43, v46, v47
	global_store_dwordx4 v[48:49], v[40:43], off
	v_pk_mul_f32 v[28:29], v[28:29], v[132:133] op_sel_hi:[1,0]
	v_pk_mul_f32 v[18:19], v[18:19], v[132:133] op_sel_hi:[1,0]
	v_pk_mul_f32 v[40:41], v[26:27], v[130:131] op_sel_hi:[1,0]
	v_pk_mul_f32 v[26:27], v[24:25], v[130:131] op_sel_hi:[1,0]
	v_cvt_pk_bf16_f32 v24, v32, v33
	v_cvt_pk_bf16_f32 v25, v34, v35
	v_cvt_pk_bf16_f32 v26, v26, v27
	v_cvt_pk_bf16_f32 v27, v40, v41
	global_store_dwordx4 v[48:49], v[24:27], off offset:256
	v_pk_mul_f32 v[16:17], v[16:17], v[132:133] op_sel_hi:[1,0]
	v_pk_mul_f32 v[14:15], v[14:15], v[112:113] op_sel_hi:[1,0]
	v_mad_i64_i32 v[24:25], s[4:5], v166, s76, v[120:121]
	v_lshl_add_u64 v[32:33], v[24:25], 0, v[122:123]
	v_pk_mul_f32 v[26:27], v[38:39], v[132:133] op_sel_hi:[1,0]
	v_pk_mul_f32 v[24:25], v[36:37], v[132:133] op_sel_hi:[1,0]
	v_pk_mul_f32 v[12:13], v[12:13], v[112:113] op_sel_hi:[1,0]
	v_cvt_pk_bf16_f32 v24, v24, v25
	v_cvt_pk_bf16_f32 v25, v26, v27
	v_cvt_pk_bf16_f32 v26, v28, v29
	v_cvt_pk_bf16_f32 v27, v30, v31
	global_store_dwordx4 v[32:33], v[24:27], off
	v_pk_mul_f32 v[6:7], v[6:7], v[112:113] op_sel_hi:[1,0]
	v_pk_mul_f32 v[4:5], v[4:5], v[112:113] op_sel_hi:[1,0]
	v_pk_mul_f32 v[24:25], v[10:11], v[132:133] op_sel_hi:[1,0]
	v_pk_mul_f32 v[10:11], v[8:9], v[132:133] op_sel_hi:[1,0]
	v_cvt_pk_bf16_f32 v8, v16, v17
	v_cvt_pk_bf16_f32 v9, v18, v19
	v_cvt_pk_bf16_f32 v10, v10, v11
	v_cvt_pk_bf16_f32 v11, v24, v25
	global_store_dwordx4 v[32:33], v[8:11], off offset:256
	s_and_b64 vcc, exec, s[0:1]
	s_mov_b64 s[8:9], s[36:37]
	v_mad_i64_i32 v[8:9], s[4:5], v162, s76, v[120:121]
	v_lshl_add_u64 v[16:17], v[8:9], 0, v[122:123]
	v_pk_mul_f32 v[10:11], v[22:23], v[112:113] op_sel_hi:[1,0]
	v_pk_mul_f32 v[8:9], v[20:21], v[112:113] op_sel_hi:[1,0]
	s_mov_b32 s5, s28
	v_cvt_pk_bf16_f32 v8, v8, v9
	v_cvt_pk_bf16_f32 v9, v10, v11
	v_cvt_pk_bf16_f32 v10, v12, v13
	v_cvt_pk_bf16_f32 v11, v14, v15
	global_store_dwordx4 v[16:17], v[8:11], off
	s_mov_b32 s4, s30
	s_mov_b64 s[6:7], s[34:35]
	v_pk_mul_f32 v[8:9], v[2:3], v[112:113] op_sel_hi:[1,0]
	v_pk_mul_f32 v[2:3], v[0:1], v[112:113] op_sel_hi:[1,0]
	v_cvt_pk_bf16_f32 v0, v4, v5
	v_cvt_pk_bf16_f32 v1, v6, v7
	v_cvt_pk_bf16_f32 v2, v2, v3
	v_cvt_pk_bf16_f32 v3, v8, v9
	global_store_dwordx4 v[16:17], v[0:3], off offset:256
	s_cbranch_vccz .LBB0_343
	s_waitcnt vmcnt(0)
	s_cmpk_gt_u32 s27, 0xff
	s_cbranch_scc1 .LBB0_350
	s_barrier

; #define PG8_STAGE(bufoff, gbase, voff) do { _Pragma("unroll") for (int _i = 0; _i < 2; ++_i) \
;     __builtin_amdgcn_global_load_lds((const unsigned*)((const char*)(gbase) + (voff)[_i]), (LAS unsigned*)(lds + (bufoff) + ldsw + _i * 8192), 16, 0, 0); } while (0)
; #define PG8_LDA(dst, b, h) do { _Pragma("unroll") for (int m = 0; m < 4; ++m) _Pragma("unroll") for (int k = 0; k < 2; ++k) dst[m][k] = *(const LAS bf16x8*)(lds + PG8_SA(b, h) + aoff + m * 2048 + k * 1024); } while (0)
; #define PG8_LDB(dst, b, h) do { _Pragma("unroll") for (int n = 0; n < 2; ++n) _Pragma("unroll") for (int k = 0; k < 2; ++k) dst[n][k] = *(const LAS bf16x8*)(lds + PG8_SB(b, h) + boff + n * 2048 + k * 1024); } while (0)
; #define PG8_MMA(ai, bj, At, Bt) do { __builtin_amdgcn_s_setprio(1); _Pragma("unroll") for (int m = 0; m < 4; ++m) _Pragma("unroll") for (int n = 0; n < 2; ++n) _Pragma("unroll") for (int k = 0; k < 2; ++k) \
;     acc[ai][bj][m][n] = __builtin_amdgcn_mfma_f32_16x16x32_bf16(Bt[n][k], At[m][k], acc[ai][bj][m][n], 0, 0, 0); __builtin_amdgcn_s_setprio(0); } while (0)
; #define PG8_WAIT_V(n) asm volatile("s_waitcnt vmcnt(" #n ")" ::: "memory")
; #define PG8_WAIT_L(n) asm volatile("s_waitcnt lgkmcnt(" #n ")" ::: "memory")
; #define PG8_BAR __builtin_amdgcn_s_barrier()
; #define PG8_SCHED __builtin_amdgcn_sched_barrier(0)
; template <class Epi, class Sched = StaticOrder>
; DI void gemm_phase(LAS unsigned char* lds, const Gemm g, const Sched& S, const Epi& E) {
;     ...
;       PG8_LDB(B0, 0, 0); PG8_SCHED; PG8_LDA(At, 0, 0); PG8_STAGE(PG8_SA(1, 1), a1 + hstep, voffA);
;       PG8_WAIT_L(8); PG8_BAR; PG8_WAIT_L(0); PG8_MMA(0, 0, At, B0); PG8_BAR; PG8_SCHED;
;       PG8_LDB(B1, 0, 1); PG8_STAGE(PG8_SB(0, 0), b2, voffB);
;       PG8_BAR; PG8_WAIT_L(0); PG8_MMA(0, 1, At, B1); PG8_BAR;
;       PG8_LDA(At, 0, 1); PG8_STAGE(PG8_SA(0, 0), a2, voffA);
;       PG8_BAR; PG8_WAIT_L(0); PG8_MMA(1, 0, At, B0); PG8_BAR; PG8_SCHED;
;       PG8_STAGE(PG8_SB(0, 1), b2 + hstep, voffB);
;       PG8_WAIT_V(6); PG8_BAR; PG8_MMA(1, 1, At, B1); PG8_BAR;
;       PG8_LDB(B0, 1, 0); PG8_SCHED; PG8_LDA(At, 1, 0); PG8_STAGE(PG8_SA(0, 1), a2 + hstep, voffA);
;       PG8_WAIT_L(8); PG8_BAR; PG8_WAIT_L(0); PG8_MMA(0, 0, At, B0); PG8_BAR; PG8_SCHED;
;       PG8_LDB(B1, 1, 1); PG8_STAGE(PG8_SB(1, 0), b3, voffB);
;       PG8_BAR; PG8_WAIT_L(0); PG8_MMA(0, 1, At, B1); PG8_BAR;
.LBB0_728:
	s_add_u32 s24, s22, 0xfff80080
	s_addc_u32 s25, s23, -1
	s_cmp_eq_u32 s53, 28
	s_cselect_b32 s27, s17, s25
	s_cselect_b32 s26, s43, s24
	s_cselect_b32 s25, s15, s52
	s_cselect_b32 s24, s44, s45
	s_add_i32 m0, s37, 0xc000
	ds_read_b128 v[144:147], v208
	ds_read_b128 v[148:151], v208 offset:1024
	ds_read_b128 v[152:155], v208 offset:2048
	ds_read_b128 v[156:159], v208 offset:3072
	ds_read_b128 v[160:163], v208 offset:4096
	ds_read_b128 v[164:167], v208 offset:5120
	ds_read_b128 v[168:171], v208 offset:6144
	ds_read_b128 v[172:175], v208 offset:7168
	global_load_lds_dwordx4 v184, s[22:23]
	s_add_i32 m0, s37, 0xe000
	s_nop 0
	global_load_lds_dwordx4 v186, s[22:23]
	s_waitcnt lgkmcnt(0)
	s_setprio 1
	s_barrier
	v_mfma_f32_16x16x32_bf16 v[124:127], v[128:131], v[144:147], v[124:127]
	v_mfma_f32_16x16x32_bf16 v[120:123], v[136:139], v[144:147], v[120:123]
	v_mfma_f32_16x16x32_bf16 v[108:111], v[128:131], v[152:155], v[108:111]
	v_mfma_f32_16x16x32_bf16 v[104:107], v[136:139], v[152:155], v[104:107]
	v_mfma_f32_16x16x32_bf16 v[92:95], v[128:131], v[160:163], v[92:95]
	v_mfma_f32_16x16x32_bf16 v[88:91], v[136:139], v[160:163], v[88:91]
	v_mfma_f32_16x16x32_bf16 v[76:79], v[128:131], v[168:171], v[76:79]
	v_mfma_f32_16x16x32_bf16 v[72:75], v[136:139], v[168:171], v[72:75]
	v_mfma_f32_16x16x32_bf16 v[124:127], v[132:135], v[148:151], v[124:127]
	v_mfma_f32_16x16x32_bf16 v[120:123], v[140:143], v[148:151], v[120:123]
	v_mfma_f32_16x16x32_bf16 v[108:111], v[132:135], v[156:159], v[108:111]
	v_mfma_f32_16x16x32_bf16 v[104:107], v[140:143], v[156:159], v[104:107]
	v_mfma_f32_16x16x32_bf16 v[92:95], v[132:135], v[164:167], v[92:95]
	v_mfma_f32_16x16x32_bf16 v[88:91], v[140:143], v[164:167], v[88:91]
	v_mfma_f32_16x16x32_bf16 v[76:79], v[132:135], v[172:175], v[76:79]
	v_mfma_f32_16x16x32_bf16 v[72:75], v[140:143], v[172:175], v[72:75]
	s_barrier
	s_setprio 0
	s_add_i32 s54, s50, s35
	s_add_u32 s98, s24, 0x80
	s_addc_u32 s99, s25, 0
	s_mov_b32 m0, s54
	ds_read_b128 v[192:195], v209
	ds_read_b128 v[196:199], v209 offset:1024
	ds_read_b128 v[200:203], v209 offset:2048
	ds_read_b128 v[212:215], v209 offset:3072
	global_load_lds_dwordx4 v180, s[24:25]
	s_add_i32 m0, s54, 0x2000
	s_nop 0
	global_load_lds_dwordx4 v176, s[24:25]
	s_waitcnt lgkmcnt(0)
	s_setprio 1
	s_barrier
	v_mfma_f32_16x16x32_bf16 v[116:119], v[192:195], v[144:147], v[116:119]
	v_mfma_f32_16x16x32_bf16 v[112:115], v[200:203], v[144:147], v[112:115]
	v_mfma_f32_16x16x32_bf16 v[100:103], v[192:195], v[152:155], v[100:103]
	v_mfma_f32_16x16x32_bf16 v[96:99], v[200:203], v[152:155], v[96:99]
	v_mfma_f32_16x16x32_bf16 v[84:87], v[192:195], v[160:163], v[84:87]
	v_mfma_f32_16x16x32_bf16 v[80:83], v[200:203], v[160:163], v[80:83]
	v_mfma_f32_16x16x32_bf16 v[68:71], v[192:195], v[168:171], v[68:71]
	v_mfma_f32_16x16x32_bf16 v[64:67], v[200:203], v[168:171], v[64:67]
	v_mfma_f32_16x16x32_bf16 v[116:119], v[196:199], v[148:151], v[116:119]
	v_mfma_f32_16x16x32_bf16 v[112:115], v[212:215], v[148:151], v[112:115]
	v_mfma_f32_16x16x32_bf16 v[100:103], v[196:199], v[156:159], v[100:103]
	v_mfma_f32_16x16x32_bf16 v[96:99], v[212:215], v[156:159], v[96:99]
	v_mfma_f32_16x16x32_bf16 v[84:87], v[196:199], v[164:167], v[84:87]
	v_mfma_f32_16x16x32_bf16 v[80:83], v[212:215], v[164:167], v[80:83]
	v_mfma_f32_16x16x32_bf16 v[68:71], v[196:199], v[172:175], v[68:71]
	v_mfma_f32_16x16x32_bf16 v[64:67], v[212:215], v[172:175], v[64:67]
	s_barrier
	s_setprio 0
	s_mov_b32 m0, s37
	s_add_u32 s100, s26, 0x80
	s_addc_u32 s101, s27, 0
	ds_read_b128 v[144:147], v208 offset:16384
	ds_read_b128 v[148:151], v208 offset:17408
	ds_read_b128 v[152:155], v208 offset:18432
	ds_read_b128 v[156:159], v208 offset:19456
	ds_read_b128 v[160:163], v208 offset:20480
	ds_read_b128 v[164:167], v208 offset:21504
	ds_read_b128 v[168:171], v208 offset:22528
	ds_read_b128 v[172:175], v208 offset:23552
	global_load_lds_dwordx4 v182, s[26:27]
	s_mov_b32 m0, s38
	s_nop 0
	global_load_lds_dwordx4 v178, s[26:27]
	s_waitcnt vmcnt(10)
	s_waitcnt lgkmcnt(0)
	s_setprio 1
	s_barrier
	v_mfma_f32_16x16x32_bf16 v[60:63], v[128:131], v[144:147], v[60:63]
	v_mfma_f32_16x16x32_bf16 v[56:59], v[136:139], v[144:147], v[56:59]
	v_mfma_f32_16x16x32_bf16 v[44:47], v[128:131], v[152:155], v[44:47]
	v_mfma_f32_16x16x32_bf16 v[40:43], v[136:139], v[152:155], v[40:43]
	v_mfma_f32_16x16x32_bf16 v[28:31], v[128:131], v[160:163], v[28:31]
	v_mfma_f32_16x16x32_bf16 v[24:27], v[136:139], v[160:163], v[24:27]
	v_mfma_f32_16x16x32_bf16 v[12:15], v[128:131], v[168:171], v[12:15]
	v_mfma_f32_16x16x32_bf16 v[8:11], v[136:139], v[168:171], v[8:11]
	v_mfma_f32_16x16x32_bf16 v[60:63], v[132:135], v[148:151], v[60:63]
	v_mfma_f32_16x16x32_bf16 v[56:59], v[140:143], v[148:151], v[56:59]
	v_mfma_f32_16x16x32_bf16 v[44:47], v[132:135], v[156:159], v[44:47]
	v_mfma_f32_16x16x32_bf16 v[40:43], v[140:143], v[156:159], v[40:43]
	v_mfma_f32_16x16x32_bf16 v[28:31], v[132:135], v[164:167], v[28:31]
	v_mfma_f32_16x16x32_bf16 v[24:27], v[140:143], v[164:167], v[24:27]
	v_mfma_f32_16x16x32_bf16 v[12:15], v[132:135], v[172:175], v[12:15]
	v_mfma_f32_16x16x32_bf16 v[8:11], v[140:143], v[172:175], v[8:11]
	s_barrier
	s_setprio 0
	s_add_u32 s54, s24, 0x80000
	s_addc_u32 s55, s25, 0
	s_add_i32 s57, s51, s35
	s_mov_b32 m0, s57
	s_nop 0
	global_load_lds_dwordx4 v180, s[54:55]
	s_add_i32 m0, s57, 0x2000
	s_nop 0
	global_load_lds_dwordx4 v176, s[54:55]
	s_add_i32 s54, 0, 0x18000
	v_add_u32_e32 v140, s54, v205
	ds_read_b128 v[128:131], v140
	ds_read_b128 v[132:135], v140 offset:1024
	ds_read_b128 v[136:139], v140 offset:2048
	ds_read_b128 v[140:143], v140 offset:3072
	s_waitcnt vmcnt(6)
	s_setprio 1
	s_barrier
; #define PG8_STAGE(bufoff, gbase, voff) do { _Pragma("unroll") for (int _i = 0; _i < 2; ++_i) \
;     __builtin_amdgcn_global_load_lds((const unsigned*)((const char*)(gbase) + (voff)[_i]), (LAS unsigned*)(lds + (bufoff) + ldsw + _i * 8192), 16, 0, 0); } while (0)
; #define PG8_LDA(dst, b, h) do { _Pragma("unroll") for (int m = 0; m < 4; ++m) _Pragma("unroll") for (int k = 0; k < 2; ++k) dst[m][k] = *(const LAS bf16x8*)(lds + PG8_SA(b, h) + aoff + m * 2048 + k * 1024); } while (0)
; #define PG8_LDB(dst, b, h) do { _Pragma("unroll") for (int n = 0; n < 2; ++n) _Pragma("unroll") for (int k = 0; k < 2; ++k) dst[n][k] = *(const LAS bf16x8*)(lds + PG8_SB(b, h) + boff + n * 2048 + k * 1024); } while (0)
; #define PG8_MMA(ai, bj, At, Bt) do { __builtin_amdgcn_s_setprio(1); _Pragma("unroll") for (int m = 0; m < 4; ++m) _Pragma("unroll") for (int n = 0; n < 2; ++n) _Pragma("unroll") for (int k = 0; k < 2; ++k) \
;     acc[ai][bj][m][n] = __builtin_amdgcn_mfma_f32_16x16x32_bf16(Bt[n][k], At[m][k], acc[ai][bj][m][n], 0, 0, 0); __builtin_amdgcn_s_setprio(0); } while (0)
; #define PG8_WAIT_V(n) asm volatile("s_waitcnt vmcnt(" #n ")" ::: "memory")
; #define PG8_WAIT_L(n) asm volatile("s_waitcnt lgkmcnt(" #n ")" ::: "memory")
; #define PG8_BAR __builtin_amdgcn_s_barrier()
; #define PG8_SCHED __builtin_amdgcn_sched_barrier(0)
; template <class Epi, class Sched = StaticOrder>
; DI void gemm_phase(LAS unsigned char* lds, const Gemm g, const Sched& S, const Epi& E) {
;     ...
;       PG8_LDA(At, 0, 1); PG8_STAGE(PG8_SA(0, 0), a2, voffA);
;       PG8_BAR; PG8_WAIT_L(0); PG8_MMA(1, 0, At, B0); PG8_BAR; PG8_SCHED;
;       PG8_STAGE(PG8_SB(0, 1), b2 + hstep, voffB);
;       PG8_WAIT_V(6); PG8_BAR; PG8_MMA(1, 1, At, B1); PG8_BAR;
;       PG8_LDB(B0, 1, 0); PG8_SCHED; PG8_LDA(At, 1, 0); PG8_STAGE(PG8_SA(0, 1), a2 + hstep, voffA);
;       PG8_WAIT_L(8); PG8_BAR; PG8_WAIT_L(0); PG8_MMA(0, 0, At, B0); PG8_BAR; PG8_SCHED;
;       PG8_LDB(B1, 1, 1); PG8_STAGE(PG8_SB(1, 0), b3, voffB);
;       PG8_BAR; PG8_WAIT_L(0); PG8_MMA(0, 1, At, B1); PG8_BAR;
;       PG8_LDA(At, 1, 1); PG8_STAGE(PG8_SA(1, 0), a3, voffA);
;       PG8_BAR; PG8_WAIT_L(0); PG8_MMA(1, 0, At, B0); PG8_BAR; PG8_SCHED;
	v_mfma_f32_16x16x32_bf16 v[52:55], v[192:195], v[144:147], v[52:55]
	v_mfma_f32_16x16x32_bf16 v[48:51], v[200:203], v[144:147], v[48:51]
	v_mfma_f32_16x16x32_bf16 v[36:39], v[192:195], v[152:155], v[36:39]
	v_mfma_f32_16x16x32_bf16 v[32:35], v[200:203], v[152:155], v[32:35]
	v_mfma_f32_16x16x32_bf16 v[20:23], v[192:195], v[160:163], v[20:23]
	v_mfma_f32_16x16x32_bf16 v[16:19], v[200:203], v[160:163], v[16:19]
	v_mfma_f32_16x16x32_bf16 v[4:7], v[192:195], v[168:171], v[4:7]
	v_mfma_f32_16x16x32_bf16 v[0:3], v[200:203], v[168:171], v[0:3]
	v_mfma_f32_16x16x32_bf16 v[52:55], v[196:199], v[148:151], v[52:55]
	v_mfma_f32_16x16x32_bf16 v[48:51], v[212:215], v[148:151], v[48:51]
	v_mfma_f32_16x16x32_bf16 v[36:39], v[196:199], v[156:159], v[36:39]
	v_mfma_f32_16x16x32_bf16 v[32:35], v[212:215], v[156:159], v[32:35]
	v_mfma_f32_16x16x32_bf16 v[20:23], v[196:199], v[164:167], v[20:23]
	v_mfma_f32_16x16x32_bf16 v[16:19], v[212:215], v[164:167], v[16:19]
	v_mfma_f32_16x16x32_bf16 v[4:7], v[196:199], v[172:175], v[4:7]
	v_mfma_f32_16x16x32_bf16 v[0:3], v[212:215], v[172:175], v[0:3]
	s_barrier
	s_setprio 0
	s_add_u32 s26, s26, 0x80000
	s_addc_u32 s27, s27, 0
	s_mov_b32 m0, s39
	ds_read_b128 v[144:147], v208 offset:32768
	ds_read_b128 v[148:151], v208 offset:33792
	ds_read_b128 v[152:155], v208 offset:34816
	ds_read_b128 v[156:159], v208 offset:35840
	ds_read_b128 v[160:163], v208 offset:36864
	ds_read_b128 v[164:167], v208 offset:37888
	ds_read_b128 v[168:171], v208 offset:38912
	ds_read_b128 v[172:175], v208 offset:39936
	global_load_lds_dwordx4 v182, s[26:27]
	s_mov_b32 m0, s40
	s_nop 0
	global_load_lds_dwordx4 v178, s[26:27]
	s_waitcnt lgkmcnt(0)
	s_setprio 1
	s_barrier
	v_mfma_f32_16x16x32_bf16 v[124:127], v[128:131], v[144:147], v[124:127]
	v_mfma_f32_16x16x32_bf16 v[120:123], v[136:139], v[144:147], v[120:123]
	v_mfma_f32_16x16x32_bf16 v[108:111], v[128:131], v[152:155], v[108:111]
	v_mfma_f32_16x16x32_bf16 v[104:107], v[136:139], v[152:155], v[104:107]
	v_mfma_f32_16x16x32_bf16 v[92:95], v[128:131], v[160:163], v[92:95]
	v_mfma_f32_16x16x32_bf16 v[88:91], v[136:139], v[160:163], v[88:91]
	v_mfma_f32_16x16x32_bf16 v[76:79], v[128:131], v[168:171], v[76:79]
	v_mfma_f32_16x16x32_bf16 v[72:75], v[136:139], v[168:171], v[72:75]
	v_mfma_f32_16x16x32_bf16 v[124:127], v[132:135], v[148:151], v[124:127]
	v_mfma_f32_16x16x32_bf16 v[120:123], v[140:143], v[148:151], v[120:123]
	v_mfma_f32_16x16x32_bf16 v[108:111], v[132:135], v[156:159], v[108:111]
	v_mfma_f32_16x16x32_bf16 v[104:107], v[140:143], v[156:159], v[104:107]
	v_mfma_f32_16x16x32_bf16 v[92:95], v[132:135], v[164:167], v[92:95]
	v_mfma_f32_16x16x32_bf16 v[88:91], v[140:143], v[164:167], v[88:91]
	v_mfma_f32_16x16x32_bf16 v[76:79], v[132:135], v[172:175], v[76:79]
	v_mfma_f32_16x16x32_bf16 v[72:75], v[140:143], v[172:175], v[72:75]
	s_barrier
	s_setprio 0
	s_add_i32 s26, 0, 0x1c000
	s_add_i32 s27, s54, s35
	v_add_u32_e32 v212, s26, v205
	s_mov_b32 m0, s27
	ds_read_b128 v[192:195], v212
	ds_read_b128 v[196:199], v212 offset:1024
	ds_read_b128 v[200:203], v212 offset:2048
	ds_read_b128 v[212:215], v212 offset:3072
	global_load_lds_dwordx4 v180, s[98:99]
	s_add_i32 m0, s27, 0x2000
	s_nop 0
	global_load_lds_dwordx4 v176, s[98:99]
	s_waitcnt lgkmcnt(0)
	s_setprio 1
	s_barrier
	v_mfma_f32_16x16x32_bf16 v[116:119], v[192:195], v[144:147], v[116:119]
	v_mfma_f32_16x16x32_bf16 v[112:115], v[200:203], v[144:147], v[112:115]
	v_mfma_f32_16x16x32_bf16 v[100:103], v[192:195], v[152:155], v[100:103]
	v_mfma_f32_16x16x32_bf16 v[96:99], v[200:203], v[152:155], v[96:99]
	v_mfma_f32_16x16x32_bf16 v[84:87], v[192:195], v[160:163], v[84:87]
	v_mfma_f32_16x16x32_bf16 v[80:83], v[200:203], v[160:163], v[80:83]
	v_mfma_f32_16x16x32_bf16 v[68:71], v[192:195], v[168:171], v[68:71]
	v_mfma_f32_16x16x32_bf16 v[64:67], v[200:203], v[168:171], v[64:67]
	v_mfma_f32_16x16x32_bf16 v[116:119], v[196:199], v[148:151], v[116:119]
	v_mfma_f32_16x16x32_bf16 v[112:115], v[212:215], v[148:151], v[112:115]
	v_mfma_f32_16x16x32_bf16 v[100:103], v[196:199], v[156:159], v[100:103]
	v_mfma_f32_16x16x32_bf16 v[96:99], v[212:215], v[156:159], v[96:99]
	v_mfma_f32_16x16x32_bf16 v[84:87], v[196:199], v[164:167], v[84:87]
	v_mfma_f32_16x16x32_bf16 v[80:83], v[212:215], v[164:167], v[80:83]
	v_mfma_f32_16x16x32_bf16 v[68:71], v[196:199], v[172:175], v[68:71]
	v_mfma_f32_16x16x32_bf16 v[64:67], v[212:215], v[172:175], v[64:67]
	s_barrier
	s_setprio 0
	s_mov_b32 m0, s46
	ds_read_b128 v[144:147], v208 offset:49152
	ds_read_b128 v[148:151], v208 offset:50176
	ds_read_b128 v[152:155], v208 offset:51200
	ds_read_b128 v[156:159], v208 offset:52224
	ds_read_b128 v[160:163], v208 offset:53248
	ds_read_b128 v[164:167], v208 offset:54272
	ds_read_b128 v[168:171], v208 offset:55296
	ds_read_b128 v[172:175], v208 offset:56320
	global_load_lds_dwordx4 v182, s[100:101]
	s_mov_b32 m0, s47
	s_nop 0
	global_load_lds_dwordx4 v178, s[100:101]
	s_waitcnt vmcnt(10)
	s_waitcnt lgkmcnt(0)
	s_setprio 1
	s_barrier
	v_mfma_f32_16x16x32_bf16 v[60:63], v[128:131], v[144:147], v[60:63]
	v_mfma_f32_16x16x32_bf16 v[56:59], v[136:139], v[144:147], v[56:59]
	v_mfma_f32_16x16x32_bf16 v[44:47], v[128:131], v[152:155], v[44:47]
	v_mfma_f32_16x16x32_bf16 v[40:43], v[136:139], v[152:155], v[40:43]
	v_mfma_f32_16x16x32_bf16 v[28:31], v[128:131], v[160:163], v[28:31]
	v_mfma_f32_16x16x32_bf16 v[24:27], v[136:139], v[160:163], v[24:27]
	v_mfma_f32_16x16x32_bf16 v[12:15], v[128:131], v[168:171], v[12:15]
	v_mfma_f32_16x16x32_bf16 v[8:11], v[136:139], v[168:171], v[8:11]
	v_mfma_f32_16x16x32_bf16 v[60:63], v[132:135], v[148:151], v[60:63]
	v_mfma_f32_16x16x32_bf16 v[56:59], v[140:143], v[148:151], v[56:59]
	v_mfma_f32_16x16x32_bf16 v[44:47], v[132:135], v[156:159], v[44:47]
	v_mfma_f32_16x16x32_bf16 v[40:43], v[140:143], v[156:159], v[40:43]
	v_mfma_f32_16x16x32_bf16 v[28:31], v[132:135], v[164:167], v[28:31]
	v_mfma_f32_16x16x32_bf16 v[24:27], v[140:143], v[164:167], v[24:27]
	v_mfma_f32_16x16x32_bf16 v[12:15], v[132:135], v[172:175], v[12:15]
	v_mfma_f32_16x16x32_bf16 v[8:11], v[140:143], v[172:175], v[8:11]
	s_barrier
; DI unsigned pack2(float lo, float hi) { f32x2 v = {lo, hi}; bf16v2 r = __builtin_convertvector(v, bf16v2); return __builtin_bit_cast(unsigned, r); }
; #define PG8_WAIT_V(n) asm volatile("s_waitcnt vmcnt(" #n ")" ::: "memory")
; #define PG8_BAR __builtin_amdgcn_s_barrier()
;   DI void operator()(const f32x4 (&acc)[2][2][4][2], const Unit& u, int wr, int wc, int fr, int fq) const {
;     const int row0 = u.pm * BM + wr * 64 + fr, col0 = u.pn * BM + wc * 32 + 8 * fq;
; #pragma unroll
;     for (int ai = 0; ai < 2; ++ai) {
;       f32x4 bv[4][2][2];
; #pragma unroll
;       for (int m = 0; m < 4; ++m)
; #pragma unroll
;         for (int bj = 0; bj < 2; ++bj) {
;           const float* bp = base + (size_t)(row0 + ai * HALF + m * 16) * 2048 + col0 + bj * HALF;
;           bv[m][bj][0] = *(const f32x4*)bp; bv[m][bj][1] = *(const f32x4*)(bp + 4);
;         }
; #pragma unroll
;       for (int m = 0; m < 4; ++m) {
;         const int row = row0 + ai * HALF + m * 16;
;         const size_t off = (size_t)row * 2048 + col0;
;         float ss = 0.f;
; #pragma unroll
;         for (int bj = 0; bj < 2; ++bj) {
;           const f32x4 v0 = acc[ai][bj][m][0] + bv[m][bj][0], v1 = acc[ai][bj][m][1] + bv[m][bj][1];
;           *(f32x4*)(C + off + bj * HALF) = v0; *(f32x4*)(C + off + bj * HALF + 4) = v1;
;           if (xb) {
;             u32x4 w; w.x = pack2(v0[0], v0[1]); w.y = pack2(v0[2], v0[3]); w.z = pack2(v1[0], v1[1]); w.w = pack2(v1[2], v1[3]);
;             *(u32x4*)(xb + off + bj * HALF) = w;
;             ss += v0[0] * v0[0] + v0[1] * v0[1] + v0[2] * v0[2] + v0[3] * v0[3] + v1[0] * v1[0] + v1[1] * v1[1] + v1[2] * v1[2] + v1[3] * v1[3];
;           }
;         }
;         if (xb) {
;           ss += __shfl_xor(ss, 16); ss += __shfl_xor(ss, 32);
;           if (fq == 0) ssq[(size_t)row * 32 + u.pn * 4 + wc] = ss;
;         }
; template <class Epi, class Sched = StaticOrder>
; DI void gemm_phase(LAS unsigned char* lds, const Gemm g, const Sched& S, const Epi& E) {
;     ...
;       PG8_LDB(B1, 1, 1); PG8_STAGE(PG8_SB(1, 0), b3, voffB);
;       PG8_BAR; PG8_WAIT_L(0); PG8_MMA(0, 1, At, B1); PG8_BAR;
;       PG8_LDA(At, 1, 1); PG8_STAGE(PG8_SA(1, 0), a3, voffA);
;       PG8_BAR; PG8_WAIT_L(0); PG8_MMA(1, 0, At, B0); PG8_BAR; PG8_SCHED;
;       PG8_STAGE(PG8_SB(1, 1), b3 + hstep, voffB);
;       PG8_WAIT_V(6); PG8_BAR; PG8_MMA(1, 1, At, B1); PG8_BAR;
	s_setprio 0
	s_add_u32 s24, s24, 0x80080
	s_addc_u32 s25, s25, 0
	s_add_i32 s26, s26, s35
	s_mov_b32 m0, s26
	s_nop 0
	global_load_lds_dwordx4 v180, s[24:25]
	s_add_i32 m0, s26, 0x2000
	s_nop 0
	global_load_lds_dwordx4 v176, s[24:25]
	ds_read_b128 v[128:131], v207
	ds_read_b128 v[132:135], v207 offset:1024
	ds_read_b128 v[136:139], v207 offset:2048
	ds_read_b128 v[140:143], v207 offset:3072
	s_waitcnt vmcnt(6)
	s_add_i32 s53, s53, 2
	s_add_u32 s22, s22, 0x100
	s_addc_u32 s23, s23, 0
	s_add_u32 s45, s45, 0x100
	s_addc_u32 s52, s52, 0
	s_cmp_gt_u32 s53, 29
	s_setprio 1
	s_barrier
	v_mfma_f32_16x16x32_bf16 v[52:55], v[192:195], v[144:147], v[52:55]
	v_mfma_f32_16x16x32_bf16 v[48:51], v[200:203], v[144:147], v[48:51]
	v_mfma_f32_16x16x32_bf16 v[36:39], v[192:195], v[152:155], v[36:39]
	v_mfma_f32_16x16x32_bf16 v[32:35], v[200:203], v[152:155], v[32:35]
	v_mfma_f32_16x16x32_bf16 v[20:23], v[192:195], v[160:163], v[20:23]
	v_mfma_f32_16x16x32_bf16 v[16:19], v[200:203], v[160:163], v[16:19]
	v_mfma_f32_16x16x32_bf16 v[4:7], v[192:195], v[168:171], v[4:7]
	v_mfma_f32_16x16x32_bf16 v[0:3], v[200:203], v[168:171], v[0:3]
	v_mfma_f32_16x16x32_bf16 v[52:55], v[196:199], v[148:151], v[52:55]
	v_mfma_f32_16x16x32_bf16 v[48:51], v[212:215], v[148:151], v[48:51]
	v_mfma_f32_16x16x32_bf16 v[36:39], v[196:199], v[156:159], v[36:39]
	v_mfma_f32_16x16x32_bf16 v[32:35], v[212:215], v[156:159], v[32:35]
	v_mfma_f32_16x16x32_bf16 v[20:23], v[196:199], v[164:167], v[20:23]
	v_mfma_f32_16x16x32_bf16 v[16:19], v[212:215], v[164:167], v[16:19]
	v_mfma_f32_16x16x32_bf16 v[4:7], v[196:199], v[172:175], v[4:7]
	v_mfma_f32_16x16x32_bf16 v[0:3], v[212:215], v[172:175], v[0:3]
	s_barrier
	s_setprio 0
	s_cbranch_scc0 .LBB0_728
	s_waitcnt lgkmcnt(0)
	v_lshl_add_u32 v196, s12, 8, v204
	v_lshl_or_b32 v192, s42, 8, v206
	v_ashrrev_i32_e32 v193, 31, v192
	v_ashrrev_i32_e32 v197, 31, v196
	v_lshl_add_u64 v[194:195], v[192:193], 2, s[60:61]
	v_lshlrev_b64 v[128:129], 13, v[196:197]
	v_lshl_add_u64 v[128:129], v[194:195], 0, v[128:129]
	global_load_dwordx4 v[214:217], v[128:129], off
	global_load_dwordx4 v[218:221], v[128:129], off offset:16
	global_load_dwordx4 v[222:225], v[128:129], off offset:512
	global_load_dwordx4 v[226:229], v[128:129], off offset:528
	v_or_b32_e32 v202, 16, v196
	v_or_b32_e32 v200, 32, v196
	v_or_b32_e32 v198, 48, v196
	v_ashrrev_i32_e32 v203, 31, v202
	v_ashrrev_i32_e32 v201, 31, v200
	v_ashrrev_i32_e32 v199, 31, v198
	v_lshlrev_b64 v[128:129], 13, v[202:203]
	v_lshlrev_b64 v[130:131], 13, v[200:201]
	v_lshlrev_b64 v[132:133], 13, v[198:199]
	v_lshl_add_u64 v[128:129], v[194:195], 0, v[128:129]
	v_lshl_add_u64 v[130:131], v[194:195], 0, v[130:131]
	v_lshl_add_u64 v[132:133], v[194:195], 0, v[132:133]
	global_load_dwordx4 v[168:171], v[128:129], off offset:16
	global_load_dwordx4 v[172:175], v[128:129], off
	global_load_dwordx4 v[160:163], v[128:129], off offset:528
	global_load_dwordx4 v[164:167], v[128:129], off offset:512
	global_load_dwordx4 v[152:155], v[130:131], off offset:16
	global_load_dwordx4 v[156:159], v[130:131], off
	global_load_dwordx4 v[144:147], v[130:131], off offset:528
	global_load_dwordx4 v[148:151], v[130:131], off offset:512
	global_load_dwordx4 v[136:139], v[132:133], off offset:16
	global_load_dwordx4 v[140:143], v[132:133], off
	s_nop 0
	global_load_dwordx4 v[128:131], v[132:133], off offset:528
	s_nop 0
	global_load_dwordx4 v[132:135], v[132:133], off offset:512
	v_and_b32_e32 v212, 64, v211
	v_xor_b32_e32 v230, 16, v211
	v_add_u32_e32 v232, 64, v212
	v_xor_b32_e32 v231, 32, v211
	v_cmp_lt_i32_e32 vcc, v230, v232
	v_lshlrev_b64 v[212:213], 11, v[196:197]
	v_readlane_b32 s64, v243, 3
	v_cndmask_b32_e32 v233, v211, v230, vcc
	v_cmp_lt_i32_e32 vcc, v231, v232
	v_readlane_b32 s78, v243, 17
	v_readlane_b32 s79, v243, 18
	v_cndmask_b32_e32 v234, v211, v231, vcc
	v_lshl_add_u64 v[230:231], v[212:213], 0, v[192:193]
	v_lshlrev_b32_e32 v212, 2, v233
	v_lshl_add_u64 v[232:233], v[230:231], 2, s[78:79]
	v_lshl_add_u64 v[230:231], v[230:231], 1, s[2:3]
	s_lshl_b32 s22, s42, 2
	s_ashr_i32 s23, s22, 31
	v_readlane_b32 s65, v243, 4
	v_readlane_b32 s66, v243, 5
	v_readlane_b32 s67, v243, 6
	v_readlane_b32 s68, v243, 7
	v_readlane_b32 s69, v243, 8
	v_readlane_b32 s70, v243, 9
	v_readlane_b32 s71, v243, 10
	v_readlane_b32 s72, v243, 11
	v_readlane_b32 s73, v243, 12
	v_readlane_b32 s74, v243, 13
	v_readlane_b32 s75, v243, 14
	v_readlane_b32 s76, v243, 15
	v_readlane_b32 s77, v243, 16
	s_waitcnt vmcnt(0)
	v_pk_add_f32 v[126:127], v[126:127], v[216:217]
	v_pk_add_f32 v[124:125], v[124:125], v[214:215]
	v_pk_add_f32 v[116:117], v[116:117], v[222:223]
	v_pk_add_f32 v[122:123], v[122:123], v[220:221]
	v_pk_add_f32 v[120:121], v[120:121], v[218:219]
	v_pk_add_f32 v[214:215], v[112:113], v[226:227]
	global_store_dwordx4 v[232:233], v[124:127], off
	global_store_dwordx4 v[232:233], v[120:123], off offset:16
	v_cvt_pk_bf16_f32 v112, v124, v125
	v_mul_f32_e32 v125, v125, v125
	v_mul_f32_e32 v213, v117, v117
	v_pk_add_f32 v[118:119], v[118:119], v[224:225]
	v_fmac_f32_e32 v125, v124, v124
	v_fmac_f32_e32 v213, v116, v116
	v_fmac_f32_e32 v125, v126, v126
	v_fmac_f32_e32 v213, v118, v118
	v_fmac_f32_e32 v125, v127, v127
	v_fmac_f32_e32 v213, v119, v119
	v_fmac_f32_e32 v125, v120, v120
	v_fmac_f32_e32 v213, v214, v214
	v_pk_add_f32 v[216:217], v[114:115], v[228:229]
	v_fmac_f32_e32 v125, v121, v121
	v_fmac_f32_e32 v213, v215, v215
	v_fmac_f32_e32 v125, v122, v122
	v_fmac_f32_e32 v213, v216, v216
	v_fmac_f32_e32 v125, v123, v123
	v_fmac_f32_e32 v213, v217, v217
	v_cvt_pk_bf16_f32 v114, v120, v121
	v_add_f32_e32 v120, v125, v213
	ds_bpermute_b32 v121, v212, v120
	v_cvt_pk_bf16_f32 v113, v126, v127
	v_cvt_pk_bf16_f32 v115, v122, v123
	global_store_dwordx4 v[230:231], v[112:115], off
	global_store_dwordx4 v[232:233], v[116:119], off offset:512
	global_store_dwordx4 v[232:233], v[214:217], off offset:528
	v_cvt_pk_bf16_f32 v122, v116, v117
	s_waitcnt lgkmcnt(0)
	v_add_f32_e32 v112, v120, v121
	v_lshlrev_b32_e32 v120, 2, v234
	ds_bpermute_b32 v113, v120, v112
	v_cvt_pk_bf16_f32 v123, v118, v119
	v_cvt_pk_bf16_f32 v124, v214, v215
	v_cvt_pk_bf16_f32 v125, v216, v217
	global_store_dwordx4 v[230:231], v[122:125], off offset:256
	s_and_saveexec_b64 s[24:25], s[0:1]
	s_cbranch_execz .LBB0_731
	s_waitcnt lgkmcnt(0)
	v_add_f32_e32 v114, v112, v113
	v_lshlrev_b64 v[112:113], 7, v[196:197]
	v_lshl_add_u64 v[112:113], s[8:9], 0, v[112:113]
	v_lshl_add_u64 v[112:113], s[22:23], 2, v[112:113]
	s_lshl_b32 s12, s41, 2
	v_lshl_add_u64 v[112:113], v[112:113], 0, s[12:13]
	global_store_dword v[112:113], v114, off

; #define PG8_STAGE(bufoff, gbase, voff) do { _Pragma("unroll") for (int _i = 0; _i < 2; ++_i) \
;     __builtin_amdgcn_global_load_lds((const unsigned*)((const char*)(gbase) + (voff)[_i]), (LAS unsigned*)(lds + (bufoff) + ldsw + _i * 8192), 16, 0, 0); } while (0)
; #define PG8_LDA(dst, b, h) do { _Pragma("unroll") for (int m = 0; m < 4; ++m) _Pragma("unroll") for (int k = 0; k < 2; ++k) dst[m][k] = *(const LAS bf16x8*)(lds + PG8_SA(b, h) + aoff + m * 2048 + k * 1024); } while (0)
; #define PG8_LDB(dst, b, h) do { _Pragma("unroll") for (int n = 0; n < 2; ++n) _Pragma("unroll") for (int k = 0; k < 2; ++k) dst[n][k] = *(const LAS bf16x8*)(lds + PG8_SB(b, h) + boff + n * 2048 + k * 1024); } while (0)
; #define PG8_MMA(ai, bj, At, Bt) do { __builtin_amdgcn_s_setprio(1); _Pragma("unroll") for (int m = 0; m < 4; ++m) _Pragma("unroll") for (int n = 0; n < 2; ++n) _Pragma("unroll") for (int k = 0; k < 2; ++k) \
;     acc[ai][bj][m][n] = __builtin_amdgcn_mfma_f32_16x16x32_bf16(Bt[n][k], At[m][k], acc[ai][bj][m][n], 0, 0, 0); __builtin_amdgcn_s_setprio(0); } while (0)
; #define PG8_WAIT_V(n) asm volatile("s_waitcnt vmcnt(" #n ")" ::: "memory")
; #define PG8_WAIT_L(n) asm volatile("s_waitcnt lgkmcnt(" #n ")" ::: "memory")
; #define PG8_BAR __builtin_amdgcn_s_barrier()
; #define PG8_SCHED __builtin_amdgcn_sched_barrier(0)
; template <class Epi, class Sched = StaticOrder>
; DI void gemm_phase(LAS unsigned char* lds, const Gemm g, const Sched& S, const Epi& E) {
;     ...
;       PG8_LDB(B0, 0, 0); PG8_SCHED; PG8_LDA(At, 0, 0); PG8_STAGE(PG8_SA(1, 1), a1 + hstep, voffA);
;       PG8_WAIT_L(8); PG8_BAR; PG8_WAIT_L(0); PG8_MMA(0, 0, At, B0); PG8_BAR; PG8_SCHED;
;       PG8_LDB(B1, 0, 1); PG8_STAGE(PG8_SB(0, 0), b2, voffB);
;       PG8_BAR; PG8_WAIT_L(0); PG8_MMA(0, 1, At, B1); PG8_BAR;
;       PG8_LDA(At, 0, 1); PG8_STAGE(PG8_SA(0, 0), a2, voffA);
;       PG8_BAR; PG8_WAIT_L(0); PG8_MMA(1, 0, At, B0); PG8_BAR; PG8_SCHED;
;       PG8_STAGE(PG8_SB(0, 1), b2 + hstep, voffB);
;       PG8_WAIT_V(6); PG8_BAR; PG8_MMA(1, 1, At, B1); PG8_BAR;
;       PG8_LDB(B0, 1, 0); PG8_SCHED; PG8_LDA(At, 1, 0); PG8_STAGE(PG8_SA(0, 1), a2 + hstep, voffA);
;       PG8_WAIT_L(8); PG8_BAR; PG8_WAIT_L(0); PG8_MMA(0, 0, At, B0); PG8_BAR; PG8_SCHED;
;       PG8_LDB(B1, 1, 1); PG8_STAGE(PG8_SB(1, 0), b3, voffB);
;       PG8_BAR; PG8_WAIT_L(0); PG8_MMA(0, 1, At, B1); PG8_BAR;
.LBB0_811:
	s_add_u32 s46, s14, 0xfff80080
	s_addc_u32 s47, s15, -1
	s_cmp_eq_u32 s52, 28
	s_cselect_b32 s49, s37, s47
	s_cselect_b32 s48, s42, s46
	s_cselect_b32 s47, s35, s45
	s_cselect_b32 s46, s43, s44
	s_add_i32 m0, s62, 0xc000
	ds_read_b128 v[80:83], v202
	ds_read_b128 v[84:87], v202 offset:1024
	ds_read_b128 v[92:95], v202 offset:2048
	ds_read_b128 v[96:99], v202 offset:3072
	ds_read_b128 v[180:183], v202 offset:4096
	ds_read_b128 v[184:187], v202 offset:5120
	ds_read_b128 v[188:191], v202 offset:6144
	ds_read_b128 v[192:195], v202 offset:7168
	global_load_lds_dwordx4 v170, s[14:15]
	s_add_i32 m0, s62, 0xe000
	s_nop 0
	global_load_lds_dwordx4 v172, s[14:15]
	s_waitcnt lgkmcnt(0)
	s_setprio 1
	s_barrier
	v_mfma_f32_16x16x32_bf16 v[156:159], v[64:67], v[80:83], v[156:159]
	v_mfma_f32_16x16x32_bf16 v[144:147], v[72:75], v[80:83], v[144:147]
	v_mfma_f32_16x16x32_bf16 v[140:143], v[64:67], v[92:95], v[140:143]
	v_mfma_f32_16x16x32_bf16 v[132:135], v[72:75], v[92:95], v[132:135]
	v_mfma_f32_16x16x32_bf16 v[124:127], v[64:67], v[180:183], v[124:127]
	v_mfma_f32_16x16x32_bf16 v[116:119], v[72:75], v[180:183], v[116:119]
	v_mfma_f32_16x16x32_bf16 v[112:115], v[64:67], v[188:191], v[112:115]
	v_mfma_f32_16x16x32_bf16 v[108:111], v[72:75], v[188:191], v[108:111]
	v_mfma_f32_16x16x32_bf16 v[156:159], v[68:71], v[84:87], v[156:159]
	v_mfma_f32_16x16x32_bf16 v[144:147], v[76:79], v[84:87], v[144:147]
	v_mfma_f32_16x16x32_bf16 v[140:143], v[68:71], v[96:99], v[140:143]
	v_mfma_f32_16x16x32_bf16 v[132:135], v[76:79], v[96:99], v[132:135]
	v_mfma_f32_16x16x32_bf16 v[124:127], v[68:71], v[184:187], v[124:127]
	v_mfma_f32_16x16x32_bf16 v[116:119], v[76:79], v[184:187], v[116:119]
	v_mfma_f32_16x16x32_bf16 v[112:115], v[68:71], v[192:195], v[112:115]
	v_mfma_f32_16x16x32_bf16 v[108:111], v[76:79], v[192:195], v[108:111]
	s_barrier
	s_setprio 0
	s_add_i32 s53, s72, s60
	s_add_u32 s98, s46, 0x80
	s_addc_u32 s99, s47, 0
	s_mov_b32 m0, s53
	ds_read_b128 v[206:209], v203
	ds_read_b128 v[212:215], v203 offset:1024
	ds_read_b128 v[216:219], v203 offset:2048
	ds_read_b128 v[220:223], v203 offset:3072
	global_load_lds_dwordx4 v164, s[46:47]
	s_add_i32 m0, s53, 0x2000
	s_nop 0
	global_load_lds_dwordx4 v160, s[46:47]
	s_waitcnt lgkmcnt(0)
	s_setprio 1
	s_barrier
	v_mfma_f32_16x16x32_bf16 v[152:155], v[206:209], v[80:83], v[152:155]
	v_mfma_f32_16x16x32_bf16 v[80:83], v[216:219], v[80:83], v[148:151]
	v_mfma_f32_16x16x32_bf16 v[152:155], v[212:215], v[84:87], v[152:155]
	v_mfma_f32_16x16x32_bf16 v[80:83], v[220:223], v[84:87], v[80:83]
	v_mfma_f32_16x16x32_bf16 v[84:87], v[206:209], v[92:95], v[136:139]
	v_mfma_f32_16x16x32_bf16 v[92:95], v[216:219], v[92:95], v[128:131]
	v_mfma_f32_16x16x32_bf16 v[104:107], v[216:219], v[180:183], v[104:107]
	v_mfma_f32_16x16x32_bf16 v[100:103], v[206:209], v[188:191], v[100:103]
	v_mfma_f32_16x16x32_bf16 v[88:91], v[216:219], v[188:191], v[88:91]
	v_mfma_f32_16x16x32_bf16 v[84:87], v[212:215], v[96:99], v[84:87]
	v_mfma_f32_16x16x32_bf16 v[92:95], v[220:223], v[96:99], v[92:95]
	v_mfma_f32_16x16x32_bf16 v[96:99], v[206:209], v[180:183], v[120:123]
	v_mfma_f32_16x16x32_bf16 v[104:107], v[220:223], v[184:187], v[104:107]
	v_mfma_f32_16x16x32_bf16 v[100:103], v[212:215], v[192:195], v[100:103]
	v_mfma_f32_16x16x32_bf16 v[88:91], v[220:223], v[192:195], v[88:91]
	v_mfma_f32_16x16x32_bf16 v[96:99], v[212:215], v[184:187], v[96:99]
	s_barrier
	s_setprio 0
	s_mov_b32 m0, s62
	s_add_u32 s100, s48, 0x80
	s_addc_u32 s101, s49, 0
	ds_read_b128 v[120:123], v202 offset:16384
	ds_read_b128 v[128:131], v202 offset:17408
	ds_read_b128 v[136:139], v202 offset:18432
	ds_read_b128 v[148:151], v202 offset:19456
	ds_read_b128 v[180:183], v202 offset:20480
	ds_read_b128 v[184:187], v202 offset:21504
	ds_read_b128 v[188:191], v202 offset:22528
	ds_read_b128 v[192:195], v202 offset:23552
	global_load_lds_dwordx4 v166, s[48:49]
	s_mov_b32 m0, s63
	s_nop 0
	global_load_lds_dwordx4 v162, s[48:49]
	s_waitcnt vmcnt(10)
	s_waitcnt lgkmcnt(0)
	s_setprio 1
	s_barrier
	v_mfma_f32_16x16x32_bf16 v[60:63], v[64:67], v[120:123], v[60:63]
	v_mfma_f32_16x16x32_bf16 v[48:51], v[72:75], v[120:123], v[48:51]
	v_mfma_f32_16x16x32_bf16 v[44:47], v[64:67], v[136:139], v[44:47]
	v_mfma_f32_16x16x32_bf16 v[36:39], v[72:75], v[136:139], v[36:39]
	v_mfma_f32_16x16x32_bf16 v[28:31], v[64:67], v[180:183], v[28:31]
	v_mfma_f32_16x16x32_bf16 v[20:23], v[72:75], v[180:183], v[20:23]
	v_mfma_f32_16x16x32_bf16 v[16:19], v[64:67], v[188:191], v[16:19]
	v_mfma_f32_16x16x32_bf16 v[12:15], v[72:75], v[188:191], v[12:15]
	v_mfma_f32_16x16x32_bf16 v[60:63], v[68:71], v[128:131], v[60:63]
	v_mfma_f32_16x16x32_bf16 v[48:51], v[76:79], v[128:131], v[48:51]
	v_mfma_f32_16x16x32_bf16 v[44:47], v[68:71], v[148:151], v[44:47]
	v_mfma_f32_16x16x32_bf16 v[36:39], v[76:79], v[148:151], v[36:39]
	v_mfma_f32_16x16x32_bf16 v[28:31], v[68:71], v[184:187], v[28:31]
	v_mfma_f32_16x16x32_bf16 v[20:23], v[76:79], v[184:187], v[20:23]
	v_mfma_f32_16x16x32_bf16 v[16:19], v[68:71], v[192:195], v[16:19]
	v_mfma_f32_16x16x32_bf16 v[12:15], v[76:79], v[192:195], v[12:15]
	s_barrier
	s_setprio 0
	s_add_u32 s54, s46, 0x80000
	s_addc_u32 s55, s47, 0
	s_add_i32 s53, s73, s60
	s_mov_b32 m0, s53
	s_nop 0
	global_load_lds_dwordx4 v164, s[54:55]
	s_add_i32 m0, s53, 0x2000
	s_nop 0
	global_load_lds_dwordx4 v160, s[54:55]
	s_add_i32 s53, 0, 0x18000
	v_add_u32_e32 v76, s53, v198
	ds_read_b128 v[64:67], v76
	ds_read_b128 v[68:71], v76 offset:1024
	ds_read_b128 v[72:75], v76 offset:2048
	ds_read_b128 v[76:79], v76 offset:3072
	s_waitcnt vmcnt(6)
	s_setprio 1
	s_barrier
; #define PG8_STAGE(bufoff, gbase, voff) do { _Pragma("unroll") for (int _i = 0; _i < 2; ++_i) \
;     __builtin_amdgcn_global_load_lds((const unsigned*)((const char*)(gbase) + (voff)[_i]), (LAS unsigned*)(lds + (bufoff) + ldsw + _i * 8192), 16, 0, 0); } while (0)
; #define PG8_LDA(dst, b, h) do { _Pragma("unroll") for (int m = 0; m < 4; ++m) _Pragma("unroll") for (int k = 0; k < 2; ++k) dst[m][k] = *(const LAS bf16x8*)(lds + PG8_SA(b, h) + aoff + m * 2048 + k * 1024); } while (0)
; #define PG8_LDB(dst, b, h) do { _Pragma("unroll") for (int n = 0; n < 2; ++n) _Pragma("unroll") for (int k = 0; k < 2; ++k) dst[n][k] = *(const LAS bf16x8*)(lds + PG8_SB(b, h) + boff + n * 2048 + k * 1024); } while (0)
; #define PG8_MMA(ai, bj, At, Bt) do { __builtin_amdgcn_s_setprio(1); _Pragma("unroll") for (int m = 0; m < 4; ++m) _Pragma("unroll") for (int n = 0; n < 2; ++n) _Pragma("unroll") for (int k = 0; k < 2; ++k) \
;     acc[ai][bj][m][n] = __builtin_amdgcn_mfma_f32_16x16x32_bf16(Bt[n][k], At[m][k], acc[ai][bj][m][n], 0, 0, 0); __builtin_amdgcn_s_setprio(0); } while (0)
; #define PG8_WAIT_V(n) asm volatile("s_waitcnt vmcnt(" #n ")" ::: "memory")
; #define PG8_WAIT_L(n) asm volatile("s_waitcnt lgkmcnt(" #n ")" ::: "memory")
; #define PG8_BAR __builtin_amdgcn_s_barrier()
; #define PG8_SCHED __builtin_amdgcn_sched_barrier(0)
; template <class Epi, class Sched = StaticOrder>
; DI void gemm_phase(LAS unsigned char* lds, const Gemm g, const Sched& S, const Epi& E) {
;     ...
;       PG8_LDA(At, 0, 1); PG8_STAGE(PG8_SA(0, 0), a2, voffA);
;       PG8_BAR; PG8_WAIT_L(0); PG8_MMA(1, 0, At, B0); PG8_BAR; PG8_SCHED;
;       PG8_STAGE(PG8_SB(0, 1), b2 + hstep, voffB);
;       PG8_WAIT_V(6); PG8_BAR; PG8_MMA(1, 1, At, B1); PG8_BAR;
;       PG8_LDB(B0, 1, 0); PG8_SCHED; PG8_LDA(At, 1, 0); PG8_STAGE(PG8_SA(0, 1), a2 + hstep, voffA);
;       PG8_WAIT_L(8); PG8_BAR; PG8_WAIT_L(0); PG8_MMA(0, 0, At, B0); PG8_BAR; PG8_SCHED;
;       PG8_LDB(B1, 1, 1); PG8_STAGE(PG8_SB(1, 0), b3, voffB);
;       PG8_BAR; PG8_WAIT_L(0); PG8_MMA(0, 1, At, B1); PG8_BAR;
;       PG8_LDA(At, 1, 1); PG8_STAGE(PG8_SA(1, 0), a3, voffA);
;       PG8_BAR; PG8_WAIT_L(0); PG8_MMA(1, 0, At, B0); PG8_BAR; PG8_SCHED;
	v_mfma_f32_16x16x32_bf16 v[56:59], v[206:209], v[120:123], v[56:59]
	v_mfma_f32_16x16x32_bf16 v[52:55], v[216:219], v[120:123], v[52:55]
	v_mfma_f32_16x16x32_bf16 v[40:43], v[206:209], v[136:139], v[40:43]
	v_mfma_f32_16x16x32_bf16 v[32:35], v[216:219], v[136:139], v[32:35]
	v_mfma_f32_16x16x32_bf16 v[24:27], v[206:209], v[180:183], v[24:27]
	v_mfma_f32_16x16x32_bf16 v[8:11], v[216:219], v[180:183], v[8:11]
	v_mfma_f32_16x16x32_bf16 v[4:7], v[206:209], v[188:191], v[4:7]
	v_mfma_f32_16x16x32_bf16 v[0:3], v[216:219], v[188:191], v[0:3]
	v_mfma_f32_16x16x32_bf16 v[56:59], v[212:215], v[128:131], v[56:59]
	v_mfma_f32_16x16x32_bf16 v[52:55], v[220:223], v[128:131], v[52:55]
	v_mfma_f32_16x16x32_bf16 v[40:43], v[212:215], v[148:151], v[40:43]
	v_mfma_f32_16x16x32_bf16 v[32:35], v[220:223], v[148:151], v[32:35]
	v_mfma_f32_16x16x32_bf16 v[24:27], v[212:215], v[184:187], v[24:27]
	v_mfma_f32_16x16x32_bf16 v[8:11], v[220:223], v[184:187], v[8:11]
	v_mfma_f32_16x16x32_bf16 v[4:7], v[212:215], v[192:195], v[4:7]
	v_mfma_f32_16x16x32_bf16 v[0:3], v[220:223], v[192:195], v[0:3]
	s_barrier
	s_setprio 0
	s_add_u32 s48, s48, 0x80000
	s_addc_u32 s49, s49, 0
	s_mov_b32 m0, s64
	ds_read_b128 v[120:123], v202 offset:32768
	ds_read_b128 v[128:131], v202 offset:33792
	ds_read_b128 v[180:183], v202 offset:34816
	ds_read_b128 v[184:187], v202 offset:35840
	ds_read_b128 v[188:191], v202 offset:36864
	ds_read_b128 v[192:195], v202 offset:37888
	ds_read_b128 v[206:209], v202 offset:38912
	ds_read_b128 v[212:215], v202 offset:39936
	global_load_lds_dwordx4 v166, s[48:49]
	s_mov_b32 m0, s65
	s_nop 0
	global_load_lds_dwordx4 v162, s[48:49]
	s_waitcnt lgkmcnt(0)
	s_setprio 1
	s_barrier
	v_mfma_f32_16x16x32_bf16 v[136:139], v[64:67], v[120:123], v[156:159]
	v_mfma_f32_16x16x32_bf16 v[156:159], v[68:71], v[128:131], v[136:139]
	v_mfma_f32_16x16x32_bf16 v[136:139], v[72:75], v[120:123], v[144:147]
	v_mfma_f32_16x16x32_bf16 v[144:147], v[76:79], v[128:131], v[136:139]
	v_mfma_f32_16x16x32_bf16 v[136:139], v[64:67], v[180:183], v[140:143]
	v_mfma_f32_16x16x32_bf16 v[132:135], v[72:75], v[180:183], v[132:135]
	v_mfma_f32_16x16x32_bf16 v[124:127], v[64:67], v[188:191], v[124:127]
	v_mfma_f32_16x16x32_bf16 v[116:119], v[72:75], v[188:191], v[116:119]
	v_mfma_f32_16x16x32_bf16 v[112:115], v[64:67], v[206:209], v[112:115]
	v_mfma_f32_16x16x32_bf16 v[108:111], v[72:75], v[206:209], v[108:111]
	v_mfma_f32_16x16x32_bf16 v[140:143], v[68:71], v[184:187], v[136:139]
	v_mfma_f32_16x16x32_bf16 v[132:135], v[76:79], v[184:187], v[132:135]
	v_mfma_f32_16x16x32_bf16 v[124:127], v[68:71], v[192:195], v[124:127]
	v_mfma_f32_16x16x32_bf16 v[116:119], v[76:79], v[192:195], v[116:119]
	v_mfma_f32_16x16x32_bf16 v[112:115], v[68:71], v[212:215], v[112:115]
	v_mfma_f32_16x16x32_bf16 v[108:111], v[76:79], v[212:215], v[108:111]
	s_barrier
	s_setprio 0
	s_add_i32 s48, 0, 0x1c000
	v_add_u32_e32 v136, s48, v198
	s_add_i32 s49, s53, s60
	ds_read_b128 v[216:219], v136
	ds_read_b128 v[220:223], v136 offset:1024
	ds_read_b128 v[224:227], v136 offset:2048
	ds_read_b128 v[228:231], v136 offset:3072
	s_mov_b32 m0, s49
	s_nop 0
	global_load_lds_dwordx4 v164, s[98:99]
	s_add_i32 m0, s49, 0x2000
	s_nop 0
	global_load_lds_dwordx4 v160, s[98:99]
	s_waitcnt lgkmcnt(0)
	s_setprio 1
	s_barrier
	v_mfma_f32_16x16x32_bf16 v[80:83], v[224:227], v[120:123], v[80:83]
	v_mfma_f32_16x16x32_bf16 v[136:139], v[216:219], v[120:123], v[152:155]
	v_mfma_f32_16x16x32_bf16 v[148:151], v[228:231], v[128:131], v[80:83]
	v_mfma_f32_16x16x32_bf16 v[80:83], v[216:219], v[180:183], v[84:87]
	v_mfma_f32_16x16x32_bf16 v[152:155], v[220:223], v[128:131], v[136:139]
	v_mfma_f32_16x16x32_bf16 v[136:139], v[220:223], v[184:187], v[80:83]
	v_mfma_f32_16x16x32_bf16 v[80:83], v[224:227], v[180:183], v[92:95]
	v_mfma_f32_16x16x32_bf16 v[128:131], v[228:231], v[184:187], v[80:83]
	v_mfma_f32_16x16x32_bf16 v[80:83], v[216:219], v[188:191], v[96:99]
	v_mfma_f32_16x16x32_bf16 v[120:123], v[220:223], v[192:195], v[80:83]
	v_mfma_f32_16x16x32_bf16 v[80:83], v[224:227], v[188:191], v[104:107]
	v_mfma_f32_16x16x32_bf16 v[104:107], v[228:231], v[192:195], v[80:83]
	v_mfma_f32_16x16x32_bf16 v[80:83], v[216:219], v[206:209], v[100:103]
	v_mfma_f32_16x16x32_bf16 v[100:103], v[220:223], v[212:215], v[80:83]
	v_mfma_f32_16x16x32_bf16 v[80:83], v[224:227], v[206:209], v[88:91]
	v_mfma_f32_16x16x32_bf16 v[88:91], v[228:231], v[212:215], v[80:83]
	s_barrier
	s_setprio 0
	s_mov_b32 m0, s67
	s_nop 2
	ds_read_b128 v[80:83], v202 offset:49152
	ds_read_b128 v[84:87], v202 offset:50176
	ds_read_b128 v[92:95], v202 offset:51200
	ds_read_b128 v[96:99], v202 offset:52224
	ds_read_b128 v[180:183], v202 offset:53248
	ds_read_b128 v[184:187], v202 offset:54272
	ds_read_b128 v[188:191], v202 offset:55296
	ds_read_b128 v[192:195], v202 offset:56320
	global_load_lds_dwordx4 v166, s[100:101]
	s_mov_b32 m0, s68
	s_nop 0
	global_load_lds_dwordx4 v162, s[100:101]
	s_waitcnt vmcnt(10)
	s_waitcnt lgkmcnt(0)
	s_setprio 1
	s_barrier
	v_mfma_f32_16x16x32_bf16 v[60:63], v[64:67], v[80:83], v[60:63]
	v_mfma_f32_16x16x32_bf16 v[48:51], v[72:75], v[80:83], v[48:51]
	v_mfma_f32_16x16x32_bf16 v[44:47], v[64:67], v[92:95], v[44:47]
	v_mfma_f32_16x16x32_bf16 v[36:39], v[72:75], v[92:95], v[36:39]
	v_mfma_f32_16x16x32_bf16 v[28:31], v[64:67], v[180:183], v[28:31]
	v_mfma_f32_16x16x32_bf16 v[20:23], v[72:75], v[180:183], v[20:23]
	v_mfma_f32_16x16x32_bf16 v[16:19], v[64:67], v[188:191], v[16:19]
	v_mfma_f32_16x16x32_bf16 v[12:15], v[72:75], v[188:191], v[12:15]
	v_mfma_f32_16x16x32_bf16 v[60:63], v[68:71], v[84:87], v[60:63]
	v_mfma_f32_16x16x32_bf16 v[48:51], v[76:79], v[84:87], v[48:51]
	v_mfma_f32_16x16x32_bf16 v[44:47], v[68:71], v[96:99], v[44:47]
	v_mfma_f32_16x16x32_bf16 v[36:39], v[76:79], v[96:99], v[36:39]
	v_mfma_f32_16x16x32_bf16 v[28:31], v[68:71], v[184:187], v[28:31]
	v_mfma_f32_16x16x32_bf16 v[20:23], v[76:79], v[184:187], v[20:23]
	v_mfma_f32_16x16x32_bf16 v[16:19], v[68:71], v[192:195], v[16:19]
	v_mfma_f32_16x16x32_bf16 v[12:15], v[76:79], v[192:195], v[12:15]
	s_barrier
; #define PG8_STAGE(bufoff, gbase, voff) do { _Pragma("unroll") for (int _i = 0; _i < 2; ++_i) \
;     __builtin_amdgcn_global_load_lds((const unsigned*)((const char*)(gbase) + (voff)[_i]), (LAS unsigned*)(lds + (bufoff) + ldsw + _i * 8192), 16, 0, 0); } while (0)
; #define PG8_LDA(dst, b, h) do { _Pragma("unroll") for (int m = 0; m < 4; ++m) _Pragma("unroll") for (int k = 0; k < 2; ++k) dst[m][k] = *(const LAS bf16x8*)(lds + PG8_SA(b, h) + aoff + m * 2048 + k * 1024); } while (0)
; #define PG8_LDB(dst, b, h) do { _Pragma("unroll") for (int n = 0; n < 2; ++n) _Pragma("unroll") for (int k = 0; k < 2; ++k) dst[n][k] = *(const LAS bf16x8*)(lds + PG8_SB(b, h) + boff + n * 2048 + k * 1024); } while (0)
; #define PG8_MMA(ai, bj, At, Bt) do { __builtin_amdgcn_s_setprio(1); _Pragma("unroll") for (int m = 0; m < 4; ++m) _Pragma("unroll") for (int n = 0; n < 2; ++n) _Pragma("unroll") for (int k = 0; k < 2; ++k) \
;     acc[ai][bj][m][n] = __builtin_amdgcn_mfma_f32_16x16x32_bf16(Bt[n][k], At[m][k], acc[ai][bj][m][n], 0, 0, 0); __builtin_amdgcn_s_setprio(0); } while (0)
; #define PG8_WAIT_V(n) asm volatile("s_waitcnt vmcnt(" #n ")" ::: "memory")
; #define PG8_WAIT_L(n) asm volatile("s_waitcnt lgkmcnt(" #n ")" ::: "memory")
;   DI void operator()(const f32x4 (&acc)[2][2][4][2], const Unit& u, int wr, int wc, int fr, int fq) const {
;     const int col = u.pn * 128 + wc * 32 + 8 * fq;
;     float w0[8], w1[8], w2[8], bb[8];
; #pragma unroll
;     for (int e = 0; e < 8; ++e) { w0[e] = cw[col + e]; w1[e] = cw[5632 + col + e]; w2[e] = cw[2 * 5632 + col + e]; bb[e] = cb[col + e]; }
; #pragma unroll
;     for (int ai = 0; ai < 2; ++ai) {
;       const int row0 = u.pm * BM + ai * HALF + wr * 64, span = row0 >> 6;
;       float rsv[4];
; #pragma unroll
;       for (int m = 0; m < 4; ++m) rsv[m] = row_rstd(ssq, row0 + 16 * m + fr, fq);
; template <class Epi, class Sched = StaticOrder>
; DI void gemm_phase(LAS unsigned char* lds, const Gemm g, const Sched& S, const Epi& E) {
;     ...
;       PG8_LDB(B1, 1, 1); PG8_STAGE(PG8_SB(1, 0), b3, voffB);
;       PG8_BAR; PG8_WAIT_L(0); PG8_MMA(0, 1, At, B1); PG8_BAR;
;       PG8_LDA(At, 1, 1); PG8_STAGE(PG8_SA(1, 0), a3, voffA);
;       PG8_BAR; PG8_WAIT_L(0); PG8_MMA(1, 0, At, B0); PG8_BAR; PG8_SCHED;
;       PG8_STAGE(PG8_SB(1, 1), b3 + hstep, voffB);
;       PG8_WAIT_V(6); PG8_BAR; PG8_MMA(1, 1, At, B1); PG8_BAR;
	s_setprio 0
	s_add_u32 s46, s46, 0x80080
	s_addc_u32 s47, s47, 0
	s_add_i32 s48, s48, s60
	s_mov_b32 m0, s48
	s_nop 0
	global_load_lds_dwordx4 v164, s[46:47]
	s_add_i32 m0, s48, 0x2000
	s_nop 0
	global_load_lds_dwordx4 v160, s[46:47]
	ds_read_b128 v[64:67], v201
	ds_read_b128 v[68:71], v201 offset:1024
	ds_read_b128 v[72:75], v201 offset:2048
	ds_read_b128 v[76:79], v201 offset:3072
	s_waitcnt vmcnt(6)
	s_add_i32 s52, s52, 2
	s_add_u32 s14, s14, 0x100
	s_addc_u32 s15, s15, 0
	s_add_u32 s44, s44, 0x100
	s_addc_u32 s45, s45, 0
	s_cmp_gt_u32 s52, 29
	s_setprio 1
	s_barrier
	v_mfma_f32_16x16x32_bf16 v[56:59], v[216:219], v[80:83], v[56:59]
	v_mfma_f32_16x16x32_bf16 v[52:55], v[224:227], v[80:83], v[52:55]
	v_mfma_f32_16x16x32_bf16 v[40:43], v[216:219], v[92:95], v[40:43]
	v_mfma_f32_16x16x32_bf16 v[32:35], v[224:227], v[92:95], v[32:35]
	v_mfma_f32_16x16x32_bf16 v[24:27], v[216:219], v[180:183], v[24:27]
	v_mfma_f32_16x16x32_bf16 v[8:11], v[224:227], v[180:183], v[8:11]
	v_mfma_f32_16x16x32_bf16 v[4:7], v[216:219], v[188:191], v[4:7]
	v_mfma_f32_16x16x32_bf16 v[0:3], v[224:227], v[188:191], v[0:3]
	v_mfma_f32_16x16x32_bf16 v[56:59], v[220:223], v[84:87], v[56:59]
	v_mfma_f32_16x16x32_bf16 v[52:55], v[228:231], v[84:87], v[52:55]
	v_mfma_f32_16x16x32_bf16 v[40:43], v[220:223], v[96:99], v[40:43]
	v_mfma_f32_16x16x32_bf16 v[32:35], v[228:231], v[96:99], v[32:35]
	v_mfma_f32_16x16x32_bf16 v[24:27], v[220:223], v[184:187], v[24:27]
	v_mfma_f32_16x16x32_bf16 v[8:11], v[228:231], v[184:187], v[8:11]
	v_mfma_f32_16x16x32_bf16 v[4:7], v[220:223], v[192:195], v[4:7]
	v_mfma_f32_16x16x32_bf16 v[0:3], v[228:231], v[192:195], v[0:3]
	s_barrier
	s_setprio 0
	s_cbranch_scc0 .LBB0_811
	s_waitcnt lgkmcnt(0)
	s_lshl_b32 s35, s12, 8
	s_add_i32 s35, s35, s66
	v_or_b32_e32 v190, s35, v179
	v_ashrrev_i32_e32 v191, 31, v190
	v_lshlrev_b64 v[64:65], 7, v[190:191]
	v_or_b32_e32 v188, 16, v190
	v_lshl_add_u64 v[64:65], v[168:169], 0, v[64:65]
	v_ashrrev_i32_e32 v189, 31, v188
	global_load_dwordx4 v[192:195], v[64:65], off
	global_load_dwordx4 v[206:209], v[64:65], off offset:16
	v_lshlrev_b64 v[64:65], 7, v[188:189]
	v_lshl_add_u64 v[64:65], v[168:169], 0, v[64:65]
	global_load_dwordx4 v[212:215], v[64:65], off
	global_load_dwordx4 v[216:219], v[64:65], off offset:16
	v_or_b32_e32 v186, 32, v190
	v_ashrrev_i32_e32 v187, 31, v186
	v_lshlrev_b64 v[64:65], 7, v[186:187]
	v_or_b32_e32 v184, 48, v190
	v_lshl_add_u64 v[64:65], v[168:169], 0, v[64:65]
	v_ashrrev_i32_e32 v185, 31, v184
	global_load_dwordx4 v[220:223], v[64:65], off
	global_load_dwordx4 v[224:227], v[64:65], off offset:16
	v_lshlrev_b64 v[64:65], 7, v[184:185]
	v_lshl_add_u64 v[64:65], v[168:169], 0, v[64:65]
	global_load_dwordx4 v[228:231], v[64:65], off
	global_load_dwordx4 v[232:235], v[64:65], off offset:16
	v_lshl_or_b32 v180, s13, 7, v200
	v_and_b32_e32 v65, 64, v204
	v_xor_b32_e32 v64, 16, v204
	v_ashrrev_i32_e32 v181, 31, v180
	v_add_u32_e32 v65, 64, v65
	v_readlane_b32 s44, v243, 3
	v_xor_b32_e32 v66, 32, v204
	v_lshlrev_b64 v[182:183], 2, v[180:181]
	v_cmp_lt_i32_e32 vcc, v64, v65
	v_readlane_b32 s52, v243, 11
	v_readlane_b32 s53, v243, 12
	v_cndmask_b32_e32 v64, v204, v64, vcc
	v_cmp_lt_i32_e32 vcc, v66, v65
	v_lshl_add_u64 v[92:93], s[52:53], 0, v[182:183]
	v_readlane_b32 s54, v243, 13
	v_cndmask_b32_e32 v65, v204, v66, vcc
	v_add_co_u32_e32 v94, vcc, 0x5000, v92
	v_readlane_b32 s55, v243, 14
	s_nop 0
	v_addc_co_u32_e32 v95, vcc, 0, v93, vcc
	v_add_co_u32_e32 v96, vcc, 0xb000, v92
	v_lshl_add_u64 v[72:73], s[54:55], 0, v[182:183]
	v_lshl_add_u64 v[74:75], v[92:93], 0, s[26:27]
	v_lshl_add_u64 v[76:77], v[92:93], 0, s[28:29]
	v_addc_co_u32_e32 v97, vcc, 0, v93, vcc
	v_lshlrev_b32_e32 v187, 2, v64
	v_lshlrev_b32_e32 v185, 2, v65
	global_load_dwordx4 v[64:67], v[92:93], off offset:16
	global_load_dwordx4 v[80:83], v[92:93], off
	global_load_dwordx4 v[68:71], v[72:73], off offset:16
	global_load_dwordx4 v[84:87], v[72:73], off
	s_nop 0
	global_load_dwordx4 v[72:75], v[74:75], off offset:16
	s_nop 0
	global_load_dwordx4 v[76:79], v[76:77], off offset:16
	s_nop 0
	global_load_dwordx4 v[92:95], v[94:95], off offset:2048
	s_nop 0
	global_load_dwordx4 v[96:99], v[96:97], off
	v_mov_b32_e32 v211, 0
	v_mov_b32_e32 v205, 0
	v_readlane_b32 s45, v243, 4
	v_readlane_b32 s46, v243, 5
	v_readlane_b32 s47, v243, 6
	v_readlane_b32 s48, v243, 7
	v_readlane_b32 s49, v243, 8
	v_readlane_b32 s50, v243, 9
	v_readlane_b32 s51, v243, 10
	v_readlane_b32 s56, v243, 15
	v_readlane_b32 s57, v243, 16
	v_readlane_b32 s58, v243, 17
	v_readlane_b32 s59, v243, 18
	s_waitcnt vmcnt(0)
	v_mov_b32_e32 v196, v192
	v_mov_b32_e32 v197, v206
	v_mov_b32_e32 v206, v193
	v_mov_b32_e32 v192, v194
	v_mov_b32_e32 v193, v208
	v_mov_b32_e32 v208, v195
	v_pk_add_f32 v[194:195], v[196:197], v[206:207]
	v_pk_add_f32 v[192:193], v[192:193], v[208:209]
	v_mov_b32_e32 v196, v212
	v_mov_b32_e32 v197, v216
	v_mov_b32_e32 v216, v213
	v_mov_b32_e32 v206, v214
	v_mov_b32_e32 v207, v218
	v_mov_b32_e32 v218, v215
	v_pk_add_f32 v[192:193], v[194:195], v[192:193]
	v_pk_add_f32 v[194:195], v[196:197], v[216:217]
	v_pk_add_f32 v[196:197], v[206:207], v[218:219]
	v_mov_b32_e32 v208, v220
	v_pk_add_f32 v[194:195], v[194:195], v[196:197]
	v_mov_b32_e32 v197, v192
	v_mov_b32_e32 v196, v194
	v_mov_b32_e32 v192, v195
	v_pk_add_f32 v[192:193], v[196:197], v[192:193]
	ds_bpermute_b32 v195, v187, v193
	ds_bpermute_b32 v194, v187, v192
	v_mov_b32_e32 v209, v224
	v_mov_b32_e32 v224, v221
	v_mov_b32_e32 v212, v222
	v_mov_b32_e32 v213, v226
	s_waitcnt lgkmcnt(0)
; DI unsigned pack2(float lo, float hi) { f32x2 v = {lo, hi}; bf16v2 r = __builtin_convertvector(v, bf16v2); return __builtin_bit_cast(unsigned, r); }
; DI float silu_f(float x) { return x * sigmoid_f(x); }
; DI float dpp_ror1(float v) { return __int_as_float(__builtin_amdgcn_update_dpp(0, __float_as_int(v), 0x121, 0xf, 0xf, false)); }
; DI float dpp_ror2(float v) { return __int_as_float(__builtin_amdgcn_update_dpp(0, __float_as_int(v), 0x122, 0xf, 0xf, false)); }
;   DI void operator()(const f32x4 (&acc)[2][2][4][2], const Unit& u, int wr, int wc, int fr, int fq) const {
;     ...
;       for (int m = 0; m < 4; ++m) rsv[m] = row_rstd(ssq, row0 + 16 * m + fr, fq);
;       float p1[8], p2[8];
; #pragma unroll
;       for (int e = 0; e < 8; ++e) { p1[e] = 0.f; p2[e] = 0.f; }
; #pragma unroll
;       for (int m = 0; m < 4; ++m) {
;         float g[8], uu[8], a[8];
;         const float rs = rsv[m];
; #pragma unroll
;         for (int e = 0; e < 4; ++e) { g[e] = acc[ai][0][m][0][e] * rs; g[4 + e] = acc[ai][0][m][1][e] * rs; uu[e] = acc[ai][1][m][0][e] * rs; uu[4 + e] = acc[ai][1][m][1][e] * rs; }
; #pragma unroll
;         for (int e = 0; e < 8; ++e) {
;           const float x1 = dpp_ror1(g[e]), x2 = dpp_ror2(g[e]);
;           const float pr1 = (fr == 0) ? p1[e] : x1, pr2 = (fr < 2) ? p2[e] : x2;
;           a[e] = w2[e] * g[e] + w1[e] * pr1 + w0[e] * pr2 + bb[e];
;           p1[e] = x1; p2[e] = x2;
;         }
;         if (m == 0 && fr < 2) {
;           float* ha = headA + (size_t)(span * 2 + fr) * 5632 + col; float* hu = headU + (size_t)(span * 2 + fr) * 5632 + col;
;           *(f32x4*)ha = (f32x4){a[0], a[1], a[2], a[3]}; *(f32x4*)(ha + 4) = (f32x4){a[4], a[5], a[6], a[7]};
;           *(f32x4*)hu = (f32x4){uu[0], uu[1], uu[2], uu[3]}; *(f32x4*)(hu + 4) = (f32x4){uu[4], uu[5], uu[6], uu[7]};
;         } else {
;           u32x4 w;
;           w.x = pack2(silu_f(a[0]) * uu[0], silu_f(a[1]) * uu[1]);
;           w.y = pack2(silu_f(a[2]) * uu[2], silu_f(a[3]) * uu[3]);
;           w.z = pack2(silu_f(a[4]) * uu[4], silu_f(a[5]) * uu[5]);
;           w.w = pack2(silu_f(a[6]) * uu[6], silu_f(a[7]) * uu[7]);
;           *(u32x4*)(H + (size_t)(row0 + 16 * m + fr) * 5632 + col) = w;
;         }
	v_pk_add_f32 v[192:193], v[192:193], v[194:195]
	ds_bpermute_b32 v195, v185, v193
	ds_bpermute_b32 v194, v185, v192
	v_mov_b32_e32 v226, v223
	v_mov_b32_e32 v196, v228
	v_mov_b32_e32 v197, v232
	v_mov_b32_e32 v232, v229
	s_waitcnt lgkmcnt(0)
	v_pk_add_f32 v[192:193], v[192:193], v[194:195]
	v_mov_b32_e32 v206, v230
	v_pk_fma_f32 v[192:193], v[192:193], s[30:31], v[178:179] op_sel_hi:[1,0,0]
	v_mov_b32_e32 v207, v234
	v_mul_f32_e32 v189, 0x4b800000, v193
	v_cmp_gt_f32_e64 s[12:13], s74, v193
	v_mov_b32_e32 v234, v231
	v_pk_add_f32 v[208:209], v[208:209], v[224:225]
	v_cndmask_b32_e64 v189, v193, v189, s[12:13]
	v_rsq_f32_e32 v189, v189
	v_pk_add_f32 v[212:213], v[212:213], v[226:227]
	v_pk_add_f32 v[196:197], v[196:197], v[232:233]
	v_pk_add_f32 v[194:195], v[206:207], v[234:235]
	v_mul_f32_e32 v191, 0x45800000, v189
	v_cndmask_b32_e64 v220, v189, v191, s[12:13]
	v_pk_add_f32 v[208:209], v[208:209], v[212:213]
	v_pk_add_f32 v[194:195], v[196:197], v[194:195]
	v_pk_mul_f32 v[156:157], v[156:157], v[220:221] op_sel_hi:[1,0]
	v_mov_b32_e32 v216, 0
	v_mov_b32_e32 v218, 0
	v_mov_b32_e32 v196, v194
	v_mov_b32_e32 v197, v208
	v_mov_b32_e32 v208, v195
	v_mov_b32_dpp v216, v156 row_ror:1 row_mask:0xf bank_mask:0xf
	v_mov_b32_dpp v218, v157 row_ror:1 row_mask:0xf bank_mask:0xf
	v_pk_add_f32 v[194:195], v[196:197], v[208:209]
	v_cndmask_b32_e64 v207, v218, 0, s[0:1]
	v_cndmask_b32_e64 v206, v216, 0, s[0:1]
	v_pk_mul_f32 v[158:159], v[158:159], v[220:221] op_sel_hi:[1,0]
	v_mov_b32_e32 v212, 0
	v_mov_b32_e32 v214, 0
	ds_bpermute_b32 v197, v187, v195
	ds_bpermute_b32 v196, v187, v194
	v_mov_b32_e32 v215, 0
	v_mov_b32_e32 v217, 0
	v_pk_mul_f32 v[206:207], v[92:93], v[206:207]
	v_mov_b32_dpp v212, v158 row_ror:1 row_mask:0xf bank_mask:0xf
	v_mov_b32_dpp v214, v159 row_ror:1 row_mask:0xf bank_mask:0xf
	v_mov_b32_dpp v215, v156 row_ror:2 row_mask:0xf bank_mask:0xf
	v_mov_b32_dpp v217, v157 row_ror:2 row_mask:0xf bank_mask:0xf
	v_pk_fma_f32 v[156:157], v[96:97], v[156:157], v[206:207]
	v_mov_b32_e32 v213, 0
	v_cndmask_b32_e64 v207, v214, 0, s[0:1]
	v_cndmask_b32_e64 v206, v212, 0, s[0:1]
	v_cndmask_b32_e64 v209, v217, 0, s[4:5]
	v_cndmask_b32_e64 v208, v215, 0, s[4:5]
	v_mov_b32_dpp v211, v158 row_ror:2 row_mask:0xf bank_mask:0xf
	v_mov_b32_dpp v213, v159 row_ror:2 row_mask:0xf bank_mask:0xf
	v_pk_mul_f32 v[206:207], v[94:95], v[206:207]
	v_pk_fma_f32 v[156:157], v[80:81], v[208:209], v[156:157]
	v_cndmask_b32_e64 v209, v213, 0, s[4:5]
	v_cndmask_b32_e64 v208, v211, 0, s[4:5]
	v_pk_fma_f32 v[158:159], v[98:99], v[158:159], v[206:207]
	v_pk_mul_f32 v[144:145], v[144:145], v[220:221] op_sel_hi:[1,0]
	v_pk_fma_f32 v[158:159], v[82:83], v[208:209], v[158:159]
	v_mov_b32_e32 v207, 0
	v_mov_b32_e32 v209, 0
	v_pk_mul_f32 v[146:147], v[146:147], v[220:221] op_sel_hi:[1,0]
	v_mov_b32_e32 v191, 0
	s_waitcnt lgkmcnt(0)
	v_pk_add_f32 v[194:195], v[194:195], v[196:197]
	v_mov_b32_dpp v207, v144 row_ror:1 row_mask:0xf bank_mask:0xf
	v_mov_b32_dpp v209, v145 row_ror:1 row_mask:0xf bank_mask:0xf
	v_mov_b32_dpp v191, v146 row_ror:1 row_mask:0xf bank_mask:0xf
	v_mov_b32_dpp v205, v147 row_ror:1 row_mask:0xf bank_mask:0xf
	ds_bpermute_b32 v197, v185, v195
	ds_bpermute_b32 v196, v185, v194
	v_pk_mul_f32 v[152:153], v[152:153], v[220:221] op_sel_hi:[1,0]
	v_pk_mul_f32 v[148:149], v[148:149], v[220:221] op_sel_hi:[1,0]
	v_pk_mul_f32 v[154:155], v[154:155], v[220:221] op_sel_hi:[1,0]
	v_pk_mul_f32 v[150:151], v[150:151], v[220:221] op_sel_hi:[1,0]
	v_mov_b32_e32 v206, 0
	v_mov_b32_e32 v208, 0
	v_cndmask_b32_e64 v223, v209, 0, s[0:1]
	v_cndmask_b32_e64 v222, v207, 0, s[0:1]
	v_mov_b32_e32 v189, 0
	v_mov_b32_e32 v193, 0
	v_cndmask_b32_e64 v221, v205, 0, s[0:1]
	v_cndmask_b32_e64 v220, v191, 0, s[0:1]
	v_mov_b32_dpp v206, v144 row_ror:2 row_mask:0xf bank_mask:0xf
	v_mov_b32_dpp v208, v145 row_ror:2 row_mask:0xf bank_mask:0xf
	v_pk_mul_f32 v[222:223], v[72:73], v[222:223]
	v_mov_b32_dpp v189, v146 row_ror:2 row_mask:0xf bank_mask:0xf
	v_mov_b32_dpp v193, v147 row_ror:2 row_mask:0xf bank_mask:0xf
	v_pk_mul_f32 v[220:221], v[74:75], v[220:221]
	v_cndmask_b32_e64 v225, v208, 0, s[4:5]
	v_cndmask_b32_e64 v224, v206, 0, s[4:5]
	v_pk_fma_f32 v[144:145], v[76:77], v[144:145], v[222:223]
	v_cndmask_b32_e64 v223, v193, 0, s[4:5]
	v_cndmask_b32_e64 v222, v189, 0, s[4:5]
	v_pk_fma_f32 v[146:147], v[78:79], v[146:147], v[220:221]
	v_pk_fma_f32 v[144:145], v[64:65], v[224:225], v[144:145]
	v_pk_fma_f32 v[146:147], v[66:67], v[222:223], v[146:147]
	v_cmp_gt_f32_e32 vcc, s74, v192
	v_pk_add_f32 v[156:157], v[84:85], v[156:157]
	v_pk_add_f32 v[158:159], v[86:87], v[158:159]
	v_pk_add_f32 v[144:145], v[68:69], v[144:145]
	v_pk_add_f32 v[146:147], v[70:71], v[146:147]
	s_and_saveexec_b64 s[12:13], s[10:11]
	s_xor_b64 s[12:13], exec, s[12:13]
	s_cbranch_execz .LBB0_814
	v_mul_f32_e32 v219, 0xbfb8aa3b, v156
	v_exp_f32_e32 v219, v219
	v_mul_f32_e32 v220, 0xbfb8aa3b, v157
	v_exp_f32_e32 v220, v220
	v_mul_f32_e32 v222, 0xbfb8aa3b, v159
	v_add_f32_e32 v219, 1.0, v219
	v_exp_f32_e32 v223, v222
	v_add_f32_e32 v221, 1.0, v220
	v_rcp_f32_e32 v220, v219
	v_mul_f32_e32 v219, 0xbfb8aa3b, v158
	v_exp_f32_e32 v219, v219
	v_rcp_f32_e32 v221, v221
	v_add_f32_e32 v219, 1.0, v219
	v_rcp_f32_e32 v222, v219
	v_add_f32_e32 v219, 1.0, v223
	v_rcp_f32_e32 v223, v219
	v_pk_mul_f32 v[156:157], v[156:157], v[220:221]
	s_nop 0
	v_pk_mul_f32 v[152:153], v[152:153], v[156:157]
	v_pk_mul_f32 v[156:157], v[158:159], v[222:223]
	v_cvt_pk_bf16_f32 v152, v152, v153
	v_mul_f32_e32 v153, 0xbfb8aa3b, v144
	v_pk_mul_f32 v[154:155], v[154:155], v[156:157]
	v_exp_f32_e32 v156, v153
	v_mul_f32_e32 v153, 0xbfb8aa3b, v145
	v_exp_f32_e32 v157, v153
	v_cvt_pk_bf16_f32 v153, v154, v155
	v_add_f32_e32 v154, 1.0, v156
	v_mul_f32_e32 v156, 0xbfb8aa3b, v146
	v_add_f32_e32 v155, 1.0, v157
	v_mul_f32_e32 v157, 0xbfb8aa3b, v147
	v_exp_f32_e32 v156, v156
	v_exp_f32_e32 v157, v157
	v_rcp_f32_e32 v154, v154
	v_rcp_f32_e32 v155, v155
	v_add_f32_e32 v156, 1.0, v156
	v_add_f32_e32 v157, 1.0, v157
	v_rcp_f32_e32 v156, v156
	v_rcp_f32_e32 v157, v157
	v_pk_mul_f32 v[144:145], v[144:145], v[154:155]
	s_nop 0
	v_pk_mul_f32 v[144:145], v[148:149], v[144:145]
	s_nop 0
	v_cvt_pk_bf16_f32 v154, v144, v145
	v_pk_mul_f32 v[144:145], v[146:147], v[156:157]
	s_nop 0
	v_pk_mul_f32 v[144:145], v[150:151], v[144:145]
	s_nop 0
	v_cvt_pk_bf16_f32 v155, v144, v145
	v_mov_b64_e32 v[144:145], s[16:17]
	v_mad_i64_i32 v[144:145], s[14:15], v190, s75, v[144:145]
	v_lshl_add_u64 v[144:145], v[180:181], 1, v[144:145]
	global_store_dwordx4 v[144:145], v[152:155], off

; #define PG8_STAGE(bufoff, gbase, voff) do { _Pragma("unroll") for (int _i = 0; _i < 2; ++_i) \
;     __builtin_amdgcn_global_load_lds((const unsigned*)((const char*)(gbase) + (voff)[_i]), (LAS unsigned*)(lds + (bufoff) + ldsw + _i * 8192), 16, 0, 0); } while (0)
; #define PG8_LDA(dst, b, h) do { _Pragma("unroll") for (int m = 0; m < 4; ++m) _Pragma("unroll") for (int k = 0; k < 2; ++k) dst[m][k] = *(const LAS bf16x8*)(lds + PG8_SA(b, h) + aoff + m * 2048 + k * 1024); } while (0)
; #define PG8_LDB(dst, b, h) do { _Pragma("unroll") for (int n = 0; n < 2; ++n) _Pragma("unroll") for (int k = 0; k < 2; ++k) dst[n][k] = *(const LAS bf16x8*)(lds + PG8_SB(b, h) + boff + n * 2048 + k * 1024); } while (0)
; #define PG8_MMA(ai, bj, At, Bt) do { __builtin_amdgcn_s_setprio(1); _Pragma("unroll") for (int m = 0; m < 4; ++m) _Pragma("unroll") for (int n = 0; n < 2; ++n) _Pragma("unroll") for (int k = 0; k < 2; ++k) \
;     acc[ai][bj][m][n] = __builtin_amdgcn_mfma_f32_16x16x32_bf16(Bt[n][k], At[m][k], acc[ai][bj][m][n], 0, 0, 0); __builtin_amdgcn_s_setprio(0); } while (0)
; #define PG8_WAIT_V(n) asm volatile("s_waitcnt vmcnt(" #n ")" ::: "memory")
; #define PG8_WAIT_L(n) asm volatile("s_waitcnt lgkmcnt(" #n ")" ::: "memory")
; #define PG8_BAR __builtin_amdgcn_s_barrier()
; #define PG8_SCHED __builtin_amdgcn_sched_barrier(0)
; template <class Epi, class Sched = StaticOrder>
; DI void gemm_phase(LAS unsigned char* lds, const Gemm g, const Sched& S, const Epi& E) {
;     ...
;       PG8_LDB(B0, 0, 0); PG8_SCHED; PG8_LDA(At, 0, 0); PG8_STAGE(PG8_SA(1, 1), a1 + hstep, voffA);
;       PG8_WAIT_L(8); PG8_BAR; PG8_WAIT_L(0); PG8_MMA(0, 0, At, B0); PG8_BAR; PG8_SCHED;
;       PG8_LDB(B1, 0, 1); PG8_STAGE(PG8_SB(0, 0), b2, voffB);
;       PG8_BAR; PG8_WAIT_L(0); PG8_MMA(0, 1, At, B1); PG8_BAR;
;       PG8_LDA(At, 0, 1); PG8_STAGE(PG8_SA(0, 0), a2, voffA);
;       PG8_BAR; PG8_WAIT_L(0); PG8_MMA(1, 0, At, B0); PG8_BAR; PG8_SCHED;
;       PG8_STAGE(PG8_SB(0, 1), b2 + hstep, voffB);
;       PG8_WAIT_V(6); PG8_BAR; PG8_MMA(1, 1, At, B1); PG8_BAR;
;       PG8_LDB(B0, 1, 0); PG8_SCHED; PG8_LDA(At, 1, 0); PG8_STAGE(PG8_SA(0, 1), a2 + hstep, voffA);
;       PG8_WAIT_L(8); PG8_BAR; PG8_WAIT_L(0); PG8_MMA(0, 0, At, B0); PG8_BAR; PG8_SCHED;
;       PG8_LDB(B1, 1, 1); PG8_STAGE(PG8_SB(1, 0), b3, voffB);
;       PG8_BAR; PG8_WAIT_L(0); PG8_MMA(0, 1, At, B1); PG8_BAR;
.LBB0_961:
	s_add_u32 s20, s18, 0xffea0080
	s_addc_u32 s21, s19, -1
	s_cmpk_eq_i32 s44, 0x54
	s_cselect_b32 s23, s5, s21
	s_cselect_b32 s22, s4, s20
	s_cselect_b32 s21, s7, s43
	s_cselect_b32 s20, s6, s42
	s_add_i32 m0, s31, 0xc000
	ds_read_b128 v[144:147], v215
	ds_read_b128 v[148:151], v215 offset:1024
	ds_read_b128 v[152:155], v215 offset:2048
	ds_read_b128 v[156:159], v215 offset:3072
	ds_read_b128 v[160:163], v215 offset:4096
	ds_read_b128 v[164:167], v215 offset:5120
	ds_read_b128 v[168:171], v215 offset:6144
	ds_read_b128 v[172:175], v215 offset:7168
	global_load_lds_dwordx4 v184, s[18:19]
	s_add_i32 m0, s31, 0xe000
	s_nop 0
	global_load_lds_dwordx4 v186, s[18:19]
	s_waitcnt lgkmcnt(0)
	s_setprio 1
	s_barrier
	v_mfma_f32_16x16x32_bf16 v[124:127], v[128:131], v[144:147], v[124:127]
	v_mfma_f32_16x16x32_bf16 v[120:123], v[136:139], v[144:147], v[120:123]
	v_mfma_f32_16x16x32_bf16 v[108:111], v[128:131], v[152:155], v[108:111]
	v_mfma_f32_16x16x32_bf16 v[104:107], v[136:139], v[152:155], v[104:107]
	v_mfma_f32_16x16x32_bf16 v[92:95], v[128:131], v[160:163], v[92:95]
	v_mfma_f32_16x16x32_bf16 v[88:91], v[136:139], v[160:163], v[88:91]
	v_mfma_f32_16x16x32_bf16 v[76:79], v[128:131], v[168:171], v[76:79]
	v_mfma_f32_16x16x32_bf16 v[72:75], v[136:139], v[168:171], v[72:75]
	v_mfma_f32_16x16x32_bf16 v[124:127], v[132:135], v[148:151], v[124:127]
	v_mfma_f32_16x16x32_bf16 v[120:123], v[140:143], v[148:151], v[120:123]
	v_mfma_f32_16x16x32_bf16 v[108:111], v[132:135], v[156:159], v[108:111]
	v_mfma_f32_16x16x32_bf16 v[104:107], v[140:143], v[156:159], v[104:107]
	v_mfma_f32_16x16x32_bf16 v[92:95], v[132:135], v[164:167], v[92:95]
	v_mfma_f32_16x16x32_bf16 v[88:91], v[140:143], v[164:167], v[88:91]
	v_mfma_f32_16x16x32_bf16 v[76:79], v[132:135], v[172:175], v[76:79]
	v_mfma_f32_16x16x32_bf16 v[72:75], v[140:143], v[172:175], v[72:75]
	s_barrier
	s_setprio 0
	s_add_i32 s45, s46, s30
	s_add_u32 s98, s20, 0x80
	s_addc_u32 s99, s21, 0
	s_mov_b32 m0, s45
	ds_read_b128 v[192:195], v216
	ds_read_b128 v[196:199], v216 offset:1024
	ds_read_b128 v[200:203], v216 offset:2048
	ds_read_b128 v[204:207], v216 offset:3072
	global_load_lds_dwordx4 v178, s[20:21]
	s_add_i32 m0, s45, 0x2000
	s_nop 0
	global_load_lds_dwordx4 v182, s[20:21]
	s_waitcnt lgkmcnt(0)
	s_setprio 1
	s_barrier
	v_mfma_f32_16x16x32_bf16 v[116:119], v[192:195], v[144:147], v[116:119]
	v_mfma_f32_16x16x32_bf16 v[112:115], v[200:203], v[144:147], v[112:115]
	v_mfma_f32_16x16x32_bf16 v[100:103], v[192:195], v[152:155], v[100:103]
	v_mfma_f32_16x16x32_bf16 v[96:99], v[200:203], v[152:155], v[96:99]
	v_mfma_f32_16x16x32_bf16 v[84:87], v[192:195], v[160:163], v[84:87]
	v_mfma_f32_16x16x32_bf16 v[80:83], v[200:203], v[160:163], v[80:83]
	v_mfma_f32_16x16x32_bf16 v[68:71], v[192:195], v[168:171], v[68:71]
	v_mfma_f32_16x16x32_bf16 v[64:67], v[200:203], v[168:171], v[64:67]
	v_mfma_f32_16x16x32_bf16 v[116:119], v[196:199], v[148:151], v[116:119]
	v_mfma_f32_16x16x32_bf16 v[112:115], v[204:207], v[148:151], v[112:115]
	v_mfma_f32_16x16x32_bf16 v[100:103], v[196:199], v[156:159], v[100:103]
	v_mfma_f32_16x16x32_bf16 v[96:99], v[204:207], v[156:159], v[96:99]
	v_mfma_f32_16x16x32_bf16 v[84:87], v[196:199], v[164:167], v[84:87]
	v_mfma_f32_16x16x32_bf16 v[80:83], v[204:207], v[164:167], v[80:83]
	v_mfma_f32_16x16x32_bf16 v[68:71], v[196:199], v[172:175], v[68:71]
	v_mfma_f32_16x16x32_bf16 v[64:67], v[204:207], v[172:175], v[64:67]
	s_barrier
	s_setprio 0
	s_mov_b32 m0, s31
	s_add_u32 s100, s22, 0x80
	s_addc_u32 s101, s23, 0
	ds_read_b128 v[144:147], v215 offset:16384
	ds_read_b128 v[148:151], v215 offset:17408
	ds_read_b128 v[152:155], v215 offset:18432
	ds_read_b128 v[156:159], v215 offset:19456
	ds_read_b128 v[160:163], v215 offset:20480
	ds_read_b128 v[164:167], v215 offset:21504
	ds_read_b128 v[168:171], v215 offset:22528
	ds_read_b128 v[172:175], v215 offset:23552
	global_load_lds_dwordx4 v176, s[22:23]
	s_mov_b32 m0, s33
	s_nop 0
	global_load_lds_dwordx4 v180, s[22:23]
	s_waitcnt vmcnt(10)
	s_waitcnt lgkmcnt(0)
	s_setprio 1
	s_barrier
	v_mfma_f32_16x16x32_bf16 v[60:63], v[128:131], v[144:147], v[60:63]
	v_mfma_f32_16x16x32_bf16 v[56:59], v[136:139], v[144:147], v[56:59]
	v_mfma_f32_16x16x32_bf16 v[44:47], v[128:131], v[152:155], v[44:47]
	v_mfma_f32_16x16x32_bf16 v[40:43], v[136:139], v[152:155], v[40:43]
	v_mfma_f32_16x16x32_bf16 v[28:31], v[128:131], v[160:163], v[28:31]
	v_mfma_f32_16x16x32_bf16 v[24:27], v[136:139], v[160:163], v[24:27]
	v_mfma_f32_16x16x32_bf16 v[12:15], v[128:131], v[168:171], v[12:15]
	v_mfma_f32_16x16x32_bf16 v[8:11], v[136:139], v[168:171], v[8:11]
	v_mfma_f32_16x16x32_bf16 v[60:63], v[132:135], v[148:151], v[60:63]
	v_mfma_f32_16x16x32_bf16 v[56:59], v[140:143], v[148:151], v[56:59]
	v_mfma_f32_16x16x32_bf16 v[44:47], v[132:135], v[156:159], v[44:47]
	v_mfma_f32_16x16x32_bf16 v[40:43], v[140:143], v[156:159], v[40:43]
	v_mfma_f32_16x16x32_bf16 v[28:31], v[132:135], v[164:167], v[28:31]
	v_mfma_f32_16x16x32_bf16 v[24:27], v[140:143], v[164:167], v[24:27]
	v_mfma_f32_16x16x32_bf16 v[12:15], v[132:135], v[172:175], v[12:15]
	v_mfma_f32_16x16x32_bf16 v[8:11], v[140:143], v[172:175], v[8:11]
	s_barrier
	s_setprio 0
	s_add_u32 s52, s20, 0x160000
	s_addc_u32 s53, s21, 0
	s_add_i32 s45, s47, s30
	s_mov_b32 m0, s45
	s_nop 0
	global_load_lds_dwordx4 v178, s[52:53]
	s_add_i32 m0, s45, 0x2000
	s_nop 0
	global_load_lds_dwordx4 v182, s[52:53]
	s_add_i32 s45, 0, 0x18000
	v_add_u32_e32 v140, s45, v212
	ds_read_b128 v[128:131], v140
	ds_read_b128 v[132:135], v140 offset:1024
	ds_read_b128 v[136:139], v140 offset:2048
	ds_read_b128 v[140:143], v140 offset:3072
	s_waitcnt vmcnt(6)
	s_setprio 1
	s_barrier
; #define PG8_STAGE(bufoff, gbase, voff) do { _Pragma("unroll") for (int _i = 0; _i < 2; ++_i) \
;     __builtin_amdgcn_global_load_lds((const unsigned*)((const char*)(gbase) + (voff)[_i]), (LAS unsigned*)(lds + (bufoff) + ldsw + _i * 8192), 16, 0, 0); } while (0)
; #define PG8_LDA(dst, b, h) do { _Pragma("unroll") for (int m = 0; m < 4; ++m) _Pragma("unroll") for (int k = 0; k < 2; ++k) dst[m][k] = *(const LAS bf16x8*)(lds + PG8_SA(b, h) + aoff + m * 2048 + k * 1024); } while (0)
; #define PG8_LDB(dst, b, h) do { _Pragma("unroll") for (int n = 0; n < 2; ++n) _Pragma("unroll") for (int k = 0; k < 2; ++k) dst[n][k] = *(const LAS bf16x8*)(lds + PG8_SB(b, h) + boff + n * 2048 + k * 1024); } while (0)
; #define PG8_MMA(ai, bj, At, Bt) do { __builtin_amdgcn_s_setprio(1); _Pragma("unroll") for (int m = 0; m < 4; ++m) _Pragma("unroll") for (int n = 0; n < 2; ++n) _Pragma("unroll") for (int k = 0; k < 2; ++k) \
;     acc[ai][bj][m][n] = __builtin_amdgcn_mfma_f32_16x16x32_bf16(Bt[n][k], At[m][k], acc[ai][bj][m][n], 0, 0, 0); __builtin_amdgcn_s_setprio(0); } while (0)
; #define PG8_WAIT_V(n) asm volatile("s_waitcnt vmcnt(" #n ")" ::: "memory")
; #define PG8_WAIT_L(n) asm volatile("s_waitcnt lgkmcnt(" #n ")" ::: "memory")
; #define PG8_BAR __builtin_amdgcn_s_barrier()
; #define PG8_SCHED __builtin_amdgcn_sched_barrier(0)
; template <class Epi, class Sched = StaticOrder>
; DI void gemm_phase(LAS unsigned char* lds, const Gemm g, const Sched& S, const Epi& E) {
;     ...
;       PG8_LDA(At, 0, 1); PG8_STAGE(PG8_SA(0, 0), a2, voffA);
;       PG8_BAR; PG8_WAIT_L(0); PG8_MMA(1, 0, At, B0); PG8_BAR; PG8_SCHED;
;       PG8_STAGE(PG8_SB(0, 1), b2 + hstep, voffB);
;       PG8_WAIT_V(6); PG8_BAR; PG8_MMA(1, 1, At, B1); PG8_BAR;
;       PG8_LDB(B0, 1, 0); PG8_SCHED; PG8_LDA(At, 1, 0); PG8_STAGE(PG8_SA(0, 1), a2 + hstep, voffA);
;       PG8_WAIT_L(8); PG8_BAR; PG8_WAIT_L(0); PG8_MMA(0, 0, At, B0); PG8_BAR; PG8_SCHED;
;       PG8_LDB(B1, 1, 1); PG8_STAGE(PG8_SB(1, 0), b3, voffB);
;       PG8_BAR; PG8_WAIT_L(0); PG8_MMA(0, 1, At, B1); PG8_BAR;
;       PG8_LDA(At, 1, 1); PG8_STAGE(PG8_SA(1, 0), a3, voffA);
;       PG8_BAR; PG8_WAIT_L(0); PG8_MMA(1, 0, At, B0); PG8_BAR; PG8_SCHED;
	v_mfma_f32_16x16x32_bf16 v[52:55], v[192:195], v[144:147], v[52:55]
	v_mfma_f32_16x16x32_bf16 v[48:51], v[200:203], v[144:147], v[48:51]
	v_mfma_f32_16x16x32_bf16 v[36:39], v[192:195], v[152:155], v[36:39]
	v_mfma_f32_16x16x32_bf16 v[32:35], v[200:203], v[152:155], v[32:35]
	v_mfma_f32_16x16x32_bf16 v[20:23], v[192:195], v[160:163], v[20:23]
	v_mfma_f32_16x16x32_bf16 v[16:19], v[200:203], v[160:163], v[16:19]
	v_mfma_f32_16x16x32_bf16 v[4:7], v[192:195], v[168:171], v[4:7]
	v_mfma_f32_16x16x32_bf16 v[0:3], v[200:203], v[168:171], v[0:3]
	v_mfma_f32_16x16x32_bf16 v[52:55], v[196:199], v[148:151], v[52:55]
	v_mfma_f32_16x16x32_bf16 v[48:51], v[204:207], v[148:151], v[48:51]
	v_mfma_f32_16x16x32_bf16 v[36:39], v[196:199], v[156:159], v[36:39]
	v_mfma_f32_16x16x32_bf16 v[32:35], v[204:207], v[156:159], v[32:35]
	v_mfma_f32_16x16x32_bf16 v[20:23], v[196:199], v[164:167], v[20:23]
	v_mfma_f32_16x16x32_bf16 v[16:19], v[204:207], v[164:167], v[16:19]
	v_mfma_f32_16x16x32_bf16 v[4:7], v[196:199], v[172:175], v[4:7]
	v_mfma_f32_16x16x32_bf16 v[0:3], v[204:207], v[172:175], v[0:3]
	s_barrier
	s_setprio 0
	s_add_u32 s22, s22, 0x160000
	s_addc_u32 s23, s23, 0
	s_mov_b32 m0, s34
	ds_read_b128 v[144:147], v215 offset:32768
	ds_read_b128 v[148:151], v215 offset:33792
	ds_read_b128 v[152:155], v215 offset:34816
	ds_read_b128 v[156:159], v215 offset:35840
	ds_read_b128 v[160:163], v215 offset:36864
	ds_read_b128 v[164:167], v215 offset:37888
	ds_read_b128 v[168:171], v215 offset:38912
	ds_read_b128 v[172:175], v215 offset:39936
	global_load_lds_dwordx4 v176, s[22:23]
	s_mov_b32 m0, s35
	s_nop 0
	global_load_lds_dwordx4 v180, s[22:23]
	s_waitcnt lgkmcnt(0)
	s_setprio 1
	s_barrier
	v_mfma_f32_16x16x32_bf16 v[124:127], v[128:131], v[144:147], v[124:127]
	v_mfma_f32_16x16x32_bf16 v[120:123], v[136:139], v[144:147], v[120:123]
	v_mfma_f32_16x16x32_bf16 v[108:111], v[128:131], v[152:155], v[108:111]
	v_mfma_f32_16x16x32_bf16 v[104:107], v[136:139], v[152:155], v[104:107]
	v_mfma_f32_16x16x32_bf16 v[92:95], v[128:131], v[160:163], v[92:95]
	v_mfma_f32_16x16x32_bf16 v[88:91], v[136:139], v[160:163], v[88:91]
	v_mfma_f32_16x16x32_bf16 v[76:79], v[128:131], v[168:171], v[76:79]
	v_mfma_f32_16x16x32_bf16 v[72:75], v[136:139], v[168:171], v[72:75]
	v_mfma_f32_16x16x32_bf16 v[124:127], v[132:135], v[148:151], v[124:127]
	v_mfma_f32_16x16x32_bf16 v[120:123], v[140:143], v[148:151], v[120:123]
	v_mfma_f32_16x16x32_bf16 v[108:111], v[132:135], v[156:159], v[108:111]
	v_mfma_f32_16x16x32_bf16 v[104:107], v[140:143], v[156:159], v[104:107]
	v_mfma_f32_16x16x32_bf16 v[92:95], v[132:135], v[164:167], v[92:95]
	v_mfma_f32_16x16x32_bf16 v[88:91], v[140:143], v[164:167], v[88:91]
	v_mfma_f32_16x16x32_bf16 v[76:79], v[132:135], v[172:175], v[76:79]
	v_mfma_f32_16x16x32_bf16 v[72:75], v[140:143], v[172:175], v[72:75]
	s_barrier
	s_setprio 0
	s_add_i32 s22, 0, 0x1c000
	s_add_i32 s23, s45, s30
	v_add_u32_e32 v204, s22, v212
	s_mov_b32 m0, s23
	ds_read_b128 v[192:195], v204
	ds_read_b128 v[196:199], v204 offset:1024
	ds_read_b128 v[200:203], v204 offset:2048
	ds_read_b128 v[204:207], v204 offset:3072
	global_load_lds_dwordx4 v178, s[98:99]
	s_add_i32 m0, s23, 0x2000
	s_nop 0
	global_load_lds_dwordx4 v182, s[98:99]
	s_waitcnt lgkmcnt(0)
	s_setprio 1
	s_barrier
	v_mfma_f32_16x16x32_bf16 v[116:119], v[192:195], v[144:147], v[116:119]
	v_mfma_f32_16x16x32_bf16 v[112:115], v[200:203], v[144:147], v[112:115]
	v_mfma_f32_16x16x32_bf16 v[100:103], v[192:195], v[152:155], v[100:103]
	v_mfma_f32_16x16x32_bf16 v[96:99], v[200:203], v[152:155], v[96:99]
	v_mfma_f32_16x16x32_bf16 v[84:87], v[192:195], v[160:163], v[84:87]
	v_mfma_f32_16x16x32_bf16 v[80:83], v[200:203], v[160:163], v[80:83]
	v_mfma_f32_16x16x32_bf16 v[68:71], v[192:195], v[168:171], v[68:71]
	v_mfma_f32_16x16x32_bf16 v[64:67], v[200:203], v[168:171], v[64:67]
	v_mfma_f32_16x16x32_bf16 v[116:119], v[196:199], v[148:151], v[116:119]
	v_mfma_f32_16x16x32_bf16 v[112:115], v[204:207], v[148:151], v[112:115]
	v_mfma_f32_16x16x32_bf16 v[100:103], v[196:199], v[156:159], v[100:103]
	v_mfma_f32_16x16x32_bf16 v[96:99], v[204:207], v[156:159], v[96:99]
	v_mfma_f32_16x16x32_bf16 v[84:87], v[196:199], v[164:167], v[84:87]
	v_mfma_f32_16x16x32_bf16 v[80:83], v[204:207], v[164:167], v[80:83]
	v_mfma_f32_16x16x32_bf16 v[68:71], v[196:199], v[172:175], v[68:71]
	v_mfma_f32_16x16x32_bf16 v[64:67], v[204:207], v[172:175], v[64:67]
	s_barrier
	s_setprio 0
	s_mov_b32 m0, s37
	ds_read_b128 v[144:147], v215 offset:49152
	ds_read_b128 v[148:151], v215 offset:50176
	ds_read_b128 v[152:155], v215 offset:51200
	ds_read_b128 v[156:159], v215 offset:52224
	ds_read_b128 v[160:163], v215 offset:53248
	ds_read_b128 v[164:167], v215 offset:54272
	ds_read_b128 v[168:171], v215 offset:55296
	ds_read_b128 v[172:175], v215 offset:56320
	global_load_lds_dwordx4 v176, s[100:101]
	s_mov_b32 m0, s38
	s_nop 0
	global_load_lds_dwordx4 v180, s[100:101]
	s_waitcnt vmcnt(10)
	s_waitcnt lgkmcnt(0)
	s_setprio 1
	s_barrier
	v_mfma_f32_16x16x32_bf16 v[60:63], v[128:131], v[144:147], v[60:63]
	v_mfma_f32_16x16x32_bf16 v[56:59], v[136:139], v[144:147], v[56:59]
	v_mfma_f32_16x16x32_bf16 v[44:47], v[128:131], v[152:155], v[44:47]
	v_mfma_f32_16x16x32_bf16 v[40:43], v[136:139], v[152:155], v[40:43]
	v_mfma_f32_16x16x32_bf16 v[28:31], v[128:131], v[160:163], v[28:31]
	v_mfma_f32_16x16x32_bf16 v[24:27], v[136:139], v[160:163], v[24:27]
	v_mfma_f32_16x16x32_bf16 v[12:15], v[128:131], v[168:171], v[12:15]
	v_mfma_f32_16x16x32_bf16 v[8:11], v[136:139], v[168:171], v[8:11]
	v_mfma_f32_16x16x32_bf16 v[60:63], v[132:135], v[148:151], v[60:63]
	v_mfma_f32_16x16x32_bf16 v[56:59], v[140:143], v[148:151], v[56:59]
	v_mfma_f32_16x16x32_bf16 v[44:47], v[132:135], v[156:159], v[44:47]
	v_mfma_f32_16x16x32_bf16 v[40:43], v[140:143], v[156:159], v[40:43]
	v_mfma_f32_16x16x32_bf16 v[28:31], v[132:135], v[164:167], v[28:31]
	v_mfma_f32_16x16x32_bf16 v[24:27], v[140:143], v[164:167], v[24:27]
	v_mfma_f32_16x16x32_bf16 v[12:15], v[132:135], v[172:175], v[12:15]
	v_mfma_f32_16x16x32_bf16 v[8:11], v[140:143], v[172:175], v[8:11]
	s_barrier
; DI unsigned pack2(float lo, float hi) { f32x2 v = {lo, hi}; bf16v2 r = __builtin_convertvector(v, bf16v2); return __builtin_bit_cast(unsigned, r); }
; #define PG8_STAGE(bufoff, gbase, voff) do { _Pragma("unroll") for (int _i = 0; _i < 2; ++_i) \
;     __builtin_amdgcn_global_load_lds((const unsigned*)((const char*)(gbase) + (voff)[_i]), (LAS unsigned*)(lds + (bufoff) + ldsw + _i * 8192), 16, 0, 0); } while (0)
; #define PG8_WAIT_V(n) asm volatile("s_waitcnt vmcnt(" #n ")" ::: "memory")
; #define PG8_BAR __builtin_amdgcn_s_barrier()
;   DI void operator()(const f32x4 (&acc)[2][2][4][2], const Unit& u, int wr, int wc, int fr, int fq) const {
;     const int row0 = u.pm * BM + wr * 64 + fr, col0 = u.pn * BM + wc * 32 + 8 * fq;
; #pragma unroll
;     for (int ai = 0; ai < 2; ++ai) {
;       f32x4 bv[4][2][2];
; #pragma unroll
;       for (int m = 0; m < 4; ++m)
; #pragma unroll
;         for (int bj = 0; bj < 2; ++bj) {
;           const float* bp = base + (size_t)(row0 + ai * HALF + m * 16) * 2048 + col0 + bj * HALF;
;           bv[m][bj][0] = *(const f32x4*)bp; bv[m][bj][1] = *(const f32x4*)(bp + 4);
;         }
; #pragma unroll
;       for (int m = 0; m < 4; ++m) {
;         const int row = row0 + ai * HALF + m * 16;
;         const size_t off = (size_t)row * 2048 + col0;
;         float ss = 0.f;
; #pragma unroll
;         for (int bj = 0; bj < 2; ++bj) {
;           const f32x4 v0 = acc[ai][bj][m][0] + bv[m][bj][0], v1 = acc[ai][bj][m][1] + bv[m][bj][1];
;           *(f32x4*)(C + off + bj * HALF) = v0; *(f32x4*)(C + off + bj * HALF + 4) = v1;
;           if (xb) {
;             u32x4 w; w.x = pack2(v0[0], v0[1]); w.y = pack2(v0[2], v0[3]); w.z = pack2(v1[0], v1[1]); w.w = pack2(v1[2], v1[3]);
;             *(u32x4*)(xb + off + bj * HALF) = w;
;             ss += v0[0] * v0[0] + v0[1] * v0[1] + v0[2] * v0[2] + v0[3] * v0[3] + v1[0] * v1[0] + v1[1] * v1[1] + v1[2] * v1[2] + v1[3] * v1[3];
;           }
;         }
;         if (xb) {
;           ss += __shfl_xor(ss, 16); ss += __shfl_xor(ss, 32);
;           if (fq == 0) ssq[(size_t)row * 32 + u.pn * 4 + wc] = ss;
;         }
; template <class Epi, class Sched = StaticOrder>
; DI void gemm_phase(LAS unsigned char* lds, const Gemm g, const Sched& S, const Epi& E) {
;     ...
;       PG8_STAGE(PG8_SB(1, 1), b3 + hstep, voffB);
;       PG8_WAIT_V(6); PG8_BAR; PG8_MMA(1, 1, At, B1); PG8_BAR;
	s_setprio 0
	s_add_u32 s20, s20, 0x160080
	s_addc_u32 s21, s21, 0
	s_add_i32 s22, s22, s30
	s_mov_b32 m0, s22
	s_nop 0
	global_load_lds_dwordx4 v178, s[20:21]
	s_add_i32 m0, s22, 0x2000
	s_nop 0
	global_load_lds_dwordx4 v182, s[20:21]
	ds_read_b128 v[128:131], v214
	ds_read_b128 v[132:135], v214 offset:1024
	ds_read_b128 v[136:139], v214 offset:2048
	ds_read_b128 v[140:143], v214 offset:3072
	s_waitcnt vmcnt(6)
	s_add_i32 s44, s44, 2
	s_add_u32 s18, s18, 0x100
	s_addc_u32 s19, s19, 0
	s_add_u32 s42, s42, 0x100
	s_addc_u32 s43, s43, 0
	s_cmpk_gt_u32 s44, 0x55
	s_setprio 1
	s_barrier
	v_mfma_f32_16x16x32_bf16 v[52:55], v[192:195], v[144:147], v[52:55]
	v_mfma_f32_16x16x32_bf16 v[48:51], v[200:203], v[144:147], v[48:51]
	v_mfma_f32_16x16x32_bf16 v[36:39], v[192:195], v[152:155], v[36:39]
	v_mfma_f32_16x16x32_bf16 v[32:35], v[200:203], v[152:155], v[32:35]
	v_mfma_f32_16x16x32_bf16 v[20:23], v[192:195], v[160:163], v[20:23]
	v_mfma_f32_16x16x32_bf16 v[16:19], v[200:203], v[160:163], v[16:19]
	v_mfma_f32_16x16x32_bf16 v[4:7], v[192:195], v[168:171], v[4:7]
	v_mfma_f32_16x16x32_bf16 v[0:3], v[200:203], v[168:171], v[0:3]
	v_mfma_f32_16x16x32_bf16 v[52:55], v[196:199], v[148:151], v[52:55]
	v_mfma_f32_16x16x32_bf16 v[48:51], v[204:207], v[148:151], v[48:51]
	v_mfma_f32_16x16x32_bf16 v[36:39], v[196:199], v[156:159], v[36:39]
	v_mfma_f32_16x16x32_bf16 v[32:35], v[204:207], v[156:159], v[32:35]
	v_mfma_f32_16x16x32_bf16 v[20:23], v[196:199], v[164:167], v[20:23]
	v_mfma_f32_16x16x32_bf16 v[16:19], v[204:207], v[164:167], v[16:19]
	v_mfma_f32_16x16x32_bf16 v[4:7], v[196:199], v[172:175], v[4:7]
	v_mfma_f32_16x16x32_bf16 v[0:3], v[204:207], v[172:175], v[0:3]
	s_barrier
	s_setprio 0
	s_cbranch_scc0 .LBB0_961
	s_waitcnt lgkmcnt(0)
	v_lshl_add_u32 v194, s51, 8, v211
	v_lshl_or_b32 v192, s2, 8, v213
	v_readlane_b32 s52, v243, 3
	v_ashrrev_i32_e32 v193, 31, v192
	v_readlane_b32 s66, v243, 17
	v_readlane_b32 s67, v243, 18
	v_ashrrev_i32_e32 v195, 31, v194
	v_lshlrev_b64 v[128:129], 13, v[194:195]
	v_lshl_add_u64 v[196:197], v[192:193], 2, s[66:67]
	v_lshl_add_u64 v[236:237], v[196:197], 0, v[128:129]
	global_load_dwordx4 v[220:223], v[236:237], off
	global_load_dwordx4 v[224:227], v[236:237], off offset:16
	global_load_dwordx4 v[228:231], v[236:237], off offset:512
	global_load_dwordx4 v[232:235], v[236:237], off offset:528
	v_or_b32_e32 v206, 16, v194
	v_or_b32_e32 v202, 32, v194
	v_or_b32_e32 v198, 48, v194
	v_ashrrev_i32_e32 v207, 31, v206
	v_ashrrev_i32_e32 v203, 31, v202
	v_ashrrev_i32_e32 v199, 31, v198
	v_lshlrev_b64 v[128:129], 13, v[206:207]
	v_lshlrev_b64 v[130:131], 13, v[202:203]
	v_lshlrev_b64 v[132:133], 13, v[198:199]
	v_lshl_add_u64 v[208:209], v[196:197], 0, v[128:129]
	v_lshl_add_u64 v[204:205], v[196:197], 0, v[130:131]
	v_lshl_add_u64 v[200:201], v[196:197], 0, v[132:133]
	global_load_dwordx4 v[168:171], v[208:209], off offset:16
	global_load_dwordx4 v[172:175], v[208:209], off
	global_load_dwordx4 v[160:163], v[208:209], off offset:528
	global_load_dwordx4 v[164:167], v[208:209], off offset:512
	global_load_dwordx4 v[152:155], v[204:205], off offset:16
	global_load_dwordx4 v[156:159], v[204:205], off
	global_load_dwordx4 v[144:147], v[204:205], off offset:528
	global_load_dwordx4 v[148:151], v[204:205], off offset:512
	global_load_dwordx4 v[136:139], v[200:201], off offset:16
	global_load_dwordx4 v[140:143], v[200:201], off
	global_load_dwordx4 v[128:131], v[200:201], off offset:528
	global_load_dwordx4 v[132:135], v[200:201], off offset:512
	v_and_b32_e32 v218, 64, v217
	v_xor_b32_e32 v238, 16, v217
	v_add_u32_e32 v240, 64, v218
	v_xor_b32_e32 v239, 32, v217
	v_cmp_lt_i32_e32 vcc, v238, v240
	v_lshlrev_b64 v[218:219], 11, v[194:195]
	s_lshl_b32 s18, s2, 2
	v_cndmask_b32_e32 v241, v217, v238, vcc
	v_cmp_lt_i32_e32 vcc, v239, v240
	s_ashr_i32 s19, s18, 31
	v_readlane_b32 s53, v243, 4
	v_cndmask_b32_e32 v240, v217, v239, vcc
	v_lshl_add_u64 v[238:239], v[218:219], 0, v[192:193]
	v_lshlrev_b32_e32 v218, 2, v241
	v_lshl_add_u64 v[238:239], v[238:239], 1, s[12:13]
	v_readlane_b32 s54, v243, 5
	v_readlane_b32 s55, v243, 6
	v_readlane_b32 s56, v243, 7
	v_readlane_b32 s57, v243, 8
	v_readlane_b32 s58, v243, 9
	v_readlane_b32 s59, v243, 10
	v_readlane_b32 s60, v243, 11
	v_readlane_b32 s61, v243, 12
	v_readlane_b32 s62, v243, 13
	v_readlane_b32 s63, v243, 14
	v_readlane_b32 s64, v243, 15
	v_readlane_b32 s65, v243, 16
	s_waitcnt vmcnt(0)
	v_pk_add_f32 v[126:127], v[126:127], v[222:223]
	v_pk_add_f32 v[124:125], v[124:125], v[220:221]
	v_pk_add_f32 v[116:117], v[116:117], v[228:229]
	v_pk_add_f32 v[122:123], v[122:123], v[226:227]
	v_pk_add_f32 v[120:121], v[120:121], v[224:225]
	v_pk_add_f32 v[220:221], v[112:113], v[232:233]
	global_store_dwordx4 v[236:237], v[124:127], off
	global_store_dwordx4 v[236:237], v[120:123], off offset:16
	v_cvt_pk_bf16_f32 v112, v124, v125
	v_mul_f32_e32 v125, v125, v125
	v_mul_f32_e32 v219, v117, v117
	v_pk_add_f32 v[118:119], v[118:119], v[230:231]
	v_fmac_f32_e32 v125, v124, v124
	v_fmac_f32_e32 v219, v116, v116
	v_fmac_f32_e32 v125, v126, v126
	v_fmac_f32_e32 v219, v118, v118
	v_fmac_f32_e32 v125, v127, v127
	v_fmac_f32_e32 v219, v119, v119
	v_fmac_f32_e32 v125, v120, v120
	v_fmac_f32_e32 v219, v220, v220
	v_pk_add_f32 v[222:223], v[114:115], v[234:235]
	v_fmac_f32_e32 v125, v121, v121
	v_fmac_f32_e32 v219, v221, v221
	v_fmac_f32_e32 v125, v122, v122
	v_fmac_f32_e32 v219, v222, v222
	v_fmac_f32_e32 v125, v123, v123
	v_fmac_f32_e32 v219, v223, v223
	v_cvt_pk_bf16_f32 v114, v120, v121
	v_add_f32_e32 v121, v125, v219
	v_cvt_pk_bf16_f32 v115, v122, v123
	ds_bpermute_b32 v122, v218, v121
	v_cvt_pk_bf16_f32 v113, v126, v127
	global_store_dwordx4 v[238:239], v[112:115], off
	global_store_dwordx4 v[236:237], v[116:119], off offset:512
	global_store_dwordx4 v[236:237], v[220:223], off offset:528
	v_lshlrev_b32_e32 v126, 2, v240
	v_cvt_pk_bf16_f32 v120, v116, v117
	s_waitcnt lgkmcnt(0)
	v_add_f32_e32 v112, v121, v122
	ds_bpermute_b32 v113, v126, v112
	v_cvt_pk_bf16_f32 v121, v118, v119
	v_cvt_pk_bf16_f32 v122, v220, v221
	v_cvt_pk_bf16_f32 v123, v222, v223
	global_store_dwordx4 v[238:239], v[120:123], off offset:256
	s_and_saveexec_b64 s[20:21], s[0:1]
	s_cbranch_execz .LBB0_964
	s_waitcnt lgkmcnt(0)
	v_add_f32_e32 v114, v112, v113
	v_lshlrev_b64 v[112:113], 7, v[194:195]
	v_lshl_add_u64 v[112:113], s[14:15], 0, v[112:113]
	v_lshl_add_u64 v[112:113], s[18:19], 2, v[112:113]
	s_lshl_b32 s2, s36, 2
	v_lshl_add_u64 v[112:113], v[112:113], 0, s[2:3]
	global_store_dword v[112:113], v114, off

; #define PG8_STAGE(bufoff, gbase, voff) do { _Pragma("unroll") for (int _i = 0; _i < 2; ++_i) \
;     __builtin_amdgcn_global_load_lds((const unsigned*)((const char*)(gbase) + (voff)[_i]), (LAS unsigned*)(lds + (bufoff) + ldsw + _i * 8192), 16, 0, 0); } while (0)
; #define PG8_LDA(dst, b, h) do { _Pragma("unroll") for (int m = 0; m < 4; ++m) _Pragma("unroll") for (int k = 0; k < 2; ++k) dst[m][k] = *(const LAS bf16x8*)(lds + PG8_SA(b, h) + aoff + m * 2048 + k * 1024); } while (0)
; #define PG8_LDB(dst, b, h) do { _Pragma("unroll") for (int n = 0; n < 2; ++n) _Pragma("unroll") for (int k = 0; k < 2; ++k) dst[n][k] = *(const LAS bf16x8*)(lds + PG8_SB(b, h) + boff + n * 2048 + k * 1024); } while (0)
; #define PG8_MMA(ai, bj, At, Bt) do { __builtin_amdgcn_s_setprio(1); _Pragma("unroll") for (int m = 0; m < 4; ++m) _Pragma("unroll") for (int n = 0; n < 2; ++n) _Pragma("unroll") for (int k = 0; k < 2; ++k) \
;     acc[ai][bj][m][n] = __builtin_amdgcn_mfma_f32_16x16x32_bf16(Bt[n][k], At[m][k], acc[ai][bj][m][n], 0, 0, 0); __builtin_amdgcn_s_setprio(0); } while (0)
; #define PG8_WAIT_V(n) asm volatile("s_waitcnt vmcnt(" #n ")" ::: "memory")
; #define PG8_WAIT_L(n) asm volatile("s_waitcnt lgkmcnt(" #n ")" ::: "memory")
; #define PG8_BAR __builtin_amdgcn_s_barrier()
; #define PG8_SCHED __builtin_amdgcn_sched_barrier(0)
; template <class Epi, class Sched = StaticOrder>
; DI void gemm_phase(LAS unsigned char* lds, const Gemm g, const Sched& S, const Epi& E) {
;     ...
;       PG8_LDB(B0, 0, 0); PG8_SCHED; PG8_LDA(At, 0, 0); PG8_STAGE(PG8_SA(1, 1), a1 + hstep, voffA);
;       PG8_WAIT_L(8); PG8_BAR; PG8_WAIT_L(0); PG8_MMA(0, 0, At, B0); PG8_BAR; PG8_SCHED;
;       PG8_LDB(B1, 0, 1); PG8_STAGE(PG8_SB(0, 0), b2, voffB);
;       PG8_BAR; PG8_WAIT_L(0); PG8_MMA(0, 1, At, B1); PG8_BAR;
;       PG8_LDA(At, 0, 1); PG8_STAGE(PG8_SA(0, 0), a2, voffA);
;       PG8_BAR; PG8_WAIT_L(0); PG8_MMA(1, 0, At, B0); PG8_BAR; PG8_SCHED;
;       PG8_STAGE(PG8_SB(0, 1), b2 + hstep, voffB);
;       PG8_WAIT_V(6); PG8_BAR; PG8_MMA(1, 1, At, B1); PG8_BAR;
;       PG8_LDB(B0, 1, 0); PG8_SCHED; PG8_LDA(At, 1, 0); PG8_STAGE(PG8_SA(0, 1), a2 + hstep, voffA);
.LBB0_1052:
	s_add_u32 s12, s10, 0xfff80080
	s_addc_u32 s13, s11, -1
	s_cmp_eq_u32 s52, 28
	s_cselect_b32 s65, s41, s13
	s_cselect_b32 s64, s42, s12
	s_cselect_b32 s13, s43, s49
	s_cselect_b32 s12, s44, s45
	s_add_i32 m0, s61, 0xc000
	ds_read_b128 v[144:147], v204
	ds_read_b128 v[148:151], v204 offset:1024
	ds_read_b128 v[152:155], v204 offset:2048
	ds_read_b128 v[156:159], v204 offset:3072
	ds_read_b128 v[178:181], v204 offset:4096
	ds_read_b128 v[182:185], v204 offset:5120
	ds_read_b128 v[186:189], v204 offset:6144
	ds_read_b128 v[190:193], v204 offset:7168
	global_load_lds_dwordx4 v172, s[10:11]
	s_add_i32 m0, s61, 0xe000
	s_nop 0
	global_load_lds_dwordx4 v174, s[10:11]
	s_waitcnt lgkmcnt(0)
	s_setprio 1
	s_barrier
	v_mfma_f32_16x16x32_bf16 v[124:127], v[128:131], v[144:147], v[124:127]
	v_mfma_f32_16x16x32_bf16 v[120:123], v[136:139], v[144:147], v[120:123]
	v_mfma_f32_16x16x32_bf16 v[116:119], v[128:131], v[152:155], v[116:119]
	v_mfma_f32_16x16x32_bf16 v[104:107], v[136:139], v[152:155], v[104:107]
	v_mfma_f32_16x16x32_bf16 v[92:95], v[128:131], v[178:181], v[92:95]
	v_mfma_f32_16x16x32_bf16 v[88:91], v[136:139], v[178:181], v[88:91]
	v_mfma_f32_16x16x32_bf16 v[84:87], v[128:131], v[186:189], v[84:87]
	v_mfma_f32_16x16x32_bf16 v[72:75], v[136:139], v[186:189], v[72:75]
	v_mfma_f32_16x16x32_bf16 v[124:127], v[132:135], v[148:151], v[124:127]
	v_mfma_f32_16x16x32_bf16 v[120:123], v[140:143], v[148:151], v[120:123]
	v_mfma_f32_16x16x32_bf16 v[116:119], v[132:135], v[156:159], v[116:119]
	v_mfma_f32_16x16x32_bf16 v[104:107], v[140:143], v[156:159], v[104:107]
	v_mfma_f32_16x16x32_bf16 v[92:95], v[132:135], v[182:185], v[92:95]
	v_mfma_f32_16x16x32_bf16 v[88:91], v[140:143], v[182:185], v[88:91]
	v_mfma_f32_16x16x32_bf16 v[84:87], v[132:135], v[190:193], v[84:87]
	v_mfma_f32_16x16x32_bf16 v[72:75], v[140:143], v[190:193], v[72:75]
	s_barrier
	s_setprio 0
	s_add_i32 s53, s80, s70
	s_add_u32 s98, s12, 0x80
	s_addc_u32 s99, s13, 0
	s_mov_b32 m0, s53
	ds_read_b128 v[194:197], v205
	ds_read_b128 v[212:215], v205 offset:1024
	ds_read_b128 v[216:219], v205 offset:2048
	ds_read_b128 v[220:223], v205 offset:3072
	global_load_lds_dwordx4 v162, s[12:13]
	s_add_i32 m0, s53, 0x2000
	s_nop 0
	global_load_lds_dwordx4 v166, s[12:13]
	s_waitcnt lgkmcnt(0)
	s_setprio 1
	s_barrier
	v_mfma_f32_16x16x32_bf16 v[112:115], v[194:197], v[144:147], v[112:115]
	v_mfma_f32_16x16x32_bf16 v[108:111], v[216:219], v[144:147], v[108:111]
	v_mfma_f32_16x16x32_bf16 v[100:103], v[194:197], v[152:155], v[100:103]
	v_mfma_f32_16x16x32_bf16 v[96:99], v[216:219], v[152:155], v[96:99]
	v_mfma_f32_16x16x32_bf16 v[80:83], v[194:197], v[178:181], v[80:83]
	v_mfma_f32_16x16x32_bf16 v[76:79], v[216:219], v[178:181], v[76:79]
	v_mfma_f32_16x16x32_bf16 v[68:71], v[194:197], v[186:189], v[68:71]
	v_mfma_f32_16x16x32_bf16 v[64:67], v[216:219], v[186:189], v[64:67]
	v_mfma_f32_16x16x32_bf16 v[112:115], v[212:215], v[148:151], v[112:115]
	v_mfma_f32_16x16x32_bf16 v[108:111], v[220:223], v[148:151], v[108:111]
	v_mfma_f32_16x16x32_bf16 v[100:103], v[212:215], v[156:159], v[100:103]
	v_mfma_f32_16x16x32_bf16 v[96:99], v[220:223], v[156:159], v[96:99]
	v_mfma_f32_16x16x32_bf16 v[80:83], v[212:215], v[182:185], v[80:83]
	v_mfma_f32_16x16x32_bf16 v[76:79], v[220:223], v[182:185], v[76:79]
	v_mfma_f32_16x16x32_bf16 v[68:71], v[212:215], v[190:193], v[68:71]
	v_mfma_f32_16x16x32_bf16 v[64:67], v[220:223], v[190:193], v[64:67]
	s_barrier
	s_setprio 0
	s_mov_b32 m0, s61
	s_add_u32 s100, s64, 0x80
	s_addc_u32 s101, s65, 0
	ds_read_b128 v[144:147], v204 offset:16384
	ds_read_b128 v[148:151], v204 offset:17408
	ds_read_b128 v[152:155], v204 offset:18432
	ds_read_b128 v[156:159], v204 offset:19456
	ds_read_b128 v[178:181], v204 offset:20480
	ds_read_b128 v[182:185], v204 offset:21504
	ds_read_b128 v[186:189], v204 offset:22528
	ds_read_b128 v[190:193], v204 offset:23552
	global_load_lds_dwordx4 v160, s[64:65]
	s_mov_b32 m0, s63
	s_nop 0
	global_load_lds_dwordx4 v164, s[64:65]
	s_waitcnt vmcnt(10)
	s_waitcnt lgkmcnt(0)
	s_setprio 1
	s_barrier
	v_mfma_f32_16x16x32_bf16 v[60:63], v[128:131], v[144:147], v[60:63]
	v_mfma_f32_16x16x32_bf16 v[56:59], v[136:139], v[144:147], v[56:59]
	v_mfma_f32_16x16x32_bf16 v[48:51], v[128:131], v[152:155], v[48:51]
	v_mfma_f32_16x16x32_bf16 v[40:43], v[136:139], v[152:155], v[40:43]
	v_mfma_f32_16x16x32_bf16 v[28:31], v[128:131], v[178:181], v[28:31]
	v_mfma_f32_16x16x32_bf16 v[24:27], v[136:139], v[178:181], v[24:27]
	v_mfma_f32_16x16x32_bf16 v[12:15], v[128:131], v[186:189], v[12:15]
	v_mfma_f32_16x16x32_bf16 v[8:11], v[136:139], v[186:189], v[8:11]
	v_mfma_f32_16x16x32_bf16 v[60:63], v[132:135], v[148:151], v[60:63]
	v_mfma_f32_16x16x32_bf16 v[56:59], v[140:143], v[148:151], v[56:59]
	v_mfma_f32_16x16x32_bf16 v[48:51], v[132:135], v[156:159], v[48:51]
	v_mfma_f32_16x16x32_bf16 v[40:43], v[140:143], v[156:159], v[40:43]
	v_mfma_f32_16x16x32_bf16 v[28:31], v[132:135], v[182:185], v[28:31]
	v_mfma_f32_16x16x32_bf16 v[24:27], v[140:143], v[182:185], v[24:27]
	v_mfma_f32_16x16x32_bf16 v[12:15], v[132:135], v[190:193], v[12:15]
	v_mfma_f32_16x16x32_bf16 v[8:11], v[140:143], v[190:193], v[8:11]
	s_barrier
	s_setprio 0
	s_add_u32 s54, s12, 0x80000
	s_addc_u32 s55, s13, 0
	s_add_i32 s53, s81, s70
	s_mov_b32 m0, s53
	s_nop 0
	global_load_lds_dwordx4 v162, s[54:55]
	s_add_i32 m0, s53, 0x2000
	s_nop 0
	global_load_lds_dwordx4 v166, s[54:55]
	s_add_i32 s53, 0, 0x18000
	v_add_u32_e32 v140, s53, v199
	ds_read_b128 v[128:131], v140
	ds_read_b128 v[132:135], v140 offset:1024
	ds_read_b128 v[136:139], v140 offset:2048
	ds_read_b128 v[140:143], v140 offset:3072
	s_waitcnt vmcnt(6)
	s_setprio 1
	s_barrier
; #define PG8_STAGE(bufoff, gbase, voff) do { _Pragma("unroll") for (int _i = 0; _i < 2; ++_i) \
;     __builtin_amdgcn_global_load_lds((const unsigned*)((const char*)(gbase) + (voff)[_i]), (LAS unsigned*)(lds + (bufoff) + ldsw + _i * 8192), 16, 0, 0); } while (0)
; #define PG8_LDA(dst, b, h) do { _Pragma("unroll") for (int m = 0; m < 4; ++m) _Pragma("unroll") for (int k = 0; k < 2; ++k) dst[m][k] = *(const LAS bf16x8*)(lds + PG8_SA(b, h) + aoff + m * 2048 + k * 1024); } while (0)
; #define PG8_LDB(dst, b, h) do { _Pragma("unroll") for (int n = 0; n < 2; ++n) _Pragma("unroll") for (int k = 0; k < 2; ++k) dst[n][k] = *(const LAS bf16x8*)(lds + PG8_SB(b, h) + boff + n * 2048 + k * 1024); } while (0)
; #define PG8_MMA(ai, bj, At, Bt) do { __builtin_amdgcn_s_setprio(1); _Pragma("unroll") for (int m = 0; m < 4; ++m) _Pragma("unroll") for (int n = 0; n < 2; ++n) _Pragma("unroll") for (int k = 0; k < 2; ++k) \
;     acc[ai][bj][m][n] = __builtin_amdgcn_mfma_f32_16x16x32_bf16(Bt[n][k], At[m][k], acc[ai][bj][m][n], 0, 0, 0); __builtin_amdgcn_s_setprio(0); } while (0)
; #define PG8_WAIT_V(n) asm volatile("s_waitcnt vmcnt(" #n ")" ::: "memory")
; #define PG8_WAIT_L(n) asm volatile("s_waitcnt lgkmcnt(" #n ")" ::: "memory")
; #define PG8_BAR __builtin_amdgcn_s_barrier()
; #define PG8_SCHED __builtin_amdgcn_sched_barrier(0)
; template <class Epi, class Sched = StaticOrder>
; DI void gemm_phase(LAS unsigned char* lds, const Gemm g, const Sched& S, const Epi& E) {
;     ...
;       PG8_WAIT_V(6); PG8_BAR; PG8_MMA(1, 1, At, B1); PG8_BAR;
;       PG8_LDB(B0, 1, 0); PG8_SCHED; PG8_LDA(At, 1, 0); PG8_STAGE(PG8_SA(0, 1), a2 + hstep, voffA);
;       PG8_WAIT_L(8); PG8_BAR; PG8_WAIT_L(0); PG8_MMA(0, 0, At, B0); PG8_BAR; PG8_SCHED;
;       PG8_LDB(B1, 1, 1); PG8_STAGE(PG8_SB(1, 0), b3, voffB);
;       PG8_BAR; PG8_WAIT_L(0); PG8_MMA(0, 1, At, B1); PG8_BAR;
;       PG8_LDA(At, 1, 1); PG8_STAGE(PG8_SA(1, 0), a3, voffA);
;       PG8_BAR; PG8_WAIT_L(0); PG8_MMA(1, 0, At, B0); PG8_BAR; PG8_SCHED;
	v_mfma_f32_16x16x32_bf16 v[52:55], v[194:197], v[144:147], v[52:55]
	v_mfma_f32_16x16x32_bf16 v[44:47], v[216:219], v[144:147], v[44:47]
	v_mfma_f32_16x16x32_bf16 v[36:39], v[194:197], v[152:155], v[36:39]
	v_mfma_f32_16x16x32_bf16 v[32:35], v[216:219], v[152:155], v[32:35]
	v_mfma_f32_16x16x32_bf16 v[20:23], v[194:197], v[178:181], v[20:23]
	v_mfma_f32_16x16x32_bf16 v[16:19], v[216:219], v[178:181], v[16:19]
	v_mfma_f32_16x16x32_bf16 v[4:7], v[194:197], v[186:189], v[4:7]
	v_mfma_f32_16x16x32_bf16 v[0:3], v[216:219], v[186:189], v[0:3]
	v_mfma_f32_16x16x32_bf16 v[52:55], v[212:215], v[148:151], v[52:55]
	v_mfma_f32_16x16x32_bf16 v[44:47], v[220:223], v[148:151], v[44:47]
	v_mfma_f32_16x16x32_bf16 v[36:39], v[212:215], v[156:159], v[36:39]
	v_mfma_f32_16x16x32_bf16 v[32:35], v[220:223], v[156:159], v[32:35]
	v_mfma_f32_16x16x32_bf16 v[20:23], v[212:215], v[182:185], v[20:23]
	v_mfma_f32_16x16x32_bf16 v[16:19], v[220:223], v[182:185], v[16:19]
	v_mfma_f32_16x16x32_bf16 v[4:7], v[212:215], v[190:193], v[4:7]
	v_mfma_f32_16x16x32_bf16 v[0:3], v[220:223], v[190:193], v[0:3]
	s_barrier
	s_setprio 0
	s_add_u32 s54, s64, 0x80000
	s_addc_u32 s55, s65, 0
	s_mov_b32 m0, s71
	ds_read_b128 v[144:147], v204 offset:32768
	ds_read_b128 v[148:151], v204 offset:33792
	ds_read_b128 v[152:155], v204 offset:34816
	ds_read_b128 v[156:159], v204 offset:35840
	ds_read_b128 v[178:181], v204 offset:36864
	ds_read_b128 v[182:185], v204 offset:37888
	ds_read_b128 v[186:189], v204 offset:38912
	ds_read_b128 v[190:193], v204 offset:39936
	global_load_lds_dwordx4 v160, s[54:55]
	s_mov_b32 m0, s72
	s_nop 0
	global_load_lds_dwordx4 v164, s[54:55]
	s_waitcnt lgkmcnt(0)
	s_setprio 1
	s_barrier
	v_mfma_f32_16x16x32_bf16 v[124:127], v[128:131], v[144:147], v[124:127]
	v_mfma_f32_16x16x32_bf16 v[120:123], v[136:139], v[144:147], v[120:123]
	v_mfma_f32_16x16x32_bf16 v[116:119], v[128:131], v[152:155], v[116:119]
	v_mfma_f32_16x16x32_bf16 v[104:107], v[136:139], v[152:155], v[104:107]
	v_mfma_f32_16x16x32_bf16 v[92:95], v[128:131], v[178:181], v[92:95]
	v_mfma_f32_16x16x32_bf16 v[88:91], v[136:139], v[178:181], v[88:91]
	v_mfma_f32_16x16x32_bf16 v[84:87], v[128:131], v[186:189], v[84:87]
	v_mfma_f32_16x16x32_bf16 v[72:75], v[136:139], v[186:189], v[72:75]
	v_mfma_f32_16x16x32_bf16 v[124:127], v[132:135], v[148:151], v[124:127]
	v_mfma_f32_16x16x32_bf16 v[120:123], v[140:143], v[148:151], v[120:123]
	v_mfma_f32_16x16x32_bf16 v[116:119], v[132:135], v[156:159], v[116:119]
	v_mfma_f32_16x16x32_bf16 v[104:107], v[140:143], v[156:159], v[104:107]
	v_mfma_f32_16x16x32_bf16 v[92:95], v[132:135], v[182:185], v[92:95]
	v_mfma_f32_16x16x32_bf16 v[88:91], v[140:143], v[182:185], v[88:91]
	v_mfma_f32_16x16x32_bf16 v[84:87], v[132:135], v[190:193], v[84:87]
	v_mfma_f32_16x16x32_bf16 v[72:75], v[140:143], v[190:193], v[72:75]
	s_barrier
	s_setprio 0
	s_add_i32 s54, 0, 0x1c000
	s_add_i32 s53, s53, s70
	v_add_u32_e32 v168, s54, v199
	s_mov_b32 m0, s53
	ds_read_b128 v[194:197], v168
	ds_read_b128 v[212:215], v168 offset:1024
	ds_read_b128 v[216:219], v168 offset:2048
	ds_read_b128 v[220:223], v168 offset:3072
	global_load_lds_dwordx4 v162, s[98:99]
	s_add_i32 m0, s53, 0x2000
	s_nop 0
	global_load_lds_dwordx4 v166, s[98:99]
	s_waitcnt lgkmcnt(0)
	s_setprio 1
	s_barrier
	v_mfma_f32_16x16x32_bf16 v[112:115], v[194:197], v[144:147], v[112:115]
	v_mfma_f32_16x16x32_bf16 v[108:111], v[216:219], v[144:147], v[108:111]
	v_mfma_f32_16x16x32_bf16 v[100:103], v[194:197], v[152:155], v[100:103]
	v_mfma_f32_16x16x32_bf16 v[96:99], v[216:219], v[152:155], v[96:99]
	v_mfma_f32_16x16x32_bf16 v[80:83], v[194:197], v[178:181], v[80:83]
	v_mfma_f32_16x16x32_bf16 v[76:79], v[216:219], v[178:181], v[76:79]
	v_mfma_f32_16x16x32_bf16 v[68:71], v[194:197], v[186:189], v[68:71]
	v_mfma_f32_16x16x32_bf16 v[64:67], v[216:219], v[186:189], v[64:67]
	v_mfma_f32_16x16x32_bf16 v[112:115], v[212:215], v[148:151], v[112:115]
	v_mfma_f32_16x16x32_bf16 v[108:111], v[220:223], v[148:151], v[108:111]
	v_mfma_f32_16x16x32_bf16 v[100:103], v[212:215], v[156:159], v[100:103]
	v_mfma_f32_16x16x32_bf16 v[96:99], v[220:223], v[156:159], v[96:99]
	v_mfma_f32_16x16x32_bf16 v[80:83], v[212:215], v[182:185], v[80:83]
	v_mfma_f32_16x16x32_bf16 v[76:79], v[220:223], v[182:185], v[76:79]
	v_mfma_f32_16x16x32_bf16 v[68:71], v[212:215], v[190:193], v[68:71]
	v_mfma_f32_16x16x32_bf16 v[64:67], v[220:223], v[190:193], v[64:67]
	s_barrier
	s_setprio 0
	s_mov_b32 m0, s76
	ds_read_b128 v[144:147], v204 offset:49152
	ds_read_b128 v[148:151], v204 offset:50176
	ds_read_b128 v[152:155], v204 offset:51200
	ds_read_b128 v[156:159], v204 offset:52224
	ds_read_b128 v[178:181], v204 offset:53248
	ds_read_b128 v[182:185], v204 offset:54272
	ds_read_b128 v[186:189], v204 offset:55296
	ds_read_b128 v[190:193], v204 offset:56320
	global_load_lds_dwordx4 v160, s[100:101]
	s_mov_b32 m0, s77
	s_nop 0
	global_load_lds_dwordx4 v164, s[100:101]
	s_waitcnt vmcnt(10)
	s_waitcnt lgkmcnt(0)
	s_setprio 1
	s_barrier
	v_mfma_f32_16x16x32_bf16 v[60:63], v[128:131], v[144:147], v[60:63]
	v_mfma_f32_16x16x32_bf16 v[56:59], v[136:139], v[144:147], v[56:59]
	v_mfma_f32_16x16x32_bf16 v[48:51], v[128:131], v[152:155], v[48:51]
	v_mfma_f32_16x16x32_bf16 v[40:43], v[136:139], v[152:155], v[40:43]
	v_mfma_f32_16x16x32_bf16 v[28:31], v[128:131], v[178:181], v[28:31]
	v_mfma_f32_16x16x32_bf16 v[24:27], v[136:139], v[178:181], v[24:27]
	v_mfma_f32_16x16x32_bf16 v[12:15], v[128:131], v[186:189], v[12:15]
	v_mfma_f32_16x16x32_bf16 v[8:11], v[136:139], v[186:189], v[8:11]
	v_mfma_f32_16x16x32_bf16 v[60:63], v[132:135], v[148:151], v[60:63]
	v_mfma_f32_16x16x32_bf16 v[56:59], v[140:143], v[148:151], v[56:59]
	v_mfma_f32_16x16x32_bf16 v[48:51], v[132:135], v[156:159], v[48:51]
	v_mfma_f32_16x16x32_bf16 v[40:43], v[140:143], v[156:159], v[40:43]
	v_mfma_f32_16x16x32_bf16 v[28:31], v[132:135], v[182:185], v[28:31]
	v_mfma_f32_16x16x32_bf16 v[24:27], v[140:143], v[182:185], v[24:27]
	v_mfma_f32_16x16x32_bf16 v[12:15], v[132:135], v[190:193], v[12:15]
	v_mfma_f32_16x16x32_bf16 v[8:11], v[140:143], v[190:193], v[8:11]
	s_barrier
; #define PG8_STAGE(bufoff, gbase, voff) do { _Pragma("unroll") for (int _i = 0; _i < 2; ++_i) \
;     __builtin_amdgcn_global_load_lds((const unsigned*)((const char*)(gbase) + (voff)[_i]), (LAS unsigned*)(lds + (bufoff) + ldsw + _i * 8192), 16, 0, 0); } while (0)
; #define PG8_MMA(ai, bj, At, Bt) do { __builtin_amdgcn_s_setprio(1); _Pragma("unroll") for (int m = 0; m < 4; ++m) _Pragma("unroll") for (int n = 0; n < 2; ++n) _Pragma("unroll") for (int k = 0; k < 2; ++k) \
;     acc[ai][bj][m][n] = __builtin_amdgcn_mfma_f32_16x16x32_bf16(Bt[n][k], At[m][k], acc[ai][bj][m][n], 0, 0, 0); __builtin_amdgcn_s_setprio(0); } while (0)
; #define PG8_WAIT_V(n) asm volatile("s_waitcnt vmcnt(" #n ")" ::: "memory")
; #define PG8_BAR __builtin_amdgcn_s_barrier()
; DI float row_rstd(const float* ssq, int row, int fq) {
;   const f32x4 a = *(const f32x4*)(ssq + (size_t)row * 32 + fq * 8), b = *(const f32x4*)(ssq + (size_t)row * 32 + fq * 8 + 4);
;   float sm = ((a[0] + a[1]) + (a[2] + a[3])) + ((b[0] + b[1]) + (b[2] + b[3]));
;   sm += __shfl_xor(sm, 16); sm += __shfl_xor(sm, 32);
;   return rsqrtf(sm * (1.0f / 2048.f) + 1e-6f);
;   DI void operator()(const f32x4 (&acc)[2][2][4][2], const Unit& u, int wr, int wc, int fr, int fq) const {
;     ...
;     const int col = u.pn * 128 + wc * 32 + 8 * fq;
;     float w0[8], w1[8], w2[8];
; #pragma unroll
;     for (int e = 0; e < 8; ++e) { w0[e] = cw[col + e]; w1[e] = cw[2048 + col + e]; w2[e] = cw[4096 + col + e]; }
; #pragma unroll
;     for (int ai = 0; ai < 2; ++ai) {
;       const int row0 = u.pm * BM + ai * HALF + wr * 64, span = row0 >> 6;
;       float rsv[4];
; #pragma unroll
;       for (int m = 0; m < 4; ++m) rsv[m] = row_rstd(ssq, row0 + 16 * m + fr, fq);
; template <class Epi, class Sched = StaticOrder>
; DI void gemm_phase(LAS unsigned char* lds, const Gemm g, const Sched& S, const Epi& E) {
;     ...
;       PG8_STAGE(PG8_SB(1, 1), b3 + hstep, voffB);
;       PG8_WAIT_V(6); PG8_BAR; PG8_MMA(1, 1, At, B1); PG8_BAR;
	s_setprio 0
	s_add_u32 s12, s12, 0x80080
	s_addc_u32 s13, s13, 0
	s_add_i32 s53, s54, s70
	s_mov_b32 m0, s53
	s_nop 0
	global_load_lds_dwordx4 v162, s[12:13]
	s_add_i32 m0, s53, 0x2000
	s_nop 0
	global_load_lds_dwordx4 v166, s[12:13]
	ds_read_b128 v[128:131], v203
	ds_read_b128 v[132:135], v203 offset:1024
	ds_read_b128 v[136:139], v203 offset:2048
	ds_read_b128 v[140:143], v203 offset:3072
	s_waitcnt vmcnt(6)
	s_add_i32 s52, s52, 2
	s_add_u32 s10, s10, 0x100
	s_addc_u32 s11, s11, 0
	s_add_u32 s45, s45, 0x100
	s_addc_u32 s49, s49, 0
	s_cmp_gt_u32 s52, 29
	s_setprio 1
	s_barrier
	v_mfma_f32_16x16x32_bf16 v[52:55], v[194:197], v[144:147], v[52:55]
	v_mfma_f32_16x16x32_bf16 v[44:47], v[216:219], v[144:147], v[44:47]
	v_mfma_f32_16x16x32_bf16 v[36:39], v[194:197], v[152:155], v[36:39]
	v_mfma_f32_16x16x32_bf16 v[32:35], v[216:219], v[152:155], v[32:35]
	v_mfma_f32_16x16x32_bf16 v[20:23], v[194:197], v[178:181], v[20:23]
	v_mfma_f32_16x16x32_bf16 v[16:19], v[216:219], v[178:181], v[16:19]
	v_mfma_f32_16x16x32_bf16 v[4:7], v[194:197], v[186:189], v[4:7]
	v_mfma_f32_16x16x32_bf16 v[0:3], v[216:219], v[186:189], v[0:3]
	v_mfma_f32_16x16x32_bf16 v[52:55], v[212:215], v[148:151], v[52:55]
	v_mfma_f32_16x16x32_bf16 v[44:47], v[220:223], v[148:151], v[44:47]
	v_mfma_f32_16x16x32_bf16 v[36:39], v[212:215], v[156:159], v[36:39]
	v_mfma_f32_16x16x32_bf16 v[32:35], v[220:223], v[156:159], v[32:35]
	v_mfma_f32_16x16x32_bf16 v[20:23], v[212:215], v[182:185], v[20:23]
	v_mfma_f32_16x16x32_bf16 v[16:19], v[220:223], v[182:185], v[16:19]
	v_mfma_f32_16x16x32_bf16 v[4:7], v[212:215], v[190:193], v[4:7]
	v_mfma_f32_16x16x32_bf16 v[0:3], v[220:223], v[190:193], v[0:3]
	s_barrier
	s_setprio 0
	s_cbranch_scc0 .LBB0_1052
	s_waitcnt lgkmcnt(0)
	s_cmp_lt_i32 s62, 16
	s_mov_b64 s[10:11], -1
	s_cbranch_scc0 .LBB0_1067
	s_lshl_b32 s41, s60, 8
	s_add_i32 s41, s41, s75
	v_or_b32_e32 v186, s41, v177
	v_ashrrev_i32_e32 v187, 31, v186
	v_lshlrev_b64 v[128:129], 7, v[186:187]
	v_or_b32_e32 v180, 16, v186
	v_lshl_add_u64 v[128:129], v[170:171], 0, v[128:129]
	v_ashrrev_i32_e32 v181, 31, v180
	global_load_dwordx4 v[152:155], v[128:129], off
	global_load_dwordx4 v[156:159], v[128:129], off offset:16
	v_lshlrev_b64 v[128:129], 7, v[180:181]
	v_lshl_add_u64 v[128:129], v[170:171], 0, v[128:129]
	global_load_dwordx4 v[188:191], v[128:129], off
	global_load_dwordx4 v[192:195], v[128:129], off offset:16
	v_or_b32_e32 v184, 32, v186
	v_ashrrev_i32_e32 v185, 31, v184
	v_lshlrev_b64 v[128:129], 7, v[184:185]
	v_or_b32_e32 v182, 48, v186
	v_lshl_add_u64 v[128:129], v[170:171], 0, v[128:129]
	v_ashrrev_i32_e32 v183, 31, v182
	global_load_dwordx4 v[212:215], v[128:129], off
	global_load_dwordx4 v[216:219], v[128:129], off offset:16
	v_lshlrev_b64 v[128:129], 7, v[182:183]
	v_lshl_add_u64 v[128:129], v[170:171], 0, v[128:129]
	global_load_dwordx4 v[220:223], v[128:129], off
	global_load_dwordx4 v[224:227], v[128:129], off offset:16
	v_and_b32_e32 v129, 64, v206
	v_lshl_or_b32 v178, s62, 7, v200
	v_xor_b32_e32 v128, 16, v206
	v_add_u32_e32 v129, 64, v129
	v_readlane_b32 s44, v243, 3
	v_xor_b32_e32 v130, 32, v206
	v_ashrrev_i32_e32 v179, 31, v178
	v_readlane_b32 s45, v243, 4
	v_cmp_lt_i32_e32 vcc, v128, v129
	s_movk_i32 s10, 0x2000
	v_lshl_add_u64 v[144:145], v[178:179], 2, s[44:45]
	v_cndmask_b32_e32 v134, v206, v128, vcc
	v_cmp_lt_i32_e32 vcc, v130, v129
	v_lshl_add_u64 v[132:133], v[144:145], 0, s[26:27]
	v_lshl_add_u64 v[136:137], v[144:145], 0, s[28:29]
	v_cndmask_b32_e32 v135, v206, v130, vcc
	v_add_co_u32_e32 v146, vcc, s10, v144
	global_load_dwordx4 v[128:131], v[144:145], off offset:16
	global_load_dwordx4 v[140:143], v[144:145], off
	v_addc_co_u32_e32 v147, vcc, 0, v145, vcc
	v_add_co_u32_e32 v148, vcc, s74, v144
	v_lshlrev_b32_e32 v196, 2, v134
	s_nop 0
	v_addc_co_u32_e32 v149, vcc, 0, v145, vcc
	v_lshlrev_b32_e32 v207, 2, v135
	global_load_dwordx4 v[132:135], v[132:133], off offset:16
	s_nop 0
	global_load_dwordx4 v[136:139], v[136:137], off offset:16
	s_nop 0
	global_load_dwordx4 v[144:147], v[146:147], off
	s_nop 0
	global_load_dwordx4 v[148:151], v[148:149], off
	v_mov_b32_e32 v197, 0
	v_mov_b32_e32 v211, 0
	v_readlane_b32 s46, v243, 5
	v_readlane_b32 s47, v243, 6
	v_readlane_b32 s48, v243, 7
	v_readlane_b32 s49, v243, 8
	v_readlane_b32 s50, v243, 9
	v_readlane_b32 s51, v243, 10
	v_readlane_b32 s52, v243, 11
	v_readlane_b32 s53, v243, 12
	v_readlane_b32 s54, v243, 13
	v_readlane_b32 s55, v243, 14
	v_readlane_b32 s56, v243, 15
	v_readlane_b32 s57, v243, 16
	v_readlane_b32 s58, v243, 17
	v_readlane_b32 s59, v243, 18
	s_waitcnt vmcnt(0)
	v_mov_b32_e32 v208, v152
	v_mov_b32_e32 v209, v156
	v_mov_b32_e32 v156, v153
	v_mov_b32_e32 v152, v154
	v_mov_b32_e32 v153, v158
	v_mov_b32_e32 v158, v155
	v_pk_add_f32 v[154:155], v[208:209], v[156:157]
	v_pk_add_f32 v[152:153], v[152:153], v[158:159]
	v_mov_b32_e32 v156, v188
	v_mov_b32_e32 v157, v192
	v_mov_b32_e32 v192, v189
	v_mov_b32_e32 v158, v190
	v_mov_b32_e32 v159, v194
	v_mov_b32_e32 v194, v191
	v_pk_add_f32 v[152:153], v[154:155], v[152:153]
	v_pk_add_f32 v[154:155], v[156:157], v[192:193]
	v_pk_add_f32 v[156:157], v[158:159], v[194:195]
	v_mov_b32_e32 v188, v212
	v_pk_add_f32 v[154:155], v[154:155], v[156:157]
	v_mov_b32_e32 v157, v152
	v_mov_b32_e32 v156, v154
	v_mov_b32_e32 v152, v155
	v_pk_add_f32 v[152:153], v[156:157], v[152:153]
	ds_bpermute_b32 v155, v196, v153
	ds_bpermute_b32 v154, v196, v152
	v_mov_b32_e32 v189, v216
	v_mov_b32_e32 v216, v213
	v_mov_b32_e32 v190, v214
	v_mov_b32_e32 v191, v218
	s_waitcnt lgkmcnt(0)
; DI unsigned pack2(float lo, float hi) { f32x2 v = {lo, hi}; bf16v2 r = __builtin_convertvector(v, bf16v2); return __builtin_bit_cast(unsigned, r); }
; DI float dpp_ror1(float v) { return __int_as_float(__builtin_amdgcn_update_dpp(0, __float_as_int(v), 0x121, 0xf, 0xf, false)); }
; DI float dpp_ror2(float v) { return __int_as_float(__builtin_amdgcn_update_dpp(0, __float_as_int(v), 0x122, 0xf, 0xf, false)); }
;   DI void operator()(const f32x4 (&acc)[2][2][4][2], const Unit& u, int wr, int wc, int fr, int fq) const {
;     ...
;       for (int m = 0; m < 4; ++m) {
;         float g[8], a[8];
;         const float rs1 = rsv[m], rs2 = rs1 * rs1;
; #pragma unroll
;         for (int e = 0; e < 4; ++e) { g[e] = acc[ai][0][m][0][e] * acc[ai][1][m][0][e] * rs2; g[4 + e] = acc[ai][0][m][1][e] * acc[ai][1][m][1][e] * rs2; }
; #pragma unroll
;         for (int e = 0; e < 8; ++e) {
;           const float x1 = dpp_ror1(g[e]), x2 = dpp_ror2(g[e]);
;           const float pr1 = (fr == 0) ? p1[e] : x1, pr2 = (fr < 2) ? p2[e] : x2;
;           a[e] = w2[e] * g[e] + w1[e] * pr1 + w0[e] * pr2;
;           p1[e] = x1; p2[e] = x2;
;         }
;         if (m == 0 && fr < 2) {
;           float* hc = headC + (size_t)(span * 2 + fr) * 2048 + col;
;           *(f32x4*)hc = (f32x4){a[0], a[1], a[2], a[3]}; *(f32x4*)(hc + 4) = (f32x4){a[4], a[5], a[6], a[7]};
;         } else {
;           u32x4 w; w.x = pack2(a[0] * rs1, a[1] * rs1); w.y = pack2(a[2] * rs1, a[3] * rs1); w.z = pack2(a[4] * rs1, a[5] * rs1); w.w = pack2(a[6] * rs1, a[7] * rs1);
;           *(u32x4*)(C + (size_t)(row0 + 16 * m + fr) * 2048 + col) = w;
;         }
	v_pk_add_f32 v[152:153], v[152:153], v[154:155]
	ds_bpermute_b32 v155, v207, v153
	ds_bpermute_b32 v154, v207, v152
	v_mov_b32_e32 v218, v215
	v_mov_b32_e32 v208, v220
	v_mov_b32_e32 v209, v224
	v_mov_b32_e32 v224, v221
	v_mov_b32_e32 v212, v222
	v_mov_b32_e32 v213, v226
	v_mov_b32_e32 v226, v223
	v_pk_add_f32 v[156:157], v[188:189], v[216:217]
	v_pk_add_f32 v[158:159], v[190:191], v[218:219]
	v_pk_add_f32 v[188:189], v[208:209], v[224:225]
	v_pk_add_f32 v[190:191], v[212:213], v[226:227]
	s_waitcnt lgkmcnt(0)
	v_pk_add_f32 v[152:153], v[152:153], v[154:155]
	v_pk_add_f32 v[156:157], v[156:157], v[158:159]
	v_pk_add_f32 v[158:159], v[188:189], v[190:191]
	v_pk_fma_f32 v[188:189], v[152:153], s[30:31], v[176:177] op_sel_hi:[1,0,0]
	v_mov_b32_e32 v153, v156
	v_mul_f32_e32 v152, 0x4b800000, v189
	v_cmp_gt_f32_e64 s[10:11], s84, v189
	v_mov_b32_e32 v156, v159
	v_mov_b32_e32 v194, v123
	v_cndmask_b32_e64 v152, v189, v152, s[10:11]
	v_rsq_f32_e32 v168, v152
	v_mov_b32_e32 v152, v158
	v_pk_add_f32 v[152:153], v[152:153], v[156:157]
	ds_bpermute_b32 v155, v196, v153
	ds_bpermute_b32 v154, v196, v152
	v_mul_f32_e32 v156, 0x45800000, v168
	v_cndmask_b32_e64 v195, v168, v156, s[10:11]
	v_mov_b32_e32 v217, 0
	v_mul_f32_e32 v156, v125, v113
	s_waitcnt lgkmcnt(0)
	v_pk_add_f32 v[190:191], v[152:153], v[154:155]
	v_mov_b32_e32 v152, v111
	v_mov_b32_e32 v153, v195
	v_mul_f32_e32 v154, v124, v112
	v_pk_mul_f32 v[152:153], v[194:195], v[152:153]
	v_mul_f32_e32 v155, v120, v108
	v_mul_f32_e32 v154, v154, v153
	v_pk_mul_f32 v[222:223], v[152:153], v[152:153] op_sel:[0,1] op_sel_hi:[1,0]
	v_mov_b32_e32 v213, 0
	v_mov_b32_dpp v217, v154 row_ror:1 row_mask:0xf bank_mask:0xf
	v_cndmask_b32_e64 v152, v217, 0, s[0:1]
	v_mul_f32_e32 v157, v121, v109
	v_mul_f32_e32 v158, v126, v114
	v_mul_f32_e32 v159, v122, v110
	v_mul_f32_e32 v168, v127, v115
	v_mul_f32_e32 v194, v155, v153
	v_mul_f32_e32 v155, v156, v153
	v_mov_b32_dpp v213, v154 row_ror:2 row_mask:0xf bank_mask:0xf
	v_mov_b32_e32 v221, 0
	v_mul_f32_e32 v152, v144, v152
	v_mul_f32_e32 v208, v157, v153
	v_mul_f32_e32 v156, v158, v153
	v_mul_f32_e32 v159, v159, v153
	v_mul_f32_e32 v157, v168, v153
	v_mov_b32_dpp v221, v155 row_ror:1 row_mask:0xf bank_mask:0xf
	v_cndmask_b32_e64 v153, v213, 0, s[8:9]
	v_fmac_f32_e32 v152, v148, v154
	v_mov_b32_e32 v219, 0
	v_fmac_f32_e32 v152, v140, v153
	v_cndmask_b32_e64 v153, v221, 0, s[0:1]
	v_mov_b32_dpp v219, v155 row_ror:2 row_mask:0xf bank_mask:0xf
	v_mul_f32_e32 v153, v145, v153
	v_mov_b32_e32 v216, 0
	v_cndmask_b32_e64 v154, v219, 0, s[8:9]
	v_fmac_f32_e32 v153, v149, v155
	v_mov_b32_dpp v216, v156 row_ror:1 row_mask:0xf bank_mask:0xf
	v_fmac_f32_e32 v153, v141, v154
	v_mov_b32_e32 v212, 0
	v_cndmask_b32_e64 v154, v216, 0, s[0:1]
	v_mov_b32_e32 v220, 0
	v_mov_b32_dpp v212, v156 row_ror:2 row_mask:0xf bank_mask:0xf
	v_mul_f32_e32 v154, v146, v154
	v_mov_b32_dpp v220, v157 row_ror:1 row_mask:0xf bank_mask:0xf
	v_cndmask_b32_e64 v155, v212, 0, s[8:9]
	v_fmac_f32_e32 v154, v150, v156
	v_mov_b32_e32 v218, 0
	v_fmac_f32_e32 v154, v142, v155
	v_cndmask_b32_e64 v155, v220, 0, s[0:1]
	v_mov_b32_dpp v218, v157 row_ror:2 row_mask:0xf bank_mask:0xf
	v_mul_f32_e32 v155, v147, v155
	v_cndmask_b32_e64 v156, v218, 0, s[8:9]
	v_fmac_f32_e32 v155, v151, v157
	v_mov_b32_dpp v197, v194 row_ror:1 row_mask:0xf bank_mask:0xf
	v_fmac_f32_e32 v155, v143, v156
	v_mov_b32_e32 v189, 0
	v_cndmask_b32_e64 v156, v197, 0, s[0:1]
	v_mov_b32_e32 v214, 0
	v_mov_b32_dpp v189, v194 row_ror:2 row_mask:0xf bank_mask:0xf
	v_mul_f32_e32 v156, v132, v156
	v_mov_b32_dpp v214, v208 row_ror:1 row_mask:0xf bank_mask:0xf
	v_cndmask_b32_e64 v157, v189, 0, s[8:9]
	v_fmac_f32_e32 v156, v136, v194
	v_fmac_f32_e32 v156, v128, v157
	v_cndmask_b32_e64 v157, v214, 0, s[0:1]
	v_mov_b32_e32 v209, 0
	v_mul_f32_e32 v157, v133, v157
	v_fmac_f32_e32 v157, v137, v208
	v_mov_b32_dpp v209, v208 row_ror:2 row_mask:0xf bank_mask:0xf
	v_mov_b32_e32 v208, 0
	v_cndmask_b32_e64 v158, v209, 0, s[8:9]
	v_fmac_f32_e32 v157, v129, v158
	v_mov_b32_dpp v208, v159 row_ror:1 row_mask:0xf bank_mask:0xf
	v_mov_b32_e32 v194, 0
	v_cndmask_b32_e64 v158, v208, 0, s[0:1]
	ds_bpermute_b32 v193, v207, v191
	ds_bpermute_b32 v192, v207, v190
	v_mov_b32_dpp v194, v159 row_ror:2 row_mask:0xf bank_mask:0xf
	v_mov_b32_e32 v215, 0
	v_mul_f32_e32 v158, v134, v158
	v_cndmask_b32_e64 v168, v194, 0, s[8:9]
	v_mov_b32_dpp v215, v222 row_ror:1 row_mask:0xf bank_mask:0xf
	v_fmac_f32_e32 v158, v138, v159
	v_mov_b32_dpp v211, v222 row_ror:2 row_mask:0xf bank_mask:0xf
	v_fmac_f32_e32 v158, v130, v168
	v_cndmask_b32_e64 v168, v215, 0, s[0:1]
	v_mul_f32_e32 v159, v139, v222
	v_cndmask_b32_e64 v223, v211, 0, s[8:9]
	v_fmac_f32_e32 v159, v135, v168
	v_cmp_gt_f32_e32 vcc, s84, v188
	v_fmac_f32_e32 v159, v131, v223
	s_and_saveexec_b64 s[10:11], s[4:5]
	s_xor_b64 s[10:11], exec, s[10:11]
	s_cbranch_execz .LBB0_1056
	v_mul_f32_e32 v152, v195, v152
	v_mul_f32_e32 v153, v195, v153
	v_cvt_pk_bf16_f32 v152, v152, v153
	v_mul_f32_e32 v153, v195, v154
	v_mul_f32_e32 v154, v195, v155
	v_cvt_pk_bf16_f32 v153, v153, v154
	v_mul_f32_e32 v154, v195, v156
	v_mul_f32_e32 v155, v195, v157
	v_cvt_pk_bf16_f32 v154, v154, v155
	v_mul_f32_e32 v155, v195, v158
	v_mul_f32_e32 v156, v195, v159
	v_cvt_pk_bf16_f32 v155, v155, v156
	v_lshlrev_b64 v[156:157], 12, v[186:187]
	v_lshl_add_u64 v[156:157], s[18:19], 0, v[156:157]
	v_lshl_add_u64 v[156:157], v[178:179], 1, v[156:157]
	global_store_dwordx4 v[156:157], v[152:155], off

; #define PG8_STAGE(bufoff, gbase, voff) do { _Pragma("unroll") for (int _i = 0; _i < 2; ++_i) \
;     __builtin_amdgcn_global_load_lds((const unsigned*)((const char*)(gbase) + (voff)[_i]), (LAS unsigned*)(lds + (bufoff) + ldsw + _i * 8192), 16, 0, 0); } while (0)
; #define PG8_LDA(dst, b, h) do { _Pragma("unroll") for (int m = 0; m < 4; ++m) _Pragma("unroll") for (int k = 0; k < 2; ++k) dst[m][k] = *(const LAS bf16x8*)(lds + PG8_SA(b, h) + aoff + m * 2048 + k * 1024); } while (0)
; #define PG8_LDB(dst, b, h) do { _Pragma("unroll") for (int n = 0; n < 2; ++n) _Pragma("unroll") for (int k = 0; k < 2; ++k) dst[n][k] = *(const LAS bf16x8*)(lds + PG8_SB(b, h) + boff + n * 2048 + k * 1024); } while (0)
; #define PG8_MMA(ai, bj, At, Bt) do { __builtin_amdgcn_s_setprio(1); _Pragma("unroll") for (int m = 0; m < 4; ++m) _Pragma("unroll") for (int n = 0; n < 2; ++n) _Pragma("unroll") for (int k = 0; k < 2; ++k) \
;     acc[ai][bj][m][n] = __builtin_amdgcn_mfma_f32_16x16x32_bf16(Bt[n][k], At[m][k], acc[ai][bj][m][n], 0, 0, 0); __builtin_amdgcn_s_setprio(0); } while (0)
; #define PG8_WAIT_V(n) asm volatile("s_waitcnt vmcnt(" #n ")" ::: "memory")
; #define PG8_WAIT_L(n) asm volatile("s_waitcnt lgkmcnt(" #n ")" ::: "memory")
; #define PG8_BAR __builtin_amdgcn_s_barrier()
; #define PG8_SCHED __builtin_amdgcn_sched_barrier(0)
; template <class Epi, class Sched = StaticOrder>
; DI void gemm_phase(LAS unsigned char* lds, const Gemm g, const Sched& S, const Epi& E) {
;     ...
;       PG8_LDB(B0, 0, 0); PG8_SCHED; PG8_LDA(At, 0, 0); PG8_STAGE(PG8_SA(1, 1), a1 + hstep, voffA);
;       PG8_WAIT_L(8); PG8_BAR; PG8_WAIT_L(0); PG8_MMA(0, 0, At, B0); PG8_BAR; PG8_SCHED;
;       PG8_LDB(B1, 0, 1); PG8_STAGE(PG8_SB(0, 0), b2, voffB);
;       PG8_BAR; PG8_WAIT_L(0); PG8_MMA(0, 1, At, B1); PG8_BAR;
;       PG8_LDA(At, 0, 1); PG8_STAGE(PG8_SA(0, 0), a2, voffA);
;       PG8_BAR; PG8_WAIT_L(0); PG8_MMA(1, 0, At, B0); PG8_BAR; PG8_SCHED;
;       PG8_STAGE(PG8_SB(0, 1), b2 + hstep, voffB);
;       PG8_WAIT_V(6); PG8_BAR; PG8_MMA(1, 1, At, B1); PG8_BAR;
;       PG8_LDB(B0, 1, 0); PG8_SCHED; PG8_LDA(At, 1, 0); PG8_STAGE(PG8_SA(0, 1), a2 + hstep, voffA);
.LBB0_1194:
	s_add_u32 s24, s22, 0xfff80080
	s_addc_u32 s25, s23, -1
	s_cmp_eq_u32 s54, 28
	s_cselect_b32 s27, s17, s25
	s_cselect_b32 s26, s43, s24
	s_cselect_b32 s25, s15, s53
	s_cselect_b32 s24, s51, s52
	s_add_i32 m0, s37, 0xc000
	ds_read_b128 v[144:147], v215
	ds_read_b128 v[148:151], v215 offset:1024
	ds_read_b128 v[152:155], v215 offset:2048
	ds_read_b128 v[156:159], v215 offset:3072
	ds_read_b128 v[160:163], v215 offset:4096
	ds_read_b128 v[164:167], v215 offset:5120
	ds_read_b128 v[168:171], v215 offset:6144
	ds_read_b128 v[172:175], v215 offset:7168
	global_load_lds_dwordx4 v184, s[22:23]
	s_add_i32 m0, s37, 0xe000
	s_nop 0
	global_load_lds_dwordx4 v186, s[22:23]
	s_waitcnt lgkmcnt(0)
	s_setprio 1
	s_barrier
	v_mfma_f32_16x16x32_bf16 v[124:127], v[128:131], v[144:147], v[124:127]
	v_mfma_f32_16x16x32_bf16 v[120:123], v[136:139], v[144:147], v[120:123]
	v_mfma_f32_16x16x32_bf16 v[108:111], v[128:131], v[152:155], v[108:111]
	v_mfma_f32_16x16x32_bf16 v[104:107], v[136:139], v[152:155], v[104:107]
	v_mfma_f32_16x16x32_bf16 v[92:95], v[128:131], v[160:163], v[92:95]
	v_mfma_f32_16x16x32_bf16 v[88:91], v[136:139], v[160:163], v[88:91]
	v_mfma_f32_16x16x32_bf16 v[76:79], v[128:131], v[168:171], v[76:79]
	v_mfma_f32_16x16x32_bf16 v[72:75], v[136:139], v[168:171], v[72:75]
	v_mfma_f32_16x16x32_bf16 v[124:127], v[132:135], v[148:151], v[124:127]
	v_mfma_f32_16x16x32_bf16 v[120:123], v[140:143], v[148:151], v[120:123]
	v_mfma_f32_16x16x32_bf16 v[108:111], v[132:135], v[156:159], v[108:111]
	v_mfma_f32_16x16x32_bf16 v[104:107], v[140:143], v[156:159], v[104:107]
	v_mfma_f32_16x16x32_bf16 v[92:95], v[132:135], v[164:167], v[92:95]
	v_mfma_f32_16x16x32_bf16 v[88:91], v[140:143], v[164:167], v[88:91]
	v_mfma_f32_16x16x32_bf16 v[76:79], v[132:135], v[172:175], v[76:79]
	v_mfma_f32_16x16x32_bf16 v[72:75], v[140:143], v[172:175], v[72:75]
	s_barrier
	s_setprio 0
	s_add_i32 s55, s48, s35
	s_add_u32 s98, s24, 0x80
	s_addc_u32 s99, s25, 0
	s_mov_b32 m0, s55
	ds_read_b128 v[192:195], v216
	ds_read_b128 v[196:199], v216 offset:1024
	ds_read_b128 v[200:203], v216 offset:2048
	ds_read_b128 v[204:207], v216 offset:3072
	global_load_lds_dwordx4 v180, s[24:25]
	s_add_i32 m0, s55, 0x2000
	s_nop 0
	global_load_lds_dwordx4 v176, s[24:25]
	s_waitcnt lgkmcnt(0)
	s_setprio 1
	s_barrier
	v_mfma_f32_16x16x32_bf16 v[116:119], v[192:195], v[144:147], v[116:119]
	v_mfma_f32_16x16x32_bf16 v[112:115], v[200:203], v[144:147], v[112:115]
	v_mfma_f32_16x16x32_bf16 v[100:103], v[192:195], v[152:155], v[100:103]
	v_mfma_f32_16x16x32_bf16 v[96:99], v[200:203], v[152:155], v[96:99]
	v_mfma_f32_16x16x32_bf16 v[84:87], v[192:195], v[160:163], v[84:87]
	v_mfma_f32_16x16x32_bf16 v[80:83], v[200:203], v[160:163], v[80:83]
	v_mfma_f32_16x16x32_bf16 v[68:71], v[192:195], v[168:171], v[68:71]
	v_mfma_f32_16x16x32_bf16 v[64:67], v[200:203], v[168:171], v[64:67]
	v_mfma_f32_16x16x32_bf16 v[116:119], v[196:199], v[148:151], v[116:119]
	v_mfma_f32_16x16x32_bf16 v[112:115], v[204:207], v[148:151], v[112:115]
	v_mfma_f32_16x16x32_bf16 v[100:103], v[196:199], v[156:159], v[100:103]
	v_mfma_f32_16x16x32_bf16 v[96:99], v[204:207], v[156:159], v[96:99]
	v_mfma_f32_16x16x32_bf16 v[84:87], v[196:199], v[164:167], v[84:87]
	v_mfma_f32_16x16x32_bf16 v[80:83], v[204:207], v[164:167], v[80:83]
	v_mfma_f32_16x16x32_bf16 v[68:71], v[196:199], v[172:175], v[68:71]
	v_mfma_f32_16x16x32_bf16 v[64:67], v[204:207], v[172:175], v[64:67]
	s_barrier
	s_setprio 0
	s_mov_b32 m0, s37
	s_add_u32 s100, s26, 0x80
	s_addc_u32 s101, s27, 0
	ds_read_b128 v[144:147], v215 offset:16384
	ds_read_b128 v[148:151], v215 offset:17408
	ds_read_b128 v[152:155], v215 offset:18432
	ds_read_b128 v[156:159], v215 offset:19456
	ds_read_b128 v[160:163], v215 offset:20480
	ds_read_b128 v[164:167], v215 offset:21504
	ds_read_b128 v[168:171], v215 offset:22528
	ds_read_b128 v[172:175], v215 offset:23552
	global_load_lds_dwordx4 v182, s[26:27]
	s_mov_b32 m0, s38
	s_nop 0
	global_load_lds_dwordx4 v178, s[26:27]
	s_waitcnt vmcnt(10)
	s_waitcnt lgkmcnt(0)
	s_setprio 1
	s_barrier
	v_mfma_f32_16x16x32_bf16 v[60:63], v[128:131], v[144:147], v[60:63]
	v_mfma_f32_16x16x32_bf16 v[56:59], v[136:139], v[144:147], v[56:59]
	v_mfma_f32_16x16x32_bf16 v[44:47], v[128:131], v[152:155], v[44:47]
	v_mfma_f32_16x16x32_bf16 v[40:43], v[136:139], v[152:155], v[40:43]
	v_mfma_f32_16x16x32_bf16 v[28:31], v[128:131], v[160:163], v[28:31]
	v_mfma_f32_16x16x32_bf16 v[24:27], v[136:139], v[160:163], v[24:27]
	v_mfma_f32_16x16x32_bf16 v[12:15], v[128:131], v[168:171], v[12:15]
	v_mfma_f32_16x16x32_bf16 v[8:11], v[136:139], v[168:171], v[8:11]
	v_mfma_f32_16x16x32_bf16 v[60:63], v[132:135], v[148:151], v[60:63]
	v_mfma_f32_16x16x32_bf16 v[56:59], v[140:143], v[148:151], v[56:59]
	v_mfma_f32_16x16x32_bf16 v[44:47], v[132:135], v[156:159], v[44:47]
	v_mfma_f32_16x16x32_bf16 v[40:43], v[140:143], v[156:159], v[40:43]
	v_mfma_f32_16x16x32_bf16 v[28:31], v[132:135], v[164:167], v[28:31]
	v_mfma_f32_16x16x32_bf16 v[24:27], v[140:143], v[164:167], v[24:27]
	v_mfma_f32_16x16x32_bf16 v[12:15], v[132:135], v[172:175], v[12:15]
	v_mfma_f32_16x16x32_bf16 v[8:11], v[140:143], v[172:175], v[8:11]
	s_barrier
	s_setprio 0
	s_add_u32 s56, s24, 0x80000
	s_addc_u32 s57, s25, 0
	s_add_i32 s55, s49, s35
	s_mov_b32 m0, s55
	s_nop 0
	global_load_lds_dwordx4 v180, s[56:57]
	s_add_i32 m0, s55, 0x2000
	s_nop 0
	global_load_lds_dwordx4 v176, s[56:57]
	s_add_i32 s55, 0, 0x18000
	v_add_u32_e32 v140, s55, v212
	ds_read_b128 v[128:131], v140
	ds_read_b128 v[132:135], v140 offset:1024
	ds_read_b128 v[136:139], v140 offset:2048
	ds_read_b128 v[140:143], v140 offset:3072
	s_waitcnt vmcnt(6)
	s_setprio 1
	s_barrier
; #define PG8_STAGE(bufoff, gbase, voff) do { _Pragma("unroll") for (int _i = 0; _i < 2; ++_i) \
;     __builtin_amdgcn_global_load_lds((const unsigned*)((const char*)(gbase) + (voff)[_i]), (LAS unsigned*)(lds + (bufoff) + ldsw + _i * 8192), 16, 0, 0); } while (0)
; #define PG8_LDA(dst, b, h) do { _Pragma("unroll") for (int m = 0; m < 4; ++m) _Pragma("unroll") for (int k = 0; k < 2; ++k) dst[m][k] = *(const LAS bf16x8*)(lds + PG8_SA(b, h) + aoff + m * 2048 + k * 1024); } while (0)
; #define PG8_LDB(dst, b, h) do { _Pragma("unroll") for (int n = 0; n < 2; ++n) _Pragma("unroll") for (int k = 0; k < 2; ++k) dst[n][k] = *(const LAS bf16x8*)(lds + PG8_SB(b, h) + boff + n * 2048 + k * 1024); } while (0)
; #define PG8_MMA(ai, bj, At, Bt) do { __builtin_amdgcn_s_setprio(1); _Pragma("unroll") for (int m = 0; m < 4; ++m) _Pragma("unroll") for (int n = 0; n < 2; ++n) _Pragma("unroll") for (int k = 0; k < 2; ++k) \
;     acc[ai][bj][m][n] = __builtin_amdgcn_mfma_f32_16x16x32_bf16(Bt[n][k], At[m][k], acc[ai][bj][m][n], 0, 0, 0); __builtin_amdgcn_s_setprio(0); } while (0)
; #define PG8_WAIT_V(n) asm volatile("s_waitcnt vmcnt(" #n ")" ::: "memory")
; #define PG8_WAIT_L(n) asm volatile("s_waitcnt lgkmcnt(" #n ")" ::: "memory")
; #define PG8_BAR __builtin_amdgcn_s_barrier()
; #define PG8_SCHED __builtin_amdgcn_sched_barrier(0)
; template <class Epi, class Sched = StaticOrder>
; DI void gemm_phase(LAS unsigned char* lds, const Gemm g, const Sched& S, const Epi& E) {
;     ...
;       PG8_WAIT_V(6); PG8_BAR; PG8_MMA(1, 1, At, B1); PG8_BAR;
;       PG8_LDB(B0, 1, 0); PG8_SCHED; PG8_LDA(At, 1, 0); PG8_STAGE(PG8_SA(0, 1), a2 + hstep, voffA);
;       PG8_WAIT_L(8); PG8_BAR; PG8_WAIT_L(0); PG8_MMA(0, 0, At, B0); PG8_BAR; PG8_SCHED;
;       PG8_LDB(B1, 1, 1); PG8_STAGE(PG8_SB(1, 0), b3, voffB);
;       PG8_BAR; PG8_WAIT_L(0); PG8_MMA(0, 1, At, B1); PG8_BAR;
;       PG8_LDA(At, 1, 1); PG8_STAGE(PG8_SA(1, 0), a3, voffA);
;       PG8_BAR; PG8_WAIT_L(0); PG8_MMA(1, 0, At, B0); PG8_BAR; PG8_SCHED;
	v_mfma_f32_16x16x32_bf16 v[52:55], v[192:195], v[144:147], v[52:55]
	v_mfma_f32_16x16x32_bf16 v[48:51], v[200:203], v[144:147], v[48:51]
	v_mfma_f32_16x16x32_bf16 v[36:39], v[192:195], v[152:155], v[36:39]
	v_mfma_f32_16x16x32_bf16 v[32:35], v[200:203], v[152:155], v[32:35]
	v_mfma_f32_16x16x32_bf16 v[20:23], v[192:195], v[160:163], v[20:23]
	v_mfma_f32_16x16x32_bf16 v[16:19], v[200:203], v[160:163], v[16:19]
	v_mfma_f32_16x16x32_bf16 v[4:7], v[192:195], v[168:171], v[4:7]
	v_mfma_f32_16x16x32_bf16 v[0:3], v[200:203], v[168:171], v[0:3]
	v_mfma_f32_16x16x32_bf16 v[52:55], v[196:199], v[148:151], v[52:55]
	v_mfma_f32_16x16x32_bf16 v[48:51], v[204:207], v[148:151], v[48:51]
	v_mfma_f32_16x16x32_bf16 v[36:39], v[196:199], v[156:159], v[36:39]
	v_mfma_f32_16x16x32_bf16 v[32:35], v[204:207], v[156:159], v[32:35]
	v_mfma_f32_16x16x32_bf16 v[20:23], v[196:199], v[164:167], v[20:23]
	v_mfma_f32_16x16x32_bf16 v[16:19], v[204:207], v[164:167], v[16:19]
	v_mfma_f32_16x16x32_bf16 v[4:7], v[196:199], v[172:175], v[4:7]
	v_mfma_f32_16x16x32_bf16 v[0:3], v[204:207], v[172:175], v[0:3]
	s_barrier
	s_setprio 0
	s_add_u32 s26, s26, 0x80000
	s_addc_u32 s27, s27, 0
	s_mov_b32 m0, s39
	ds_read_b128 v[144:147], v215 offset:32768
	ds_read_b128 v[148:151], v215 offset:33792
	ds_read_b128 v[152:155], v215 offset:34816
	ds_read_b128 v[156:159], v215 offset:35840
	ds_read_b128 v[160:163], v215 offset:36864
	ds_read_b128 v[164:167], v215 offset:37888
	ds_read_b128 v[168:171], v215 offset:38912
	ds_read_b128 v[172:175], v215 offset:39936
	global_load_lds_dwordx4 v182, s[26:27]
	s_mov_b32 m0, s40
	s_nop 0
	global_load_lds_dwordx4 v178, s[26:27]
	s_waitcnt lgkmcnt(0)
	s_setprio 1
	s_barrier
	v_mfma_f32_16x16x32_bf16 v[124:127], v[128:131], v[144:147], v[124:127]
	v_mfma_f32_16x16x32_bf16 v[120:123], v[136:139], v[144:147], v[120:123]
	v_mfma_f32_16x16x32_bf16 v[108:111], v[128:131], v[152:155], v[108:111]
	v_mfma_f32_16x16x32_bf16 v[104:107], v[136:139], v[152:155], v[104:107]
	v_mfma_f32_16x16x32_bf16 v[92:95], v[128:131], v[160:163], v[92:95]
	v_mfma_f32_16x16x32_bf16 v[88:91], v[136:139], v[160:163], v[88:91]
	v_mfma_f32_16x16x32_bf16 v[76:79], v[128:131], v[168:171], v[76:79]
	v_mfma_f32_16x16x32_bf16 v[72:75], v[136:139], v[168:171], v[72:75]
	v_mfma_f32_16x16x32_bf16 v[124:127], v[132:135], v[148:151], v[124:127]
	v_mfma_f32_16x16x32_bf16 v[120:123], v[140:143], v[148:151], v[120:123]
	v_mfma_f32_16x16x32_bf16 v[108:111], v[132:135], v[156:159], v[108:111]
	v_mfma_f32_16x16x32_bf16 v[104:107], v[140:143], v[156:159], v[104:107]
	v_mfma_f32_16x16x32_bf16 v[92:95], v[132:135], v[164:167], v[92:95]
	v_mfma_f32_16x16x32_bf16 v[88:91], v[140:143], v[164:167], v[88:91]
	v_mfma_f32_16x16x32_bf16 v[76:79], v[132:135], v[172:175], v[76:79]
	v_mfma_f32_16x16x32_bf16 v[72:75], v[140:143], v[172:175], v[72:75]
	s_barrier
	s_setprio 0
	s_add_i32 s26, 0, 0x1c000
	s_add_i32 s27, s55, s35
	v_add_u32_e32 v204, s26, v212
	s_mov_b32 m0, s27
	ds_read_b128 v[192:195], v204
	ds_read_b128 v[196:199], v204 offset:1024
	ds_read_b128 v[200:203], v204 offset:2048
	ds_read_b128 v[204:207], v204 offset:3072
	global_load_lds_dwordx4 v180, s[98:99]
	s_add_i32 m0, s27, 0x2000
	s_nop 0
	global_load_lds_dwordx4 v176, s[98:99]
	s_waitcnt lgkmcnt(0)
	s_setprio 1
	s_barrier
	v_mfma_f32_16x16x32_bf16 v[116:119], v[192:195], v[144:147], v[116:119]
	v_mfma_f32_16x16x32_bf16 v[112:115], v[200:203], v[144:147], v[112:115]
	v_mfma_f32_16x16x32_bf16 v[100:103], v[192:195], v[152:155], v[100:103]
	v_mfma_f32_16x16x32_bf16 v[96:99], v[200:203], v[152:155], v[96:99]
	v_mfma_f32_16x16x32_bf16 v[84:87], v[192:195], v[160:163], v[84:87]
	v_mfma_f32_16x16x32_bf16 v[80:83], v[200:203], v[160:163], v[80:83]
	v_mfma_f32_16x16x32_bf16 v[68:71], v[192:195], v[168:171], v[68:71]
	v_mfma_f32_16x16x32_bf16 v[64:67], v[200:203], v[168:171], v[64:67]
	v_mfma_f32_16x16x32_bf16 v[116:119], v[196:199], v[148:151], v[116:119]
	v_mfma_f32_16x16x32_bf16 v[112:115], v[204:207], v[148:151], v[112:115]
	v_mfma_f32_16x16x32_bf16 v[100:103], v[196:199], v[156:159], v[100:103]
	v_mfma_f32_16x16x32_bf16 v[96:99], v[204:207], v[156:159], v[96:99]
	v_mfma_f32_16x16x32_bf16 v[84:87], v[196:199], v[164:167], v[84:87]
	v_mfma_f32_16x16x32_bf16 v[80:83], v[204:207], v[164:167], v[80:83]
	v_mfma_f32_16x16x32_bf16 v[68:71], v[196:199], v[172:175], v[68:71]
	v_mfma_f32_16x16x32_bf16 v[64:67], v[204:207], v[172:175], v[64:67]
	s_barrier
	s_setprio 0
	s_mov_b32 m0, s44
	ds_read_b128 v[144:147], v215 offset:49152
	ds_read_b128 v[148:151], v215 offset:50176
	ds_read_b128 v[152:155], v215 offset:51200
	ds_read_b128 v[156:159], v215 offset:52224
	ds_read_b128 v[160:163], v215 offset:53248
	ds_read_b128 v[164:167], v215 offset:54272
	ds_read_b128 v[168:171], v215 offset:55296
	ds_read_b128 v[172:175], v215 offset:56320
	global_load_lds_dwordx4 v182, s[100:101]
	s_mov_b32 m0, s45
	s_nop 0
	global_load_lds_dwordx4 v178, s[100:101]
	s_waitcnt vmcnt(10)
	s_waitcnt lgkmcnt(0)
	s_setprio 1
	s_barrier
	v_mfma_f32_16x16x32_bf16 v[60:63], v[128:131], v[144:147], v[60:63]
	v_mfma_f32_16x16x32_bf16 v[56:59], v[136:139], v[144:147], v[56:59]
	v_mfma_f32_16x16x32_bf16 v[44:47], v[128:131], v[152:155], v[44:47]
	v_mfma_f32_16x16x32_bf16 v[40:43], v[136:139], v[152:155], v[40:43]
	v_mfma_f32_16x16x32_bf16 v[28:31], v[128:131], v[160:163], v[28:31]
	v_mfma_f32_16x16x32_bf16 v[24:27], v[136:139], v[160:163], v[24:27]
	v_mfma_f32_16x16x32_bf16 v[12:15], v[128:131], v[168:171], v[12:15]
	v_mfma_f32_16x16x32_bf16 v[8:11], v[136:139], v[168:171], v[8:11]
	v_mfma_f32_16x16x32_bf16 v[60:63], v[132:135], v[148:151], v[60:63]
	v_mfma_f32_16x16x32_bf16 v[56:59], v[140:143], v[148:151], v[56:59]
	v_mfma_f32_16x16x32_bf16 v[44:47], v[132:135], v[156:159], v[44:47]
	v_mfma_f32_16x16x32_bf16 v[40:43], v[140:143], v[156:159], v[40:43]
	v_mfma_f32_16x16x32_bf16 v[28:31], v[132:135], v[164:167], v[28:31]
	v_mfma_f32_16x16x32_bf16 v[24:27], v[140:143], v[164:167], v[24:27]
	v_mfma_f32_16x16x32_bf16 v[12:15], v[132:135], v[172:175], v[12:15]
	v_mfma_f32_16x16x32_bf16 v[8:11], v[140:143], v[172:175], v[8:11]
	s_barrier
; DI unsigned pack2(float lo, float hi) { f32x2 v = {lo, hi}; bf16v2 r = __builtin_convertvector(v, bf16v2); return __builtin_bit_cast(unsigned, r); }
; #define PG8_STAGE(bufoff, gbase, voff) do { _Pragma("unroll") for (int _i = 0; _i < 2; ++_i) \
;     __builtin_amdgcn_global_load_lds((const unsigned*)((const char*)(gbase) + (voff)[_i]), (LAS unsigned*)(lds + (bufoff) + ldsw + _i * 8192), 16, 0, 0); } while (0)
; #define PG8_WAIT_V(n) asm volatile("s_waitcnt vmcnt(" #n ")" ::: "memory")
; #define PG8_BAR __builtin_amdgcn_s_barrier()
;   DI void operator()(const f32x4 (&acc)[2][2][4][2], const Unit& u, int wr, int wc, int fr, int fq) const {
;     const int row0 = u.pm * BM + wr * 64 + fr, col0 = u.pn * BM + wc * 32 + 8 * fq;
; #pragma unroll
;     for (int ai = 0; ai < 2; ++ai) {
;       f32x4 bv[4][2][2];
; #pragma unroll
;       for (int m = 0; m < 4; ++m)
; #pragma unroll
;         for (int bj = 0; bj < 2; ++bj) {
;           const float* bp = base + (size_t)(row0 + ai * HALF + m * 16) * 2048 + col0 + bj * HALF;
;           bv[m][bj][0] = *(const f32x4*)bp; bv[m][bj][1] = *(const f32x4*)(bp + 4);
;         }
; #pragma unroll
;       for (int m = 0; m < 4; ++m) {
;         const int row = row0 + ai * HALF + m * 16;
;         const size_t off = (size_t)row * 2048 + col0;
;         float ss = 0.f;
; #pragma unroll
;         for (int bj = 0; bj < 2; ++bj) {
;           const f32x4 v0 = acc[ai][bj][m][0] + bv[m][bj][0], v1 = acc[ai][bj][m][1] + bv[m][bj][1];
;           *(f32x4*)(C + off + bj * HALF) = v0; *(f32x4*)(C + off + bj * HALF + 4) = v1;
;           if (xb) {
;             u32x4 w; w.x = pack2(v0[0], v0[1]); w.y = pack2(v0[2], v0[3]); w.z = pack2(v1[0], v1[1]); w.w = pack2(v1[2], v1[3]);
;             *(u32x4*)(xb + off + bj * HALF) = w;
;             ss += v0[0] * v0[0] + v0[1] * v0[1] + v0[2] * v0[2] + v0[3] * v0[3] + v1[0] * v1[0] + v1[1] * v1[1] + v1[2] * v1[2] + v1[3] * v1[3];
;           }
;         }
;         if (xb) {
;           ss += __shfl_xor(ss, 16); ss += __shfl_xor(ss, 32);
;           if (fq == 0) ssq[(size_t)row * 32 + u.pn * 4 + wc] = ss;
;         }
; template <class Epi, class Sched = StaticOrder>
; DI void gemm_phase(LAS unsigned char* lds, const Gemm g, const Sched& S, const Epi& E) {
;     ...
;       PG8_STAGE(PG8_SB(1, 1), b3 + hstep, voffB);
;       PG8_WAIT_V(6); PG8_BAR; PG8_MMA(1, 1, At, B1); PG8_BAR;
	s_setprio 0
	s_add_u32 s24, s24, 0x80080
	s_addc_u32 s25, s25, 0
	s_add_i32 s26, s26, s35
	s_mov_b32 m0, s26
	s_nop 0
	global_load_lds_dwordx4 v180, s[24:25]
	s_add_i32 m0, s26, 0x2000
	s_nop 0
	global_load_lds_dwordx4 v176, s[24:25]
	ds_read_b128 v[128:131], v214
	ds_read_b128 v[132:135], v214 offset:1024
	ds_read_b128 v[136:139], v214 offset:2048
	ds_read_b128 v[140:143], v214 offset:3072
	s_waitcnt vmcnt(6)
	s_add_i32 s54, s54, 2
	s_add_u32 s22, s22, 0x100
	s_addc_u32 s23, s23, 0
	s_add_u32 s52, s52, 0x100
	s_addc_u32 s53, s53, 0
	s_cmp_gt_u32 s54, 29
	s_setprio 1
	s_barrier
	v_mfma_f32_16x16x32_bf16 v[52:55], v[192:195], v[144:147], v[52:55]
	v_mfma_f32_16x16x32_bf16 v[48:51], v[200:203], v[144:147], v[48:51]
	v_mfma_f32_16x16x32_bf16 v[36:39], v[192:195], v[152:155], v[36:39]
	v_mfma_f32_16x16x32_bf16 v[32:35], v[200:203], v[152:155], v[32:35]
	v_mfma_f32_16x16x32_bf16 v[20:23], v[192:195], v[160:163], v[20:23]
	v_mfma_f32_16x16x32_bf16 v[16:19], v[200:203], v[160:163], v[16:19]
	v_mfma_f32_16x16x32_bf16 v[4:7], v[192:195], v[168:171], v[4:7]
	v_mfma_f32_16x16x32_bf16 v[0:3], v[200:203], v[168:171], v[0:3]
	v_mfma_f32_16x16x32_bf16 v[52:55], v[196:199], v[148:151], v[52:55]
	v_mfma_f32_16x16x32_bf16 v[48:51], v[204:207], v[148:151], v[48:51]
	v_mfma_f32_16x16x32_bf16 v[36:39], v[196:199], v[156:159], v[36:39]
	v_mfma_f32_16x16x32_bf16 v[32:35], v[204:207], v[156:159], v[32:35]
	v_mfma_f32_16x16x32_bf16 v[20:23], v[196:199], v[164:167], v[20:23]
	v_mfma_f32_16x16x32_bf16 v[16:19], v[204:207], v[164:167], v[16:19]
	v_mfma_f32_16x16x32_bf16 v[4:7], v[196:199], v[172:175], v[4:7]
	v_mfma_f32_16x16x32_bf16 v[0:3], v[204:207], v[172:175], v[0:3]
	s_barrier
	s_setprio 0
	s_cbranch_scc0 .LBB0_1194
	s_waitcnt lgkmcnt(0)
	v_lshl_add_u32 v194, s12, 8, v211
	v_lshl_or_b32 v192, s42, 8, v213
	v_readlane_b32 s52, v243, 3
	v_ashrrev_i32_e32 v193, 31, v192
	v_readlane_b32 s66, v243, 17
	v_readlane_b32 s67, v243, 18
	v_ashrrev_i32_e32 v195, 31, v194
	v_lshlrev_b64 v[128:129], 13, v[194:195]
	v_lshl_add_u64 v[196:197], v[192:193], 2, s[66:67]
	v_lshl_add_u64 v[236:237], v[196:197], 0, v[128:129]
	global_load_dwordx4 v[220:223], v[236:237], off
	global_load_dwordx4 v[224:227], v[236:237], off offset:16
	global_load_dwordx4 v[228:231], v[236:237], off offset:512
	global_load_dwordx4 v[232:235], v[236:237], off offset:528
	v_or_b32_e32 v206, 16, v194
	v_or_b32_e32 v202, 32, v194
	v_or_b32_e32 v198, 48, v194
	v_ashrrev_i32_e32 v207, 31, v206
	v_ashrrev_i32_e32 v203, 31, v202
	v_ashrrev_i32_e32 v199, 31, v198
	v_lshlrev_b64 v[128:129], 13, v[206:207]
	v_lshlrev_b64 v[130:131], 13, v[202:203]
	v_lshlrev_b64 v[132:133], 13, v[198:199]
	v_lshl_add_u64 v[208:209], v[196:197], 0, v[128:129]
	v_lshl_add_u64 v[204:205], v[196:197], 0, v[130:131]
	v_lshl_add_u64 v[200:201], v[196:197], 0, v[132:133]
	global_load_dwordx4 v[168:171], v[208:209], off offset:16
	global_load_dwordx4 v[172:175], v[208:209], off
	global_load_dwordx4 v[160:163], v[208:209], off offset:528
	global_load_dwordx4 v[164:167], v[208:209], off offset:512
	global_load_dwordx4 v[152:155], v[204:205], off offset:16
	global_load_dwordx4 v[156:159], v[204:205], off
	global_load_dwordx4 v[144:147], v[204:205], off offset:528
	global_load_dwordx4 v[148:151], v[204:205], off offset:512
	global_load_dwordx4 v[136:139], v[200:201], off offset:16
	global_load_dwordx4 v[140:143], v[200:201], off
	global_load_dwordx4 v[128:131], v[200:201], off offset:528
	global_load_dwordx4 v[132:135], v[200:201], off offset:512
	v_and_b32_e32 v218, 64, v217
	v_xor_b32_e32 v238, 16, v217
	v_add_u32_e32 v240, 64, v218
	v_xor_b32_e32 v239, 32, v217
	v_cmp_lt_i32_e32 vcc, v238, v240
	v_lshlrev_b64 v[218:219], 11, v[194:195]
	s_lshl_b32 s22, s42, 2
	v_cndmask_b32_e32 v241, v217, v238, vcc
	v_cmp_lt_i32_e32 vcc, v239, v240
	s_ashr_i32 s23, s22, 31
	v_readlane_b32 s53, v243, 4
	v_cndmask_b32_e32 v240, v217, v239, vcc
	v_lshl_add_u64 v[238:239], v[218:219], 0, v[192:193]
	v_lshlrev_b32_e32 v218, 2, v241
	v_lshl_add_u64 v[238:239], v[238:239], 1, s[2:3]
	v_readlane_b32 s54, v243, 5
	v_readlane_b32 s55, v243, 6
	v_readlane_b32 s56, v243, 7
	v_readlane_b32 s57, v243, 8
	v_readlane_b32 s58, v243, 9
	v_readlane_b32 s59, v243, 10
	v_readlane_b32 s60, v243, 11
	v_readlane_b32 s61, v243, 12
	v_readlane_b32 s62, v243, 13
	v_readlane_b32 s63, v243, 14
	v_readlane_b32 s64, v243, 15
	v_readlane_b32 s65, v243, 16
	s_waitcnt vmcnt(0)
	v_pk_add_f32 v[126:127], v[126:127], v[222:223]
	v_pk_add_f32 v[124:125], v[124:125], v[220:221]
	v_pk_add_f32 v[116:117], v[116:117], v[228:229]
	v_pk_add_f32 v[122:123], v[122:123], v[226:227]
	v_pk_add_f32 v[120:121], v[120:121], v[224:225]
	v_pk_add_f32 v[220:221], v[112:113], v[232:233]
	global_store_dwordx4 v[236:237], v[124:127], off
	global_store_dwordx4 v[236:237], v[120:123], off offset:16
	v_cvt_pk_bf16_f32 v112, v124, v125
	v_mul_f32_e32 v125, v125, v125
	v_mul_f32_e32 v219, v117, v117
	v_pk_add_f32 v[118:119], v[118:119], v[230:231]
	v_fmac_f32_e32 v125, v124, v124
	v_fmac_f32_e32 v219, v116, v116
	v_fmac_f32_e32 v125, v126, v126
	v_fmac_f32_e32 v219, v118, v118
	v_fmac_f32_e32 v125, v127, v127
	v_fmac_f32_e32 v219, v119, v119
	v_fmac_f32_e32 v125, v120, v120
	v_fmac_f32_e32 v219, v220, v220
	v_pk_add_f32 v[222:223], v[114:115], v[234:235]
	v_fmac_f32_e32 v125, v121, v121
	v_fmac_f32_e32 v219, v221, v221
	v_fmac_f32_e32 v125, v122, v122
	v_fmac_f32_e32 v219, v222, v222
	v_fmac_f32_e32 v125, v123, v123
	v_fmac_f32_e32 v219, v223, v223
	v_cvt_pk_bf16_f32 v114, v120, v121
	v_add_f32_e32 v121, v125, v219
	v_cvt_pk_bf16_f32 v115, v122, v123
	ds_bpermute_b32 v122, v218, v121
	v_cvt_pk_bf16_f32 v113, v126, v127
	global_store_dwordx4 v[238:239], v[112:115], off
	global_store_dwordx4 v[236:237], v[116:119], off offset:512
	global_store_dwordx4 v[236:237], v[220:223], off offset:528
	v_lshlrev_b32_e32 v126, 2, v240
	v_cvt_pk_bf16_f32 v120, v116, v117
	s_waitcnt lgkmcnt(0)
	v_add_f32_e32 v112, v121, v122
	ds_bpermute_b32 v113, v126, v112
	v_cvt_pk_bf16_f32 v121, v118, v119
	v_cvt_pk_bf16_f32 v122, v220, v221
	v_cvt_pk_bf16_f32 v123, v222, v223
	global_store_dwordx4 v[238:239], v[120:123], off offset:256
	s_and_saveexec_b64 s[24:25], s[0:1]
	s_cbranch_execz .LBB0_1197
	s_waitcnt lgkmcnt(0)
	v_add_f32_e32 v114, v112, v113
	v_lshlrev_b64 v[112:113], 7, v[194:195]
	v_lshl_add_u64 v[112:113], s[8:9], 0, v[112:113]
	v_lshl_add_u64 v[112:113], s[22:23], 2, v[112:113]
	s_lshl_b32 s12, s41, 2
	v_lshl_add_u64 v[112:113], v[112:113], 0, s[12:13]
	global_store_dword v[112:113], v114, off

; #define PG8_STAGE(bufoff, gbase, voff) do { _Pragma("unroll") for (int _i = 0; _i < 2; ++_i) \
;     __builtin_amdgcn_global_load_lds((const unsigned*)((const char*)(gbase) + (voff)[_i]), (LAS unsigned*)(lds + (bufoff) + ldsw + _i * 8192), 16, 0, 0); } while (0)
; #define PG8_LDA(dst, b, h) do { _Pragma("unroll") for (int m = 0; m < 4; ++m) _Pragma("unroll") for (int k = 0; k < 2; ++k) dst[m][k] = *(const LAS bf16x8*)(lds + PG8_SA(b, h) + aoff + m * 2048 + k * 1024); } while (0)
; #define PG8_LDB(dst, b, h) do { _Pragma("unroll") for (int n = 0; n < 2; ++n) _Pragma("unroll") for (int k = 0; k < 2; ++k) dst[n][k] = *(const LAS bf16x8*)(lds + PG8_SB(b, h) + boff + n * 2048 + k * 1024); } while (0)
; #define PG8_MMA(ai, bj, At, Bt) do { __builtin_amdgcn_s_setprio(1); _Pragma("unroll") for (int m = 0; m < 4; ++m) _Pragma("unroll") for (int n = 0; n < 2; ++n) _Pragma("unroll") for (int k = 0; k < 2; ++k) \
;     acc[ai][bj][m][n] = __builtin_amdgcn_mfma_f32_16x16x32_bf16(Bt[n][k], At[m][k], acc[ai][bj][m][n], 0, 0, 0); __builtin_amdgcn_s_setprio(0); } while (0)
; #define PG8_WAIT_V(n) asm volatile("s_waitcnt vmcnt(" #n ")" ::: "memory")
; #define PG8_WAIT_L(n) asm volatile("s_waitcnt lgkmcnt(" #n ")" ::: "memory")
; #define PG8_BAR __builtin_amdgcn_s_barrier()
; #define PG8_SCHED __builtin_amdgcn_sched_barrier(0)
; template <class Epi, class Sched = StaticOrder>
; DI void gemm_phase(LAS unsigned char* lds, const Gemm g, const Sched& S, const Epi& E) {
;     ...
;       PG8_LDB(B0, 0, 0); PG8_SCHED; PG8_LDA(At, 0, 0); PG8_STAGE(PG8_SA(1, 1), a1 + hstep, voffA);
;       PG8_WAIT_L(8); PG8_BAR; PG8_WAIT_L(0); PG8_MMA(0, 0, At, B0); PG8_BAR; PG8_SCHED;
;       PG8_LDB(B1, 0, 1); PG8_STAGE(PG8_SB(0, 0), b2, voffB);
;       PG8_BAR; PG8_WAIT_L(0); PG8_MMA(0, 1, At, B1); PG8_BAR;
;       PG8_LDA(At, 0, 1); PG8_STAGE(PG8_SA(0, 0), a2, voffA);
;       PG8_BAR; PG8_WAIT_L(0); PG8_MMA(1, 0, At, B0); PG8_BAR; PG8_SCHED;
;       PG8_STAGE(PG8_SB(0, 1), b2 + hstep, voffB);
;       PG8_WAIT_V(6); PG8_BAR; PG8_MMA(1, 1, At, B1); PG8_BAR;
;       PG8_LDB(B0, 1, 0); PG8_SCHED; PG8_LDA(At, 1, 0); PG8_STAGE(PG8_SA(0, 1), a2 + hstep, voffA);
.LBB0_1277:
	s_add_u32 s48, s14, 0xfff80080
	s_addc_u32 s49, s15, -1
	s_cmp_eq_u32 s58, 28
	s_cselect_b32 s51, s41, s49
	s_cselect_b32 s50, s42, s48
	s_cselect_b32 s49, s39, s53
	s_cselect_b32 s48, s43, s52
	s_add_i32 m0, s64, 0xc000
	ds_read_b128 v[80:83], v202
	ds_read_b128 v[84:87], v202 offset:1024
	ds_read_b128 v[88:91], v202 offset:2048
	ds_read_b128 v[92:95], v202 offset:3072
	ds_read_b128 v[180:183], v202 offset:4096
	ds_read_b128 v[184:187], v202 offset:5120
	ds_read_b128 v[188:191], v202 offset:6144
	ds_read_b128 v[192:195], v202 offset:7168
	global_load_lds_dwordx4 v170, s[14:15]
	s_add_i32 m0, s64, 0xe000
	s_nop 0
	global_load_lds_dwordx4 v172, s[14:15]
	s_waitcnt lgkmcnt(0)
	s_setprio 1
	s_barrier
	v_mfma_f32_16x16x32_bf16 v[156:159], v[64:67], v[80:83], v[156:159]
	v_mfma_f32_16x16x32_bf16 v[144:147], v[72:75], v[80:83], v[144:147]
	v_mfma_f32_16x16x32_bf16 v[140:143], v[64:67], v[88:91], v[140:143]
	v_mfma_f32_16x16x32_bf16 v[132:135], v[72:75], v[88:91], v[132:135]
	v_mfma_f32_16x16x32_bf16 v[124:127], v[64:67], v[180:183], v[124:127]
	v_mfma_f32_16x16x32_bf16 v[116:119], v[72:75], v[180:183], v[116:119]
	v_mfma_f32_16x16x32_bf16 v[112:115], v[64:67], v[188:191], v[112:115]
	v_mfma_f32_16x16x32_bf16 v[108:111], v[72:75], v[188:191], v[108:111]
	v_mfma_f32_16x16x32_bf16 v[156:159], v[68:71], v[84:87], v[156:159]
	v_mfma_f32_16x16x32_bf16 v[144:147], v[76:79], v[84:87], v[144:147]
	v_mfma_f32_16x16x32_bf16 v[140:143], v[68:71], v[92:95], v[140:143]
	v_mfma_f32_16x16x32_bf16 v[132:135], v[76:79], v[92:95], v[132:135]
	v_mfma_f32_16x16x32_bf16 v[124:127], v[68:71], v[184:187], v[124:127]
	v_mfma_f32_16x16x32_bf16 v[116:119], v[76:79], v[184:187], v[116:119]
	v_mfma_f32_16x16x32_bf16 v[112:115], v[68:71], v[192:195], v[112:115]
	v_mfma_f32_16x16x32_bf16 v[108:111], v[76:79], v[192:195], v[108:111]
	s_barrier
	s_setprio 0
	s_add_i32 s59, s72, s62
	s_add_u32 s98, s48, 0x80
	s_addc_u32 s99, s49, 0
	s_mov_b32 m0, s59
	ds_read_b128 v[206:209], v203
	ds_read_b128 v[212:215], v203 offset:1024
	ds_read_b128 v[216:219], v203 offset:2048
	ds_read_b128 v[220:223], v203 offset:3072
	global_load_lds_dwordx4 v164, s[48:49]
	s_add_i32 m0, s59, 0x2000
	s_nop 0
	global_load_lds_dwordx4 v160, s[48:49]
	s_waitcnt lgkmcnt(0)
	s_setprio 1
	s_barrier
	v_mfma_f32_16x16x32_bf16 v[152:155], v[206:209], v[80:83], v[152:155]
	v_mfma_f32_16x16x32_bf16 v[80:83], v[216:219], v[80:83], v[148:151]
	v_mfma_f32_16x16x32_bf16 v[152:155], v[212:215], v[84:87], v[152:155]
	v_mfma_f32_16x16x32_bf16 v[80:83], v[220:223], v[84:87], v[80:83]
	v_mfma_f32_16x16x32_bf16 v[84:87], v[206:209], v[88:91], v[136:139]
	v_mfma_f32_16x16x32_bf16 v[88:91], v[216:219], v[88:91], v[128:131]
	v_mfma_f32_16x16x32_bf16 v[104:107], v[216:219], v[180:183], v[104:107]
	v_mfma_f32_16x16x32_bf16 v[100:103], v[206:209], v[188:191], v[100:103]
	v_mfma_f32_16x16x32_bf16 v[96:99], v[216:219], v[188:191], v[96:99]
	v_mfma_f32_16x16x32_bf16 v[84:87], v[212:215], v[92:95], v[84:87]
	v_mfma_f32_16x16x32_bf16 v[88:91], v[220:223], v[92:95], v[88:91]
	v_mfma_f32_16x16x32_bf16 v[92:95], v[206:209], v[180:183], v[120:123]
	v_mfma_f32_16x16x32_bf16 v[104:107], v[220:223], v[184:187], v[104:107]
	v_mfma_f32_16x16x32_bf16 v[100:103], v[212:215], v[192:195], v[100:103]
	v_mfma_f32_16x16x32_bf16 v[96:99], v[220:223], v[192:195], v[96:99]
	v_mfma_f32_16x16x32_bf16 v[92:95], v[212:215], v[184:187], v[92:95]
	s_barrier
	s_setprio 0
	s_mov_b32 m0, s64
	s_add_u32 s100, s50, 0x80
	s_addc_u32 s101, s51, 0
	ds_read_b128 v[120:123], v202 offset:16384
	ds_read_b128 v[128:131], v202 offset:17408
	ds_read_b128 v[136:139], v202 offset:18432
	ds_read_b128 v[148:151], v202 offset:19456
	ds_read_b128 v[180:183], v202 offset:20480
	ds_read_b128 v[184:187], v202 offset:21504
	ds_read_b128 v[188:191], v202 offset:22528
	ds_read_b128 v[192:195], v202 offset:23552
	global_load_lds_dwordx4 v166, s[50:51]
	s_mov_b32 m0, s65
	s_nop 0
	global_load_lds_dwordx4 v162, s[50:51]
	s_waitcnt vmcnt(10)
	s_waitcnt lgkmcnt(0)
	s_setprio 1
	s_barrier
	v_mfma_f32_16x16x32_bf16 v[60:63], v[64:67], v[120:123], v[60:63]
	v_mfma_f32_16x16x32_bf16 v[48:51], v[72:75], v[120:123], v[48:51]
	v_mfma_f32_16x16x32_bf16 v[44:47], v[64:67], v[136:139], v[44:47]
	v_mfma_f32_16x16x32_bf16 v[36:39], v[72:75], v[136:139], v[36:39]
	v_mfma_f32_16x16x32_bf16 v[28:31], v[64:67], v[180:183], v[28:31]
	v_mfma_f32_16x16x32_bf16 v[20:23], v[72:75], v[180:183], v[20:23]
	v_mfma_f32_16x16x32_bf16 v[16:19], v[64:67], v[188:191], v[16:19]
	v_mfma_f32_16x16x32_bf16 v[12:15], v[72:75], v[188:191], v[12:15]
	v_mfma_f32_16x16x32_bf16 v[60:63], v[68:71], v[128:131], v[60:63]
	v_mfma_f32_16x16x32_bf16 v[48:51], v[76:79], v[128:131], v[48:51]
	v_mfma_f32_16x16x32_bf16 v[44:47], v[68:71], v[148:151], v[44:47]
	v_mfma_f32_16x16x32_bf16 v[36:39], v[76:79], v[148:151], v[36:39]
	v_mfma_f32_16x16x32_bf16 v[28:31], v[68:71], v[184:187], v[28:31]
	v_mfma_f32_16x16x32_bf16 v[20:23], v[76:79], v[184:187], v[20:23]
	v_mfma_f32_16x16x32_bf16 v[16:19], v[68:71], v[192:195], v[16:19]
	v_mfma_f32_16x16x32_bf16 v[12:15], v[76:79], v[192:195], v[12:15]
	s_barrier
	s_setprio 0
	s_add_u32 s78, s48, 0x80000
	s_addc_u32 s79, s49, 0
	s_add_i32 s59, s73, s62
	s_mov_b32 m0, s59
	s_nop 0
	global_load_lds_dwordx4 v164, s[78:79]
	s_add_i32 m0, s59, 0x2000
	s_nop 0
	global_load_lds_dwordx4 v160, s[78:79]
	s_add_i32 s59, 0, 0x18000
	v_add_u32_e32 v76, s59, v198
	ds_read_b128 v[64:67], v76
	ds_read_b128 v[68:71], v76 offset:1024
	ds_read_b128 v[72:75], v76 offset:2048
	ds_read_b128 v[76:79], v76 offset:3072
	s_waitcnt vmcnt(6)
	s_setprio 1
	s_barrier
; #define PG8_STAGE(bufoff, gbase, voff) do { _Pragma("unroll") for (int _i = 0; _i < 2; ++_i) \
;     __builtin_amdgcn_global_load_lds((const unsigned*)((const char*)(gbase) + (voff)[_i]), (LAS unsigned*)(lds + (bufoff) + ldsw + _i * 8192), 16, 0, 0); } while (0)
; #define PG8_LDA(dst, b, h) do { _Pragma("unroll") for (int m = 0; m < 4; ++m) _Pragma("unroll") for (int k = 0; k < 2; ++k) dst[m][k] = *(const LAS bf16x8*)(lds + PG8_SA(b, h) + aoff + m * 2048 + k * 1024); } while (0)
; #define PG8_LDB(dst, b, h) do { _Pragma("unroll") for (int n = 0; n < 2; ++n) _Pragma("unroll") for (int k = 0; k < 2; ++k) dst[n][k] = *(const LAS bf16x8*)(lds + PG8_SB(b, h) + boff + n * 2048 + k * 1024); } while (0)
; #define PG8_MMA(ai, bj, At, Bt) do { __builtin_amdgcn_s_setprio(1); _Pragma("unroll") for (int m = 0; m < 4; ++m) _Pragma("unroll") for (int n = 0; n < 2; ++n) _Pragma("unroll") for (int k = 0; k < 2; ++k) \
;     acc[ai][bj][m][n] = __builtin_amdgcn_mfma_f32_16x16x32_bf16(Bt[n][k], At[m][k], acc[ai][bj][m][n], 0, 0, 0); __builtin_amdgcn_s_setprio(0); } while (0)
; #define PG8_WAIT_V(n) asm volatile("s_waitcnt vmcnt(" #n ")" ::: "memory")
; #define PG8_WAIT_L(n) asm volatile("s_waitcnt lgkmcnt(" #n ")" ::: "memory")
; #define PG8_BAR __builtin_amdgcn_s_barrier()
; #define PG8_SCHED __builtin_amdgcn_sched_barrier(0)
; template <class Epi, class Sched = StaticOrder>
; DI void gemm_phase(LAS unsigned char* lds, const Gemm g, const Sched& S, const Epi& E) {
;     ...
;       PG8_WAIT_V(6); PG8_BAR; PG8_MMA(1, 1, At, B1); PG8_BAR;
;       PG8_LDB(B0, 1, 0); PG8_SCHED; PG8_LDA(At, 1, 0); PG8_STAGE(PG8_SA(0, 1), a2 + hstep, voffA);
;       PG8_WAIT_L(8); PG8_BAR; PG8_WAIT_L(0); PG8_MMA(0, 0, At, B0); PG8_BAR; PG8_SCHED;
;       PG8_LDB(B1, 1, 1); PG8_STAGE(PG8_SB(1, 0), b3, voffB);
;       PG8_BAR; PG8_WAIT_L(0); PG8_MMA(0, 1, At, B1); PG8_BAR;
;       PG8_LDA(At, 1, 1); PG8_STAGE(PG8_SA(1, 0), a3, voffA);
;       PG8_BAR; PG8_WAIT_L(0); PG8_MMA(1, 0, At, B0); PG8_BAR; PG8_SCHED;
	v_mfma_f32_16x16x32_bf16 v[56:59], v[206:209], v[120:123], v[56:59]
	v_mfma_f32_16x16x32_bf16 v[52:55], v[216:219], v[120:123], v[52:55]
	v_mfma_f32_16x16x32_bf16 v[40:43], v[206:209], v[136:139], v[40:43]
	v_mfma_f32_16x16x32_bf16 v[32:35], v[216:219], v[136:139], v[32:35]
	v_mfma_f32_16x16x32_bf16 v[24:27], v[206:209], v[180:183], v[24:27]
	v_mfma_f32_16x16x32_bf16 v[8:11], v[216:219], v[180:183], v[8:11]
	v_mfma_f32_16x16x32_bf16 v[4:7], v[206:209], v[188:191], v[4:7]
	v_mfma_f32_16x16x32_bf16 v[0:3], v[216:219], v[188:191], v[0:3]
	v_mfma_f32_16x16x32_bf16 v[56:59], v[212:215], v[128:131], v[56:59]
	v_mfma_f32_16x16x32_bf16 v[52:55], v[220:223], v[128:131], v[52:55]
	v_mfma_f32_16x16x32_bf16 v[40:43], v[212:215], v[148:151], v[40:43]
	v_mfma_f32_16x16x32_bf16 v[32:35], v[220:223], v[148:151], v[32:35]
	v_mfma_f32_16x16x32_bf16 v[24:27], v[212:215], v[184:187], v[24:27]
	v_mfma_f32_16x16x32_bf16 v[8:11], v[220:223], v[184:187], v[8:11]
	v_mfma_f32_16x16x32_bf16 v[4:7], v[212:215], v[192:195], v[4:7]
	v_mfma_f32_16x16x32_bf16 v[0:3], v[220:223], v[192:195], v[0:3]
	s_barrier
	s_setprio 0
	s_add_u32 s50, s50, 0x80000
	s_addc_u32 s51, s51, 0
	s_mov_b32 m0, s66
	ds_read_b128 v[120:123], v202 offset:32768
	ds_read_b128 v[128:131], v202 offset:33792
	ds_read_b128 v[180:183], v202 offset:34816
	ds_read_b128 v[184:187], v202 offset:35840
	ds_read_b128 v[188:191], v202 offset:36864
	ds_read_b128 v[192:195], v202 offset:37888
	ds_read_b128 v[206:209], v202 offset:38912
	ds_read_b128 v[212:215], v202 offset:39936
	global_load_lds_dwordx4 v166, s[50:51]
	s_mov_b32 m0, s67
	s_nop 0
	global_load_lds_dwordx4 v162, s[50:51]
	s_waitcnt lgkmcnt(0)
	s_setprio 1
	s_barrier
	v_mfma_f32_16x16x32_bf16 v[136:139], v[64:67], v[120:123], v[156:159]
	v_mfma_f32_16x16x32_bf16 v[156:159], v[68:71], v[128:131], v[136:139]
	v_mfma_f32_16x16x32_bf16 v[136:139], v[72:75], v[120:123], v[144:147]
	v_mfma_f32_16x16x32_bf16 v[144:147], v[76:79], v[128:131], v[136:139]
	v_mfma_f32_16x16x32_bf16 v[136:139], v[64:67], v[180:183], v[140:143]
	v_mfma_f32_16x16x32_bf16 v[132:135], v[72:75], v[180:183], v[132:135]
	v_mfma_f32_16x16x32_bf16 v[124:127], v[64:67], v[188:191], v[124:127]
	v_mfma_f32_16x16x32_bf16 v[116:119], v[72:75], v[188:191], v[116:119]
	v_mfma_f32_16x16x32_bf16 v[112:115], v[64:67], v[206:209], v[112:115]
	v_mfma_f32_16x16x32_bf16 v[108:111], v[72:75], v[206:209], v[108:111]
	v_mfma_f32_16x16x32_bf16 v[140:143], v[68:71], v[184:187], v[136:139]
	v_mfma_f32_16x16x32_bf16 v[132:135], v[76:79], v[184:187], v[132:135]
	v_mfma_f32_16x16x32_bf16 v[124:127], v[68:71], v[192:195], v[124:127]
	v_mfma_f32_16x16x32_bf16 v[116:119], v[76:79], v[192:195], v[116:119]
	v_mfma_f32_16x16x32_bf16 v[112:115], v[68:71], v[212:215], v[112:115]
	v_mfma_f32_16x16x32_bf16 v[108:111], v[76:79], v[212:215], v[108:111]
	s_barrier
	s_setprio 0
	s_add_i32 s50, 0, 0x1c000
	v_add_u32_e32 v136, s50, v198
	s_add_i32 s51, s59, s62
	ds_read_b128 v[216:219], v136
	ds_read_b128 v[220:223], v136 offset:1024
	ds_read_b128 v[224:227], v136 offset:2048
	ds_read_b128 v[228:231], v136 offset:3072
	s_mov_b32 m0, s51
	s_nop 0
	global_load_lds_dwordx4 v164, s[98:99]
	s_add_i32 m0, s51, 0x2000
	s_nop 0
	global_load_lds_dwordx4 v160, s[98:99]
	s_waitcnt lgkmcnt(0)
	s_setprio 1
	s_barrier
	v_mfma_f32_16x16x32_bf16 v[80:83], v[224:227], v[120:123], v[80:83]
	v_mfma_f32_16x16x32_bf16 v[136:139], v[216:219], v[120:123], v[152:155]
	v_mfma_f32_16x16x32_bf16 v[148:151], v[228:231], v[128:131], v[80:83]
	v_mfma_f32_16x16x32_bf16 v[80:83], v[216:219], v[180:183], v[84:87]
	v_mfma_f32_16x16x32_bf16 v[152:155], v[220:223], v[128:131], v[136:139]
	v_mfma_f32_16x16x32_bf16 v[136:139], v[220:223], v[184:187], v[80:83]
	v_mfma_f32_16x16x32_bf16 v[80:83], v[224:227], v[180:183], v[88:91]
	v_mfma_f32_16x16x32_bf16 v[128:131], v[228:231], v[184:187], v[80:83]
	v_mfma_f32_16x16x32_bf16 v[80:83], v[216:219], v[188:191], v[92:95]
	v_mfma_f32_16x16x32_bf16 v[120:123], v[220:223], v[192:195], v[80:83]
	v_mfma_f32_16x16x32_bf16 v[80:83], v[224:227], v[188:191], v[104:107]
	v_mfma_f32_16x16x32_bf16 v[104:107], v[228:231], v[192:195], v[80:83]
	v_mfma_f32_16x16x32_bf16 v[80:83], v[216:219], v[206:209], v[100:103]
	v_mfma_f32_16x16x32_bf16 v[100:103], v[220:223], v[212:215], v[80:83]
	v_mfma_f32_16x16x32_bf16 v[80:83], v[224:227], v[206:209], v[96:99]
	v_mfma_f32_16x16x32_bf16 v[96:99], v[228:231], v[212:215], v[80:83]
	s_barrier
	s_setprio 0
	s_mov_b32 m0, s55
	s_nop 2
	ds_read_b128 v[80:83], v202 offset:49152
	ds_read_b128 v[84:87], v202 offset:50176
	ds_read_b128 v[88:91], v202 offset:51200
	ds_read_b128 v[92:95], v202 offset:52224
	ds_read_b128 v[180:183], v202 offset:53248
	ds_read_b128 v[184:187], v202 offset:54272
	ds_read_b128 v[188:191], v202 offset:55296
	ds_read_b128 v[192:195], v202 offset:56320
	global_load_lds_dwordx4 v166, s[100:101]
	s_mov_b32 m0, s68
	s_nop 0
	global_load_lds_dwordx4 v162, s[100:101]
	s_waitcnt vmcnt(10)
	s_waitcnt lgkmcnt(0)
	s_setprio 1
	s_barrier
	v_mfma_f32_16x16x32_bf16 v[60:63], v[64:67], v[80:83], v[60:63]
	v_mfma_f32_16x16x32_bf16 v[48:51], v[72:75], v[80:83], v[48:51]
	v_mfma_f32_16x16x32_bf16 v[44:47], v[64:67], v[88:91], v[44:47]
	v_mfma_f32_16x16x32_bf16 v[36:39], v[72:75], v[88:91], v[36:39]
	v_mfma_f32_16x16x32_bf16 v[28:31], v[64:67], v[180:183], v[28:31]
	v_mfma_f32_16x16x32_bf16 v[20:23], v[72:75], v[180:183], v[20:23]
	v_mfma_f32_16x16x32_bf16 v[16:19], v[64:67], v[188:191], v[16:19]
	v_mfma_f32_16x16x32_bf16 v[12:15], v[72:75], v[188:191], v[12:15]
	v_mfma_f32_16x16x32_bf16 v[60:63], v[68:71], v[84:87], v[60:63]
	v_mfma_f32_16x16x32_bf16 v[48:51], v[76:79], v[84:87], v[48:51]
	v_mfma_f32_16x16x32_bf16 v[44:47], v[68:71], v[92:95], v[44:47]
	v_mfma_f32_16x16x32_bf16 v[36:39], v[76:79], v[92:95], v[36:39]
	v_mfma_f32_16x16x32_bf16 v[28:31], v[68:71], v[184:187], v[28:31]
	v_mfma_f32_16x16x32_bf16 v[20:23], v[76:79], v[184:187], v[20:23]
	v_mfma_f32_16x16x32_bf16 v[16:19], v[68:71], v[192:195], v[16:19]
	v_mfma_f32_16x16x32_bf16 v[12:15], v[76:79], v[192:195], v[12:15]
	s_barrier
; #define PG8_STAGE(bufoff, gbase, voff) do { _Pragma("unroll") for (int _i = 0; _i < 2; ++_i) \
;     __builtin_amdgcn_global_load_lds((const unsigned*)((const char*)(gbase) + (voff)[_i]), (LAS unsigned*)(lds + (bufoff) + ldsw + _i * 8192), 16, 0, 0); } while (0)
; #define PG8_MMA(ai, bj, At, Bt) do { __builtin_amdgcn_s_setprio(1); _Pragma("unroll") for (int m = 0; m < 4; ++m) _Pragma("unroll") for (int n = 0; n < 2; ++n) _Pragma("unroll") for (int k = 0; k < 2; ++k) \
;     acc[ai][bj][m][n] = __builtin_amdgcn_mfma_f32_16x16x32_bf16(Bt[n][k], At[m][k], acc[ai][bj][m][n], 0, 0, 0); __builtin_amdgcn_s_setprio(0); } while (0)
; #define PG8_WAIT_V(n) asm volatile("s_waitcnt vmcnt(" #n ")" ::: "memory")
; #define PG8_BAR __builtin_amdgcn_s_barrier()
; DI float row_rstd(const float* ssq, int row, int fq) {
;   const f32x4 a = *(const f32x4*)(ssq + (size_t)row * 32 + fq * 8), b = *(const f32x4*)(ssq + (size_t)row * 32 + fq * 8 + 4);
;   float sm = ((a[0] + a[1]) + (a[2] + a[3])) + ((b[0] + b[1]) + (b[2] + b[3]));
;   sm += __shfl_xor(sm, 16); sm += __shfl_xor(sm, 32);
;   return rsqrtf(sm * (1.0f / 2048.f) + 1e-6f);
;   DI void operator()(const f32x4 (&acc)[2][2][4][2], const Unit& u, int wr, int wc, int fr, int fq) const {
;     const int col = u.pn * 128 + wc * 32 + 8 * fq;
;     float w0[8], w1[8], w2[8], bb[8];
; #pragma unroll
;     for (int e = 0; e < 8; ++e) { w0[e] = cw[col + e]; w1[e] = cw[5632 + col + e]; w2[e] = cw[2 * 5632 + col + e]; bb[e] = cb[col + e]; }
; #pragma unroll
;     for (int ai = 0; ai < 2; ++ai) {
;       const int row0 = u.pm * BM + ai * HALF + wr * 64, span = row0 >> 6;
;       float rsv[4];
; #pragma unroll
;       for (int m = 0; m < 4; ++m) rsv[m] = row_rstd(ssq, row0 + 16 * m + fr, fq);
; template <class Epi, class Sched = StaticOrder>
; DI void gemm_phase(LAS unsigned char* lds, const Gemm g, const Sched& S, const Epi& E) {
;     ...
;       PG8_STAGE(PG8_SB(1, 1), b3 + hstep, voffB);
;       PG8_WAIT_V(6); PG8_BAR; PG8_MMA(1, 1, At, B1); PG8_BAR;
	s_setprio 0
	s_add_u32 s48, s48, 0x80080
	s_addc_u32 s49, s49, 0
	s_add_i32 s50, s50, s62
	s_mov_b32 m0, s50
	s_nop 0
	global_load_lds_dwordx4 v164, s[48:49]
	s_add_i32 m0, s50, 0x2000
	s_nop 0
	global_load_lds_dwordx4 v160, s[48:49]
	ds_read_b128 v[64:67], v201
	ds_read_b128 v[68:71], v201 offset:1024
	ds_read_b128 v[72:75], v201 offset:2048
	ds_read_b128 v[76:79], v201 offset:3072
	s_waitcnt vmcnt(6)
	s_add_i32 s58, s58, 2
	s_add_u32 s14, s14, 0x100
	s_addc_u32 s15, s15, 0
	s_add_u32 s52, s52, 0x100
	s_addc_u32 s53, s53, 0
	s_cmp_gt_u32 s58, 29
	s_setprio 1
	s_barrier
	v_mfma_f32_16x16x32_bf16 v[56:59], v[216:219], v[80:83], v[56:59]
	v_mfma_f32_16x16x32_bf16 v[52:55], v[224:227], v[80:83], v[52:55]
	v_mfma_f32_16x16x32_bf16 v[40:43], v[216:219], v[88:91], v[40:43]
	v_mfma_f32_16x16x32_bf16 v[32:35], v[224:227], v[88:91], v[32:35]
	v_mfma_f32_16x16x32_bf16 v[24:27], v[216:219], v[180:183], v[24:27]
	v_mfma_f32_16x16x32_bf16 v[8:11], v[224:227], v[180:183], v[8:11]
	v_mfma_f32_16x16x32_bf16 v[4:7], v[216:219], v[188:191], v[4:7]
	v_mfma_f32_16x16x32_bf16 v[0:3], v[224:227], v[188:191], v[0:3]
	v_mfma_f32_16x16x32_bf16 v[56:59], v[220:223], v[84:87], v[56:59]
	v_mfma_f32_16x16x32_bf16 v[52:55], v[228:231], v[84:87], v[52:55]
	v_mfma_f32_16x16x32_bf16 v[40:43], v[220:223], v[92:95], v[40:43]
	v_mfma_f32_16x16x32_bf16 v[32:35], v[228:231], v[92:95], v[32:35]
	v_mfma_f32_16x16x32_bf16 v[24:27], v[220:223], v[184:187], v[24:27]
	v_mfma_f32_16x16x32_bf16 v[8:11], v[228:231], v[184:187], v[8:11]
	v_mfma_f32_16x16x32_bf16 v[4:7], v[220:223], v[192:195], v[4:7]
	v_mfma_f32_16x16x32_bf16 v[0:3], v[228:231], v[192:195], v[0:3]
	s_barrier
	s_setprio 0
	s_cbranch_scc0 .LBB0_1277
	s_waitcnt lgkmcnt(0)
	s_lshl_b32 s39, s12, 8
	s_add_i32 s39, s39, s54
	v_or_b32_e32 v190, s39, v179
	v_ashrrev_i32_e32 v191, 31, v190
	v_lshlrev_b64 v[64:65], 7, v[190:191]
	v_or_b32_e32 v188, 16, v190
	v_lshl_add_u64 v[64:65], v[168:169], 0, v[64:65]
	v_ashrrev_i32_e32 v189, 31, v188
	global_load_dwordx4 v[192:195], v[64:65], off
	global_load_dwordx4 v[206:209], v[64:65], off offset:16
	v_lshlrev_b64 v[64:65], 7, v[188:189]
	v_lshl_add_u64 v[64:65], v[168:169], 0, v[64:65]
	global_load_dwordx4 v[212:215], v[64:65], off
	global_load_dwordx4 v[216:219], v[64:65], off offset:16
	v_or_b32_e32 v186, 32, v190
	v_ashrrev_i32_e32 v187, 31, v186
	v_lshlrev_b64 v[64:65], 7, v[186:187]
	v_or_b32_e32 v184, 48, v190
	v_lshl_add_u64 v[64:65], v[168:169], 0, v[64:65]
	v_ashrrev_i32_e32 v185, 31, v184
	global_load_dwordx4 v[220:223], v[64:65], off
	global_load_dwordx4 v[224:227], v[64:65], off offset:16
	v_lshlrev_b64 v[64:65], 7, v[184:185]
	v_lshl_add_u64 v[64:65], v[168:169], 0, v[64:65]
	global_load_dwordx4 v[228:231], v[64:65], off
	global_load_dwordx4 v[232:235], v[64:65], off offset:16
	v_lshl_or_b32 v180, s13, 7, v200
	v_and_b32_e32 v65, 64, v204
	v_xor_b32_e32 v64, 16, v204
	v_ashrrev_i32_e32 v181, 31, v180
	v_add_u32_e32 v65, 64, v65
	v_xor_b32_e32 v66, 32, v204
	v_lshlrev_b64 v[182:183], 2, v[180:181]
	v_cmp_lt_i32_e32 vcc, v64, v65
	v_lshl_add_u64 v[88:89], s[16:17], 0, v[182:183]
	v_lshl_add_u64 v[72:73], s[18:19], 0, v[182:183]
	v_cndmask_b32_e32 v64, v204, v64, vcc
	v_cmp_lt_i32_e32 vcc, v66, v65
	v_lshl_add_u64 v[74:75], v[88:89], 0, s[30:31]
	v_lshl_add_u64 v[76:77], v[88:89], 0, s[34:35]
	v_cndmask_b32_e32 v65, v204, v66, vcc
	v_add_co_u32_e32 v90, vcc, 0x5000, v88
	v_lshlrev_b32_e32 v187, 2, v64
	s_nop 0
	v_addc_co_u32_e32 v91, vcc, 0, v89, vcc
	v_add_co_u32_e32 v92, vcc, 0xb000, v88
	v_lshlrev_b32_e32 v185, 2, v65
	s_nop 0
	v_addc_co_u32_e32 v93, vcc, 0, v89, vcc
	global_load_dwordx4 v[64:67], v[88:89], off offset:16
	global_load_dwordx4 v[80:83], v[88:89], off
	global_load_dwordx4 v[68:71], v[72:73], off offset:16
	global_load_dwordx4 v[84:87], v[72:73], off
	s_nop 0
	global_load_dwordx4 v[72:75], v[74:75], off offset:16
	s_nop 0
	global_load_dwordx4 v[76:79], v[76:77], off offset:16
	s_nop 0
	global_load_dwordx4 v[88:91], v[90:91], off offset:2048
	s_nop 0
	global_load_dwordx4 v[92:95], v[92:93], off
	v_mov_b32_e32 v211, 0
	v_mov_b32_e32 v205, 0
	s_waitcnt vmcnt(0)
	v_mov_b32_e32 v196, v192
	v_mov_b32_e32 v197, v206
	v_mov_b32_e32 v206, v193
	v_mov_b32_e32 v192, v194
	v_mov_b32_e32 v193, v208
	v_mov_b32_e32 v208, v195
	v_pk_add_f32 v[194:195], v[196:197], v[206:207]
	v_pk_add_f32 v[192:193], v[192:193], v[208:209]
	v_mov_b32_e32 v196, v212
	v_mov_b32_e32 v197, v216
	v_mov_b32_e32 v216, v213
	v_mov_b32_e32 v206, v214
	v_mov_b32_e32 v207, v218
	v_mov_b32_e32 v218, v215
	v_pk_add_f32 v[192:193], v[194:195], v[192:193]
	v_pk_add_f32 v[194:195], v[196:197], v[216:217]
	v_pk_add_f32 v[196:197], v[206:207], v[218:219]
	v_mov_b32_e32 v208, v220
	v_pk_add_f32 v[194:195], v[194:195], v[196:197]
	v_mov_b32_e32 v197, v192
	v_mov_b32_e32 v196, v194
	v_mov_b32_e32 v192, v195
	v_pk_add_f32 v[192:193], v[196:197], v[192:193]
	ds_bpermute_b32 v195, v187, v193
	ds_bpermute_b32 v194, v187, v192
	v_mov_b32_e32 v209, v224
	v_mov_b32_e32 v224, v221
	v_mov_b32_e32 v212, v222
	v_mov_b32_e32 v213, v226
	s_waitcnt lgkmcnt(0)
	v_pk_add_f32 v[192:193], v[192:193], v[194:195]
	ds_bpermute_b32 v195, v185, v193
	ds_bpermute_b32 v194, v185, v192
	v_mov_b32_e32 v226, v223
	v_mov_b32_e32 v196, v228
	v_mov_b32_e32 v197, v232
	v_mov_b32_e32 v232, v229
	s_waitcnt lgkmcnt(0)
; DI unsigned pack2(float lo, float hi) { f32x2 v = {lo, hi}; bf16v2 r = __builtin_convertvector(v, bf16v2); return __builtin_bit_cast(unsigned, r); }
; DI float silu_f(float x) { return x * sigmoid_f(x); }
; DI float dpp_ror1(float v) { return __int_as_float(__builtin_amdgcn_update_dpp(0, __float_as_int(v), 0x121, 0xf, 0xf, false)); }
; DI float dpp_ror2(float v) { return __int_as_float(__builtin_amdgcn_update_dpp(0, __float_as_int(v), 0x122, 0xf, 0xf, false)); }
;   DI void operator()(const f32x4 (&acc)[2][2][4][2], const Unit& u, int wr, int wc, int fr, int fq) const {
;     ...
;       for (int m = 0; m < 4; ++m) rsv[m] = row_rstd(ssq, row0 + 16 * m + fr, fq);
;       float p1[8], p2[8];
; #pragma unroll
;       for (int e = 0; e < 8; ++e) { p1[e] = 0.f; p2[e] = 0.f; }
; #pragma unroll
;       for (int m = 0; m < 4; ++m) {
;         float g[8], uu[8], a[8];
;         const float rs = rsv[m];
; #pragma unroll
;         for (int e = 0; e < 4; ++e) { g[e] = acc[ai][0][m][0][e] * rs; g[4 + e] = acc[ai][0][m][1][e] * rs; uu[e] = acc[ai][1][m][0][e] * rs; uu[4 + e] = acc[ai][1][m][1][e] * rs; }
; #pragma unroll
;         for (int e = 0; e < 8; ++e) {
;           const float x1 = dpp_ror1(g[e]), x2 = dpp_ror2(g[e]);
;           const float pr1 = (fr == 0) ? p1[e] : x1, pr2 = (fr < 2) ? p2[e] : x2;
;           a[e] = w2[e] * g[e] + w1[e] * pr1 + w0[e] * pr2 + bb[e];
;           p1[e] = x1; p2[e] = x2;
;         }
;         if (m == 0 && fr < 2) {
;           float* ha = headA + (size_t)(span * 2 + fr) * 5632 + col; float* hu = headU + (size_t)(span * 2 + fr) * 5632 + col;
;           *(f32x4*)ha = (f32x4){a[0], a[1], a[2], a[3]}; *(f32x4*)(ha + 4) = (f32x4){a[4], a[5], a[6], a[7]};
;           *(f32x4*)hu = (f32x4){uu[0], uu[1], uu[2], uu[3]}; *(f32x4*)(hu + 4) = (f32x4){uu[4], uu[5], uu[6], uu[7]};
;         } else {
;           u32x4 w;
;           w.x = pack2(silu_f(a[0]) * uu[0], silu_f(a[1]) * uu[1]);
;           w.y = pack2(silu_f(a[2]) * uu[2], silu_f(a[3]) * uu[3]);
;           w.z = pack2(silu_f(a[4]) * uu[4], silu_f(a[5]) * uu[5]);
;           w.w = pack2(silu_f(a[6]) * uu[6], silu_f(a[7]) * uu[7]);
;           *(u32x4*)(H + (size_t)(row0 + 16 * m + fr) * 5632 + col) = w;
	v_pk_add_f32 v[192:193], v[192:193], v[194:195]
	v_mov_b32_e32 v206, v230
	v_pk_fma_f32 v[192:193], v[192:193], s[36:37], v[178:179] op_sel_hi:[1,0,0]
	v_mov_b32_e32 v207, v234
	v_mul_f32_e32 v189, 0x4b800000, v193
	v_cmp_gt_f32_e64 s[12:13], s74, v193
	v_mov_b32_e32 v234, v231
	v_pk_add_f32 v[208:209], v[208:209], v[224:225]
	v_cndmask_b32_e64 v189, v193, v189, s[12:13]
	v_rsq_f32_e32 v189, v189
	v_pk_add_f32 v[212:213], v[212:213], v[226:227]
	v_pk_add_f32 v[196:197], v[196:197], v[232:233]
	v_pk_add_f32 v[194:195], v[206:207], v[234:235]
	v_mul_f32_e32 v191, 0x45800000, v189
	v_cndmask_b32_e64 v220, v189, v191, s[12:13]
	v_pk_add_f32 v[208:209], v[208:209], v[212:213]
	v_pk_add_f32 v[194:195], v[196:197], v[194:195]
	v_pk_mul_f32 v[156:157], v[156:157], v[220:221] op_sel_hi:[1,0]
	v_mov_b32_e32 v216, 0
	v_mov_b32_e32 v218, 0
	v_mov_b32_e32 v196, v194
	v_mov_b32_e32 v197, v208
	v_mov_b32_e32 v208, v195
	v_mov_b32_dpp v216, v156 row_ror:1 row_mask:0xf bank_mask:0xf
	v_mov_b32_dpp v218, v157 row_ror:1 row_mask:0xf bank_mask:0xf
	v_pk_add_f32 v[194:195], v[196:197], v[208:209]
	v_cndmask_b32_e64 v207, v218, 0, s[0:1]
	v_cndmask_b32_e64 v206, v216, 0, s[0:1]
	v_pk_mul_f32 v[158:159], v[158:159], v[220:221] op_sel_hi:[1,0]
	v_mov_b32_e32 v212, 0
	v_mov_b32_e32 v214, 0
	ds_bpermute_b32 v197, v187, v195
	ds_bpermute_b32 v196, v187, v194
	v_mov_b32_e32 v215, 0
	v_mov_b32_e32 v217, 0
	v_pk_mul_f32 v[206:207], v[88:89], v[206:207]
	v_mov_b32_dpp v212, v158 row_ror:1 row_mask:0xf bank_mask:0xf
	v_mov_b32_dpp v214, v159 row_ror:1 row_mask:0xf bank_mask:0xf
	v_mov_b32_dpp v215, v156 row_ror:2 row_mask:0xf bank_mask:0xf
	v_mov_b32_dpp v217, v157 row_ror:2 row_mask:0xf bank_mask:0xf
	v_pk_fma_f32 v[156:157], v[92:93], v[156:157], v[206:207]
	v_mov_b32_e32 v213, 0
	v_cndmask_b32_e64 v207, v214, 0, s[0:1]
	v_cndmask_b32_e64 v206, v212, 0, s[0:1]
	v_cndmask_b32_e64 v209, v217, 0, s[4:5]
	v_cndmask_b32_e64 v208, v215, 0, s[4:5]
	v_mov_b32_dpp v211, v158 row_ror:2 row_mask:0xf bank_mask:0xf
	v_mov_b32_dpp v213, v159 row_ror:2 row_mask:0xf bank_mask:0xf
	v_pk_mul_f32 v[206:207], v[90:91], v[206:207]
	v_pk_fma_f32 v[156:157], v[80:81], v[208:209], v[156:157]
	v_cndmask_b32_e64 v209, v213, 0, s[4:5]
	v_cndmask_b32_e64 v208, v211, 0, s[4:5]
	v_pk_fma_f32 v[158:159], v[94:95], v[158:159], v[206:207]
	v_pk_mul_f32 v[144:145], v[144:145], v[220:221] op_sel_hi:[1,0]
	v_pk_fma_f32 v[158:159], v[82:83], v[208:209], v[158:159]
	v_mov_b32_e32 v207, 0
	v_mov_b32_e32 v209, 0
	v_pk_mul_f32 v[146:147], v[146:147], v[220:221] op_sel_hi:[1,0]
	v_mov_b32_e32 v191, 0
	s_waitcnt lgkmcnt(0)
	v_pk_add_f32 v[194:195], v[194:195], v[196:197]
	v_mov_b32_dpp v207, v144 row_ror:1 row_mask:0xf bank_mask:0xf
	v_mov_b32_dpp v209, v145 row_ror:1 row_mask:0xf bank_mask:0xf
	v_mov_b32_dpp v191, v146 row_ror:1 row_mask:0xf bank_mask:0xf
	v_mov_b32_dpp v205, v147 row_ror:1 row_mask:0xf bank_mask:0xf
	ds_bpermute_b32 v197, v185, v195
	ds_bpermute_b32 v196, v185, v194
	v_pk_mul_f32 v[152:153], v[152:153], v[220:221] op_sel_hi:[1,0]
	v_pk_mul_f32 v[148:149], v[148:149], v[220:221] op_sel_hi:[1,0]
	v_pk_mul_f32 v[154:155], v[154:155], v[220:221] op_sel_hi:[1,0]
	v_pk_mul_f32 v[150:151], v[150:151], v[220:221] op_sel_hi:[1,0]
	v_mov_b32_e32 v206, 0
	v_mov_b32_e32 v208, 0
	v_cndmask_b32_e64 v223, v209, 0, s[0:1]
	v_cndmask_b32_e64 v222, v207, 0, s[0:1]
	v_mov_b32_e32 v189, 0
	v_mov_b32_e32 v193, 0
	v_cndmask_b32_e64 v221, v205, 0, s[0:1]
	v_cndmask_b32_e64 v220, v191, 0, s[0:1]
	v_mov_b32_dpp v206, v144 row_ror:2 row_mask:0xf bank_mask:0xf
	v_mov_b32_dpp v208, v145 row_ror:2 row_mask:0xf bank_mask:0xf
	v_pk_mul_f32 v[222:223], v[72:73], v[222:223]
	v_mov_b32_dpp v189, v146 row_ror:2 row_mask:0xf bank_mask:0xf
	v_mov_b32_dpp v193, v147 row_ror:2 row_mask:0xf bank_mask:0xf
	v_pk_mul_f32 v[220:221], v[74:75], v[220:221]
	v_cndmask_b32_e64 v225, v208, 0, s[4:5]
	v_cndmask_b32_e64 v224, v206, 0, s[4:5]
	v_pk_fma_f32 v[144:145], v[76:77], v[144:145], v[222:223]
	v_cndmask_b32_e64 v223, v193, 0, s[4:5]
	v_cndmask_b32_e64 v222, v189, 0, s[4:5]
	v_pk_fma_f32 v[146:147], v[78:79], v[146:147], v[220:221]
	v_pk_fma_f32 v[144:145], v[64:65], v[224:225], v[144:145]
	v_pk_fma_f32 v[146:147], v[66:67], v[222:223], v[146:147]
	v_cmp_gt_f32_e32 vcc, s74, v192
	v_pk_add_f32 v[156:157], v[84:85], v[156:157]
	v_pk_add_f32 v[158:159], v[86:87], v[158:159]
	v_pk_add_f32 v[144:145], v[68:69], v[144:145]
	v_pk_add_f32 v[146:147], v[70:71], v[146:147]
	s_and_saveexec_b64 s[12:13], s[10:11]
	s_xor_b64 s[12:13], exec, s[12:13]
	s_cbranch_execz .LBB0_1280
	v_mul_f32_e32 v219, 0xbfb8aa3b, v156
	v_exp_f32_e32 v219, v219
	v_mul_f32_e32 v220, 0xbfb8aa3b, v157
	v_exp_f32_e32 v220, v220
	v_mul_f32_e32 v222, 0xbfb8aa3b, v159
	v_add_f32_e32 v219, 1.0, v219
	v_exp_f32_e32 v223, v222
	v_add_f32_e32 v221, 1.0, v220
	v_rcp_f32_e32 v220, v219
	v_mul_f32_e32 v219, 0xbfb8aa3b, v158
	v_exp_f32_e32 v219, v219
	v_rcp_f32_e32 v221, v221
	v_add_f32_e32 v219, 1.0, v219
	v_rcp_f32_e32 v222, v219
	v_add_f32_e32 v219, 1.0, v223
	v_rcp_f32_e32 v223, v219
	v_pk_mul_f32 v[156:157], v[156:157], v[220:221]
	s_nop 0
	v_pk_mul_f32 v[152:153], v[152:153], v[156:157]
	v_pk_mul_f32 v[156:157], v[158:159], v[222:223]
	v_cvt_pk_bf16_f32 v152, v152, v153
	v_mul_f32_e32 v153, 0xbfb8aa3b, v144
	v_pk_mul_f32 v[154:155], v[154:155], v[156:157]
	v_exp_f32_e32 v156, v153
	v_mul_f32_e32 v153, 0xbfb8aa3b, v145
	v_exp_f32_e32 v157, v153
	v_cvt_pk_bf16_f32 v153, v154, v155
	v_add_f32_e32 v154, 1.0, v156
	v_mul_f32_e32 v156, 0xbfb8aa3b, v146
	v_add_f32_e32 v155, 1.0, v157
	v_mul_f32_e32 v157, 0xbfb8aa3b, v147
	v_exp_f32_e32 v156, v156
	v_exp_f32_e32 v157, v157
	v_rcp_f32_e32 v154, v154
	v_rcp_f32_e32 v155, v155
	v_add_f32_e32 v156, 1.0, v156
	v_add_f32_e32 v157, 1.0, v157
	v_rcp_f32_e32 v156, v156
	v_rcp_f32_e32 v157, v157
	v_pk_mul_f32 v[144:145], v[144:145], v[154:155]
	s_nop 0
	v_pk_mul_f32 v[144:145], v[148:149], v[144:145]
	s_nop 0
	v_cvt_pk_bf16_f32 v154, v144, v145
	v_pk_mul_f32 v[144:145], v[146:147], v[156:157]
	s_nop 0
	v_pk_mul_f32 v[144:145], v[150:151], v[144:145]
	s_nop 0
	v_cvt_pk_bf16_f32 v155, v144, v145
	v_mov_b64_e32 v[144:145], s[20:21]
	v_mad_i64_i32 v[144:145], s[14:15], v190, s75, v[144:145]
	v_lshl_add_u64 v[144:145], v[180:181], 1, v[144:145]
	global_store_dwordx4 v[144:145], v[152:155], off

; #define PG8_STAGE(bufoff, gbase, voff) do { _Pragma("unroll") for (int _i = 0; _i < 2; ++_i) \
;     __builtin_amdgcn_global_load_lds((const unsigned*)((const char*)(gbase) + (voff)[_i]), (LAS unsigned*)(lds + (bufoff) + ldsw + _i * 8192), 16, 0, 0); } while (0)
; #define PG8_LDA(dst, b, h) do { _Pragma("unroll") for (int m = 0; m < 4; ++m) _Pragma("unroll") for (int k = 0; k < 2; ++k) dst[m][k] = *(const LAS bf16x8*)(lds + PG8_SA(b, h) + aoff + m * 2048 + k * 1024); } while (0)
; #define PG8_LDB(dst, b, h) do { _Pragma("unroll") for (int n = 0; n < 2; ++n) _Pragma("unroll") for (int k = 0; k < 2; ++k) dst[n][k] = *(const LAS bf16x8*)(lds + PG8_SB(b, h) + boff + n * 2048 + k * 1024); } while (0)
; #define PG8_MMA(ai, bj, At, Bt) do { __builtin_amdgcn_s_setprio(1); _Pragma("unroll") for (int m = 0; m < 4; ++m) _Pragma("unroll") for (int n = 0; n < 2; ++n) _Pragma("unroll") for (int k = 0; k < 2; ++k) \
;     acc[ai][bj][m][n] = __builtin_amdgcn_mfma_f32_16x16x32_bf16(Bt[n][k], At[m][k], acc[ai][bj][m][n], 0, 0, 0); __builtin_amdgcn_s_setprio(0); } while (0)
; #define PG8_WAIT_V(n) asm volatile("s_waitcnt vmcnt(" #n ")" ::: "memory")
; #define PG8_WAIT_L(n) asm volatile("s_waitcnt lgkmcnt(" #n ")" ::: "memory")
; #define PG8_BAR __builtin_amdgcn_s_barrier()
; #define PG8_SCHED __builtin_amdgcn_sched_barrier(0)
; template <class Epi, class Sched = StaticOrder>
; DI void gemm_phase(LAS unsigned char* lds, const Gemm g, const Sched& S, const Epi& E) {
;     ...
;       PG8_LDB(B0, 0, 0); PG8_SCHED; PG8_LDA(At, 0, 0); PG8_STAGE(PG8_SA(1, 1), a1 + hstep, voffA);
;       PG8_WAIT_L(8); PG8_BAR; PG8_WAIT_L(0); PG8_MMA(0, 0, At, B0); PG8_BAR; PG8_SCHED;
;       PG8_LDB(B1, 0, 1); PG8_STAGE(PG8_SB(0, 0), b2, voffB);
;       PG8_BAR; PG8_WAIT_L(0); PG8_MMA(0, 1, At, B1); PG8_BAR;
;       PG8_LDA(At, 0, 1); PG8_STAGE(PG8_SA(0, 0), a2, voffA);
;       PG8_BAR; PG8_WAIT_L(0); PG8_MMA(1, 0, At, B0); PG8_BAR; PG8_SCHED;
;       PG8_STAGE(PG8_SB(0, 1), b2 + hstep, voffB);
;       PG8_WAIT_V(6); PG8_BAR; PG8_MMA(1, 1, At, B1); PG8_BAR;
;       PG8_LDB(B0, 1, 0); PG8_SCHED; PG8_LDA(At, 1, 0); PG8_STAGE(PG8_SA(0, 1), a2 + hstep, voffA);
.LBB0_1424:
	s_add_u32 s18, s16, 0xffea0080
	s_addc_u32 s19, s17, -1
	s_cmpk_eq_i32 s47, 0x54
	s_cselect_b32 s21, s3, s19
	s_cselect_b32 s20, s2, s18
	s_cselect_b32 s19, s5, s46
	s_cselect_b32 s18, s4, s45
	s_add_i32 m0, s30, 0xc000
	ds_read_b128 v[166:169], v160
	ds_read_b128 v[170:173], v160 offset:1024
	ds_read_b128 v[174:177], v160 offset:2048
	ds_read_b128 v[178:181], v160 offset:3072
	ds_read_b128 v[182:185], v160 offset:4096
	ds_read_b128 v[186:189], v160 offset:5120
	ds_read_b128 v[190:193], v160 offset:6144
	ds_read_b128 v[194:197], v160 offset:7168
	global_load_lds_dwordx4 v136, s[16:17]
	s_add_i32 m0, s30, 0xe000
	s_nop 0
	global_load_lds_dwordx4 v138, s[16:17]
	s_waitcnt lgkmcnt(0)
	s_setprio 1
	s_barrier
	v_mfma_f32_16x16x32_bf16 v[124:127], v[144:147], v[166:169], v[124:127]
	v_mfma_f32_16x16x32_bf16 v[120:123], v[152:155], v[166:169], v[120:123]
	v_mfma_f32_16x16x32_bf16 v[116:119], v[144:147], v[174:177], v[116:119]
	v_mfma_f32_16x16x32_bf16 v[112:115], v[152:155], v[174:177], v[112:115]
	v_mfma_f32_16x16x32_bf16 v[104:107], v[144:147], v[182:185], v[104:107]
	v_mfma_f32_16x16x32_bf16 v[96:99], v[152:155], v[182:185], v[96:99]
	v_mfma_f32_16x16x32_bf16 v[88:91], v[144:147], v[190:193], v[88:91]
	v_mfma_f32_16x16x32_bf16 v[80:83], v[152:155], v[190:193], v[80:83]
	v_mfma_f32_16x16x32_bf16 v[124:127], v[148:151], v[170:173], v[124:127]
	v_mfma_f32_16x16x32_bf16 v[120:123], v[162:165], v[170:173], v[120:123]
	v_mfma_f32_16x16x32_bf16 v[116:119], v[148:151], v[178:181], v[116:119]
	v_mfma_f32_16x16x32_bf16 v[112:115], v[162:165], v[178:181], v[112:115]
	v_mfma_f32_16x16x32_bf16 v[104:107], v[148:151], v[186:189], v[104:107]
	v_mfma_f32_16x16x32_bf16 v[96:99], v[162:165], v[186:189], v[96:99]
	v_mfma_f32_16x16x32_bf16 v[88:91], v[148:151], v[194:197], v[88:91]
	v_mfma_f32_16x16x32_bf16 v[80:83], v[162:165], v[194:197], v[80:83]
	s_barrier
	s_setprio 0
	s_add_i32 s48, s39, s28
	s_add_u32 s98, s18, 0x80
	s_addc_u32 s99, s19, 0
	s_mov_b32 m0, s48
	ds_read_b128 v[198:201], v161
	ds_read_b128 v[202:205], v161 offset:1024
	ds_read_b128 v[206:209], v161 offset:2048
	ds_read_b128 v[210:213], v161 offset:3072
	global_load_lds_dwordx4 v132, s[18:19]
	s_add_i32 m0, s48, 0x2000
	s_nop 0
	global_load_lds_dwordx4 v128, s[18:19]
	s_waitcnt lgkmcnt(0)
	s_setprio 1
	s_barrier
	v_mfma_f32_16x16x32_bf16 v[108:111], v[198:201], v[166:169], v[108:111]
	v_mfma_f32_16x16x32_bf16 v[100:103], v[206:209], v[166:169], v[100:103]
	v_mfma_f32_16x16x32_bf16 v[92:95], v[198:201], v[174:177], v[92:95]
	v_mfma_f32_16x16x32_bf16 v[84:87], v[206:209], v[174:177], v[84:87]
	v_mfma_f32_16x16x32_bf16 v[76:79], v[198:201], v[182:185], v[76:79]
	v_mfma_f32_16x16x32_bf16 v[72:75], v[206:209], v[182:185], v[72:75]
	v_mfma_f32_16x16x32_bf16 v[68:71], v[198:201], v[190:193], v[68:71]
	v_mfma_f32_16x16x32_bf16 v[64:67], v[206:209], v[190:193], v[64:67]
	v_mfma_f32_16x16x32_bf16 v[108:111], v[202:205], v[170:173], v[108:111]
	v_mfma_f32_16x16x32_bf16 v[100:103], v[210:213], v[170:173], v[100:103]
	v_mfma_f32_16x16x32_bf16 v[92:95], v[202:205], v[178:181], v[92:95]
	v_mfma_f32_16x16x32_bf16 v[84:87], v[210:213], v[178:181], v[84:87]
	v_mfma_f32_16x16x32_bf16 v[76:79], v[202:205], v[186:189], v[76:79]
	v_mfma_f32_16x16x32_bf16 v[72:75], v[210:213], v[186:189], v[72:75]
	v_mfma_f32_16x16x32_bf16 v[68:71], v[202:205], v[194:197], v[68:71]
	v_mfma_f32_16x16x32_bf16 v[64:67], v[210:213], v[194:197], v[64:67]
	s_barrier
	s_setprio 0
	s_mov_b32 m0, s30
	s_add_u32 s100, s20, 0x80
	s_addc_u32 s101, s21, 0
	ds_read_b128 v[166:169], v160 offset:16384
	ds_read_b128 v[170:173], v160 offset:17408
	ds_read_b128 v[174:177], v160 offset:18432
	ds_read_b128 v[178:181], v160 offset:19456
	ds_read_b128 v[182:185], v160 offset:20480
	ds_read_b128 v[186:189], v160 offset:21504
	ds_read_b128 v[190:193], v160 offset:22528
	ds_read_b128 v[194:197], v160 offset:23552
	global_load_lds_dwordx4 v134, s[20:21]
	s_mov_b32 m0, s31
	s_nop 0
	global_load_lds_dwordx4 v130, s[20:21]
	s_waitcnt vmcnt(10)
	s_waitcnt lgkmcnt(0)
	s_setprio 1
	s_barrier
	v_mfma_f32_16x16x32_bf16 v[60:63], v[144:147], v[166:169], v[60:63]
	v_mfma_f32_16x16x32_bf16 v[56:59], v[152:155], v[166:169], v[56:59]
	v_mfma_f32_16x16x32_bf16 v[52:55], v[144:147], v[174:177], v[52:55]
	v_mfma_f32_16x16x32_bf16 v[44:47], v[152:155], v[174:177], v[44:47]
	v_mfma_f32_16x16x32_bf16 v[36:39], v[144:147], v[182:185], v[36:39]
	v_mfma_f32_16x16x32_bf16 v[28:31], v[152:155], v[182:185], v[28:31]
	v_mfma_f32_16x16x32_bf16 v[20:23], v[144:147], v[190:193], v[20:23]
	v_mfma_f32_16x16x32_bf16 v[12:15], v[152:155], v[190:193], v[12:15]
	v_mfma_f32_16x16x32_bf16 v[60:63], v[148:151], v[170:173], v[60:63]
	v_mfma_f32_16x16x32_bf16 v[56:59], v[162:165], v[170:173], v[56:59]
	v_mfma_f32_16x16x32_bf16 v[52:55], v[148:151], v[178:181], v[52:55]
	v_mfma_f32_16x16x32_bf16 v[44:47], v[162:165], v[178:181], v[44:47]
	v_mfma_f32_16x16x32_bf16 v[36:39], v[148:151], v[186:189], v[36:39]
	v_mfma_f32_16x16x32_bf16 v[28:31], v[162:165], v[186:189], v[28:31]
	v_mfma_f32_16x16x32_bf16 v[20:23], v[148:151], v[194:197], v[20:23]
	v_mfma_f32_16x16x32_bf16 v[12:15], v[162:165], v[194:197], v[12:15]
	s_barrier
	s_setprio 0
	s_add_u32 s48, s18, 0x160000
	s_addc_u32 s49, s19, 0
	s_add_i32 s50, s40, s28
	s_mov_b32 m0, s50
	s_nop 0
	global_load_lds_dwordx4 v132, s[48:49]
	s_add_i32 m0, s50, 0x2000
	s_nop 0
	global_load_lds_dwordx4 v128, s[48:49]
	s_add_i32 s48, 0, 0x18000
	v_add_u32_e32 v162, s48, v157
	ds_read_b128 v[144:147], v162
	ds_read_b128 v[148:151], v162 offset:1024
	ds_read_b128 v[152:155], v162 offset:2048
	ds_read_b128 v[162:165], v162 offset:3072
	s_waitcnt vmcnt(6)
	s_setprio 1
	s_barrier
; #define PG8_STAGE(bufoff, gbase, voff) do { _Pragma("unroll") for (int _i = 0; _i < 2; ++_i) \
;     __builtin_amdgcn_global_load_lds((const unsigned*)((const char*)(gbase) + (voff)[_i]), (LAS unsigned*)(lds + (bufoff) + ldsw + _i * 8192), 16, 0, 0); } while (0)
; #define PG8_LDA(dst, b, h) do { _Pragma("unroll") for (int m = 0; m < 4; ++m) _Pragma("unroll") for (int k = 0; k < 2; ++k) dst[m][k] = *(const LAS bf16x8*)(lds + PG8_SA(b, h) + aoff + m * 2048 + k * 1024); } while (0)
; #define PG8_LDB(dst, b, h) do { _Pragma("unroll") for (int n = 0; n < 2; ++n) _Pragma("unroll") for (int k = 0; k < 2; ++k) dst[n][k] = *(const LAS bf16x8*)(lds + PG8_SB(b, h) + boff + n * 2048 + k * 1024); } while (0)
; #define PG8_MMA(ai, bj, At, Bt) do { __builtin_amdgcn_s_setprio(1); _Pragma("unroll") for (int m = 0; m < 4; ++m) _Pragma("unroll") for (int n = 0; n < 2; ++n) _Pragma("unroll") for (int k = 0; k < 2; ++k) \
;     acc[ai][bj][m][n] = __builtin_amdgcn_mfma_f32_16x16x32_bf16(Bt[n][k], At[m][k], acc[ai][bj][m][n], 0, 0, 0); __builtin_amdgcn_s_setprio(0); } while (0)
; #define PG8_WAIT_V(n) asm volatile("s_waitcnt vmcnt(" #n ")" ::: "memory")
; #define PG8_WAIT_L(n) asm volatile("s_waitcnt lgkmcnt(" #n ")" ::: "memory")
; #define PG8_BAR __builtin_amdgcn_s_barrier()
; #define PG8_SCHED __builtin_amdgcn_sched_barrier(0)
; template <class Epi, class Sched = StaticOrder>
; DI void gemm_phase(LAS unsigned char* lds, const Gemm g, const Sched& S, const Epi& E) {
;     ...
;       PG8_WAIT_V(6); PG8_BAR; PG8_MMA(1, 1, At, B1); PG8_BAR;
;       PG8_LDB(B0, 1, 0); PG8_SCHED; PG8_LDA(At, 1, 0); PG8_STAGE(PG8_SA(0, 1), a2 + hstep, voffA);
;       PG8_WAIT_L(8); PG8_BAR; PG8_WAIT_L(0); PG8_MMA(0, 0, At, B0); PG8_BAR; PG8_SCHED;
;       PG8_LDB(B1, 1, 1); PG8_STAGE(PG8_SB(1, 0), b3, voffB);
;       PG8_BAR; PG8_WAIT_L(0); PG8_MMA(0, 1, At, B1); PG8_BAR;
;       PG8_LDA(At, 1, 1); PG8_STAGE(PG8_SA(1, 0), a3, voffA);
;       PG8_BAR; PG8_WAIT_L(0); PG8_MMA(1, 0, At, B0); PG8_BAR; PG8_SCHED;
	v_mfma_f32_16x16x32_bf16 v[48:51], v[198:201], v[166:169], v[48:51]
	v_mfma_f32_16x16x32_bf16 v[40:43], v[206:209], v[166:169], v[40:43]
	v_mfma_f32_16x16x32_bf16 v[32:35], v[198:201], v[174:177], v[32:35]
	v_mfma_f32_16x16x32_bf16 v[24:27], v[206:209], v[174:177], v[24:27]
	v_mfma_f32_16x16x32_bf16 v[16:19], v[198:201], v[182:185], v[16:19]
	v_mfma_f32_16x16x32_bf16 v[8:11], v[206:209], v[182:185], v[8:11]
	v_mfma_f32_16x16x32_bf16 v[4:7], v[198:201], v[190:193], v[4:7]
	v_mfma_f32_16x16x32_bf16 v[0:3], v[206:209], v[190:193], v[0:3]
	v_mfma_f32_16x16x32_bf16 v[48:51], v[202:205], v[170:173], v[48:51]
	v_mfma_f32_16x16x32_bf16 v[40:43], v[210:213], v[170:173], v[40:43]
	v_mfma_f32_16x16x32_bf16 v[32:35], v[202:205], v[178:181], v[32:35]
	v_mfma_f32_16x16x32_bf16 v[24:27], v[210:213], v[178:181], v[24:27]
	v_mfma_f32_16x16x32_bf16 v[16:19], v[202:205], v[186:189], v[16:19]
	v_mfma_f32_16x16x32_bf16 v[8:11], v[210:213], v[186:189], v[8:11]
	v_mfma_f32_16x16x32_bf16 v[4:7], v[202:205], v[194:197], v[4:7]
	v_mfma_f32_16x16x32_bf16 v[0:3], v[210:213], v[194:197], v[0:3]
	s_barrier
	s_setprio 0
	s_add_u32 s20, s20, 0x160000
	s_addc_u32 s21, s21, 0
	s_mov_b32 m0, s33
	ds_read_b128 v[166:169], v160 offset:32768
	ds_read_b128 v[170:173], v160 offset:33792
	ds_read_b128 v[174:177], v160 offset:34816
	ds_read_b128 v[178:181], v160 offset:35840
	ds_read_b128 v[182:185], v160 offset:36864
	ds_read_b128 v[186:189], v160 offset:37888
	ds_read_b128 v[190:193], v160 offset:38912
	ds_read_b128 v[194:197], v160 offset:39936
	global_load_lds_dwordx4 v134, s[20:21]
	s_mov_b32 m0, s34
	s_nop 0
	global_load_lds_dwordx4 v130, s[20:21]
	s_waitcnt lgkmcnt(0)
	s_setprio 1
	s_barrier
	v_mfma_f32_16x16x32_bf16 v[124:127], v[144:147], v[166:169], v[124:127]
	v_mfma_f32_16x16x32_bf16 v[120:123], v[152:155], v[166:169], v[120:123]
	v_mfma_f32_16x16x32_bf16 v[116:119], v[144:147], v[174:177], v[116:119]
	v_mfma_f32_16x16x32_bf16 v[112:115], v[152:155], v[174:177], v[112:115]
	v_mfma_f32_16x16x32_bf16 v[104:107], v[144:147], v[182:185], v[104:107]
	v_mfma_f32_16x16x32_bf16 v[96:99], v[152:155], v[182:185], v[96:99]
	v_mfma_f32_16x16x32_bf16 v[88:91], v[144:147], v[190:193], v[88:91]
	v_mfma_f32_16x16x32_bf16 v[80:83], v[152:155], v[190:193], v[80:83]
	v_mfma_f32_16x16x32_bf16 v[124:127], v[148:151], v[170:173], v[124:127]
	v_mfma_f32_16x16x32_bf16 v[120:123], v[162:165], v[170:173], v[120:123]
	v_mfma_f32_16x16x32_bf16 v[116:119], v[148:151], v[178:181], v[116:119]
	v_mfma_f32_16x16x32_bf16 v[112:115], v[162:165], v[178:181], v[112:115]
	v_mfma_f32_16x16x32_bf16 v[104:107], v[148:151], v[186:189], v[104:107]
	v_mfma_f32_16x16x32_bf16 v[96:99], v[162:165], v[186:189], v[96:99]
	v_mfma_f32_16x16x32_bf16 v[88:91], v[148:151], v[194:197], v[88:91]
	v_mfma_f32_16x16x32_bf16 v[80:83], v[162:165], v[194:197], v[80:83]
	s_barrier
	s_setprio 0
	s_add_i32 s20, 0, 0x1c000
	s_add_i32 s21, s48, s28
	v_add_u32_e32 v210, s20, v157
	s_mov_b32 m0, s21
	ds_read_b128 v[198:201], v210
	ds_read_b128 v[202:205], v210 offset:1024
	ds_read_b128 v[206:209], v210 offset:2048
	ds_read_b128 v[210:213], v210 offset:3072
	global_load_lds_dwordx4 v132, s[98:99]
	s_add_i32 m0, s21, 0x2000
	s_nop 0
	global_load_lds_dwordx4 v128, s[98:99]
	s_waitcnt lgkmcnt(0)
	s_setprio 1
	s_barrier
	v_mfma_f32_16x16x32_bf16 v[108:111], v[198:201], v[166:169], v[108:111]
	v_mfma_f32_16x16x32_bf16 v[100:103], v[206:209], v[166:169], v[100:103]
	v_mfma_f32_16x16x32_bf16 v[92:95], v[198:201], v[174:177], v[92:95]
	v_mfma_f32_16x16x32_bf16 v[84:87], v[206:209], v[174:177], v[84:87]
	v_mfma_f32_16x16x32_bf16 v[76:79], v[198:201], v[182:185], v[76:79]
	v_mfma_f32_16x16x32_bf16 v[72:75], v[206:209], v[182:185], v[72:75]
	v_mfma_f32_16x16x32_bf16 v[68:71], v[198:201], v[190:193], v[68:71]
	v_mfma_f32_16x16x32_bf16 v[64:67], v[206:209], v[190:193], v[64:67]
	v_mfma_f32_16x16x32_bf16 v[108:111], v[202:205], v[170:173], v[108:111]
	v_mfma_f32_16x16x32_bf16 v[100:103], v[210:213], v[170:173], v[100:103]
	v_mfma_f32_16x16x32_bf16 v[92:95], v[202:205], v[178:181], v[92:95]
	v_mfma_f32_16x16x32_bf16 v[84:87], v[210:213], v[178:181], v[84:87]
	v_mfma_f32_16x16x32_bf16 v[76:79], v[202:205], v[186:189], v[76:79]
	v_mfma_f32_16x16x32_bf16 v[72:75], v[210:213], v[186:189], v[72:75]
	v_mfma_f32_16x16x32_bf16 v[68:71], v[202:205], v[194:197], v[68:71]
	v_mfma_f32_16x16x32_bf16 v[64:67], v[210:213], v[194:197], v[64:67]
	s_barrier
	s_setprio 0
	s_mov_b32 m0, s35
	ds_read_b128 v[166:169], v160 offset:49152
	ds_read_b128 v[170:173], v160 offset:50176
	ds_read_b128 v[174:177], v160 offset:51200
	ds_read_b128 v[178:181], v160 offset:52224
	ds_read_b128 v[182:185], v160 offset:53248
	ds_read_b128 v[186:189], v160 offset:54272
	ds_read_b128 v[190:193], v160 offset:55296
	ds_read_b128 v[194:197], v160 offset:56320
	global_load_lds_dwordx4 v134, s[100:101]
	s_mov_b32 m0, s36
	s_nop 0
	global_load_lds_dwordx4 v130, s[100:101]
	s_waitcnt vmcnt(10)
	s_waitcnt lgkmcnt(0)
	s_setprio 1
	s_barrier
	v_mfma_f32_16x16x32_bf16 v[60:63], v[144:147], v[166:169], v[60:63]
	v_mfma_f32_16x16x32_bf16 v[56:59], v[152:155], v[166:169], v[56:59]
	v_mfma_f32_16x16x32_bf16 v[52:55], v[144:147], v[174:177], v[52:55]
	v_mfma_f32_16x16x32_bf16 v[44:47], v[152:155], v[174:177], v[44:47]
	v_mfma_f32_16x16x32_bf16 v[36:39], v[144:147], v[182:185], v[36:39]
	v_mfma_f32_16x16x32_bf16 v[28:31], v[152:155], v[182:185], v[28:31]
	v_mfma_f32_16x16x32_bf16 v[20:23], v[144:147], v[190:193], v[20:23]
	v_mfma_f32_16x16x32_bf16 v[12:15], v[152:155], v[190:193], v[12:15]
	v_mfma_f32_16x16x32_bf16 v[60:63], v[148:151], v[170:173], v[60:63]
	v_mfma_f32_16x16x32_bf16 v[56:59], v[162:165], v[170:173], v[56:59]
	v_mfma_f32_16x16x32_bf16 v[52:55], v[148:151], v[178:181], v[52:55]
	v_mfma_f32_16x16x32_bf16 v[44:47], v[162:165], v[178:181], v[44:47]
	v_mfma_f32_16x16x32_bf16 v[36:39], v[148:151], v[186:189], v[36:39]
	v_mfma_f32_16x16x32_bf16 v[28:31], v[162:165], v[186:189], v[28:31]
	v_mfma_f32_16x16x32_bf16 v[20:23], v[148:151], v[194:197], v[20:23]
	v_mfma_f32_16x16x32_bf16 v[12:15], v[162:165], v[194:197], v[12:15]
	s_barrier
; #define PG8_STAGE(bufoff, gbase, voff) do { _Pragma("unroll") for (int _i = 0; _i < 2; ++_i) \
;     __builtin_amdgcn_global_load_lds((const unsigned*)((const char*)(gbase) + (voff)[_i]), (LAS unsigned*)(lds + (bufoff) + ldsw + _i * 8192), 16, 0, 0); } while (0)
; #define PG8_MMA(ai, bj, At, Bt) do { __builtin_amdgcn_s_setprio(1); _Pragma("unroll") for (int m = 0; m < 4; ++m) _Pragma("unroll") for (int n = 0; n < 2; ++n) _Pragma("unroll") for (int k = 0; k < 2; ++k) \
;     acc[ai][bj][m][n] = __builtin_amdgcn_mfma_f32_16x16x32_bf16(Bt[n][k], At[m][k], acc[ai][bj][m][n], 0, 0, 0); __builtin_amdgcn_s_setprio(0); } while (0)
; #define PG8_WAIT_V(n) asm volatile("s_waitcnt vmcnt(" #n ")" ::: "memory")
; #define PG8_BAR __builtin_amdgcn_s_barrier()
;   DI void operator()(const f32x4 (&acc)[2][2][4][2], const Unit& u, int wr, int wc, int fr, int fq) const {
;     const int row0 = u.pm * BM + wr * 64 + fr, col0 = u.pn * BM + wc * 32 + 8 * fq;
; #pragma unroll
;     for (int ai = 0; ai < 2; ++ai) {
;       f32x4 bv[4][2][2];
; #pragma unroll
;       for (int m = 0; m < 4; ++m)
; #pragma unroll
;         for (int bj = 0; bj < 2; ++bj) {
;           const float* bp = base + (size_t)(row0 + ai * HALF + m * 16) * 2048 + col0 + bj * HALF;
;           bv[m][bj][0] = *(const f32x4*)bp; bv[m][bj][1] = *(const f32x4*)(bp + 4);
;         }
; template <class Epi, class Sched = StaticOrder>
; DI void gemm_phase(LAS unsigned char* lds, const Gemm g, const Sched& S, const Epi& E) {
;     ...
;       PG8_STAGE(PG8_SB(1, 1), b3 + hstep, voffB);
;       PG8_WAIT_V(6); PG8_BAR; PG8_MMA(1, 1, At, B1); PG8_BAR;
	s_setprio 0
	s_add_u32 s18, s18, 0x160080
	s_addc_u32 s19, s19, 0
	s_add_i32 s20, s20, s28
	s_mov_b32 m0, s20
	s_nop 0
	global_load_lds_dwordx4 v132, s[18:19]
	s_add_i32 m0, s20, 0x2000
	s_nop 0
	global_load_lds_dwordx4 v128, s[18:19]
	ds_read_b128 v[144:147], v159
	ds_read_b128 v[148:151], v159 offset:1024
	ds_read_b128 v[152:155], v159 offset:2048
	ds_read_b128 v[162:165], v159 offset:3072
	s_waitcnt vmcnt(6)
	s_add_i32 s47, s47, 2
	s_add_u32 s16, s16, 0x100
	s_addc_u32 s17, s17, 0
	s_add_u32 s45, s45, 0x100
	s_addc_u32 s46, s46, 0
	s_cmpk_gt_u32 s47, 0x55
	s_setprio 1
	s_barrier
	v_mfma_f32_16x16x32_bf16 v[48:51], v[198:201], v[166:169], v[48:51]
	v_mfma_f32_16x16x32_bf16 v[40:43], v[206:209], v[166:169], v[40:43]
	v_mfma_f32_16x16x32_bf16 v[32:35], v[198:201], v[174:177], v[32:35]
	v_mfma_f32_16x16x32_bf16 v[24:27], v[206:209], v[174:177], v[24:27]
	v_mfma_f32_16x16x32_bf16 v[16:19], v[198:201], v[182:185], v[16:19]
	v_mfma_f32_16x16x32_bf16 v[8:11], v[206:209], v[182:185], v[8:11]
	v_mfma_f32_16x16x32_bf16 v[4:7], v[198:201], v[190:193], v[4:7]
	v_mfma_f32_16x16x32_bf16 v[0:3], v[206:209], v[190:193], v[0:3]
	v_mfma_f32_16x16x32_bf16 v[48:51], v[202:205], v[170:173], v[48:51]
	v_mfma_f32_16x16x32_bf16 v[40:43], v[210:213], v[170:173], v[40:43]
	v_mfma_f32_16x16x32_bf16 v[32:35], v[202:205], v[178:181], v[32:35]
	v_mfma_f32_16x16x32_bf16 v[24:27], v[210:213], v[178:181], v[24:27]
	v_mfma_f32_16x16x32_bf16 v[16:19], v[202:205], v[186:189], v[16:19]
	v_mfma_f32_16x16x32_bf16 v[8:11], v[210:213], v[186:189], v[8:11]
	v_mfma_f32_16x16x32_bf16 v[4:7], v[202:205], v[194:197], v[4:7]
	v_mfma_f32_16x16x32_bf16 v[0:3], v[210:213], v[194:197], v[0:3]
	s_barrier
	s_setprio 0
	s_cbranch_scc0 .LBB0_1424
	s_waitcnt lgkmcnt(0)
	v_lshl_or_b32 v144, s44, 8, v158
	v_lshl_add_u32 v154, s43, 8, v156
	v_ashrrev_i32_e32 v145, 31, v144
	v_lshlrev_b64 v[144:145], 2, v[144:145]
	v_ashrrev_i32_e32 v155, 31, v154
	v_lshl_add_u64 v[146:147], s[54:55], 0, v[144:145]
	v_lshlrev_b64 v[148:149], 13, v[154:155]
	v_or_b32_e32 v174, 16, v154
	v_lshl_add_u64 v[170:171], v[146:147], 0, v[148:149]
	v_ashrrev_i32_e32 v175, 31, v174
	global_load_dwordx4 v[150:153], v[170:171], off offset:16
	global_load_dwordx4 v[162:165], v[170:171], off
	global_load_dwordx4 v[166:169], v[170:171], off offset:528
	s_nop 0
	global_load_dwordx4 v[170:173], v[170:171], off offset:512
	v_lshlrev_b64 v[222:223], 13, v[174:175]
	v_or_b32_e32 v190, 32, v154
	v_lshl_add_u64 v[186:187], v[146:147], 0, v[222:223]
	v_ashrrev_i32_e32 v191, 31, v190
	global_load_dwordx4 v[174:177], v[186:187], off offset:16
	global_load_dwordx4 v[178:181], v[186:187], off
	global_load_dwordx4 v[182:185], v[186:187], off offset:528
	s_nop 0
	global_load_dwordx4 v[186:189], v[186:187], off offset:512
	v_lshlrev_b64 v[224:225], 13, v[190:191]
	v_or_b32_e32 v154, 48, v154
	v_lshl_add_u64 v[202:203], v[146:147], 0, v[224:225]
	v_ashrrev_i32_e32 v155, 31, v154
	global_load_dwordx4 v[190:193], v[202:203], off offset:16
	global_load_dwordx4 v[194:197], v[202:203], off
	global_load_dwordx4 v[198:201], v[202:203], off offset:528
	s_nop 0
	global_load_dwordx4 v[202:205], v[202:203], off offset:512
	v_lshlrev_b64 v[154:155], 13, v[154:155]
	v_lshl_add_u64 v[218:219], v[146:147], 0, v[154:155]
	global_load_dwordx4 v[206:209], v[218:219], off offset:16
	global_load_dwordx4 v[210:213], v[218:219], off
	global_load_dwordx4 v[214:217], v[218:219], off offset:528
	s_nop 0
	global_load_dwordx4 v[218:221], v[218:219], off offset:512
	s_and_b64 vcc, exec, s[0:1]
	s_mov_b32 s44, s41
	s_mov_b32 s43, s42
	s_mov_b64 s[18:19], s[4:5]
	s_mov_b64 s[16:17], s[2:3]
	s_waitcnt vmcnt(0)
; #define PG8_WAIT_V(n) asm volatile("s_waitcnt vmcnt(" #n ")" ::: "memory")
; #define PG8_BAR __builtin_amdgcn_s_barrier()
;   DI void operator()(const f32x4 (&acc)[2][2][4][2], const Unit& u, int wr, int wc, int fr, int fq) const {
;     ...
; #pragma unroll
;       for (int m = 0; m < 4; ++m) {
;         const int row = row0 + ai * HALF + m * 16;
;         const size_t off = (size_t)row * 2048 + col0;
;         float ss = 0.f;
; #pragma unroll
;         for (int bj = 0; bj < 2; ++bj) {
;           const f32x4 v0 = acc[ai][bj][m][0] + bv[m][bj][0], v1 = acc[ai][bj][m][1] + bv[m][bj][1];
;           *(f32x4*)(C + off + bj * HALF) = v0; *(f32x4*)(C + off + bj * HALF + 4) = v1;
; template <class Epi, class Sched = StaticOrder>
; DI void gemm_phase(LAS unsigned char* lds, const Gemm g, const Sched& S, const Epi& E) {
;     ...
;   PG8_WAIT_V(0);
;   if (wr == 0) PG8_BAR;
;   PG8_BAR;
	v_pk_add_f32 v[120:121], v[120:121], v[150:151]
	v_lshl_add_u64 v[150:151], s[54:55], 0, v[148:149]
	v_pk_add_f32 v[126:127], v[126:127], v[164:165]
	v_pk_add_f32 v[124:125], v[124:125], v[162:163]
	v_lshl_add_u64 v[150:151], v[150:151], 0, v[144:145]
	v_pk_add_f32 v[110:111], v[110:111], v[172:173]
	v_pk_add_f32 v[108:109], v[108:109], v[170:171]
	v_pk_add_f32 v[122:123], v[122:123], v[152:153]
	global_store_dwordx4 v[150:151], v[124:127], off
	global_store_dwordx4 v[150:151], v[120:123], off offset:16
	v_pk_add_f32 v[102:103], v[102:103], v[168:169]
	v_pk_add_f32 v[100:101], v[100:101], v[166:167]
	global_store_dwordx4 v[150:151], v[108:111], off offset:512
	global_store_dwordx4 v[150:151], v[100:103], off offset:528
	v_pk_add_f32 v[94:95], v[94:95], v[188:189]
	v_pk_add_f32 v[108:109], v[112:113], v[174:175]
	v_lshl_add_u64 v[112:113], s[54:55], 0, v[222:223]
	v_pk_add_f32 v[102:103], v[118:119], v[180:181]
	v_pk_add_f32 v[100:101], v[116:117], v[178:179]
	v_lshl_add_u64 v[112:113], v[112:113], 0, v[144:145]
	v_pk_add_f32 v[92:93], v[92:93], v[186:187]
	v_pk_add_f32 v[110:111], v[114:115], v[176:177]
	global_store_dwordx4 v[112:113], v[100:103], off
	global_store_dwordx4 v[112:113], v[108:111], off offset:16
	v_pk_add_f32 v[86:87], v[86:87], v[184:185]
	v_pk_add_f32 v[84:85], v[84:85], v[182:183]
	global_store_dwordx4 v[112:113], v[92:95], off offset:512
	global_store_dwordx4 v[112:113], v[84:87], off offset:528
	v_pk_add_f32 v[78:79], v[78:79], v[204:205]
	v_pk_add_f32 v[92:93], v[96:97], v[190:191]
	v_lshl_add_u64 v[96:97], s[54:55], 0, v[224:225]
	v_pk_add_f32 v[86:87], v[106:107], v[196:197]
	v_pk_add_f32 v[84:85], v[104:105], v[194:195]
	v_lshl_add_u64 v[96:97], v[96:97], 0, v[144:145]
	v_pk_add_f32 v[76:77], v[76:77], v[202:203]
	v_pk_add_f32 v[94:95], v[98:99], v[192:193]
	global_store_dwordx4 v[96:97], v[84:87], off
	global_store_dwordx4 v[96:97], v[92:95], off offset:16
	v_pk_add_f32 v[74:75], v[74:75], v[200:201]
	v_pk_add_f32 v[72:73], v[72:73], v[198:199]
	global_store_dwordx4 v[96:97], v[76:79], off offset:512
	global_store_dwordx4 v[96:97], v[72:75], off offset:528
	v_pk_add_f32 v[70:71], v[70:71], v[220:221]
	v_pk_add_f32 v[76:77], v[80:81], v[206:207]
	v_lshl_add_u64 v[80:81], s[54:55], 0, v[154:155]
	v_pk_add_f32 v[74:75], v[90:91], v[212:213]
	v_pk_add_f32 v[72:73], v[88:89], v[210:211]
	v_lshl_add_u64 v[80:81], v[80:81], 0, v[144:145]
	v_pk_add_f32 v[68:69], v[68:69], v[218:219]
	v_pk_add_f32 v[64:65], v[64:65], v[214:215]
	v_lshl_add_u64 v[154:155], v[148:149], 0, s[10:11]
	v_pk_add_f32 v[78:79], v[82:83], v[208:209]
	global_store_dwordx4 v[80:81], v[72:75], off
	global_store_dwordx4 v[80:81], v[76:79], off offset:16
	v_pk_add_f32 v[66:67], v[66:67], v[216:217]
	global_store_dwordx4 v[80:81], v[68:71], off offset:512
	global_store_dwordx4 v[80:81], v[64:67], off offset:528
	v_lshl_add_u64 v[152:153], v[148:149], 0, s[12:13]
	v_lshl_add_u64 v[150:151], v[148:149], 0, s[14:15]
	v_lshl_add_u64 v[64:65], v[146:147], 0, v[154:155]
	global_load_dwordx4 v[108:111], v[64:65], off offset:16
	global_load_dwordx4 v[120:123], v[64:65], off
	global_load_dwordx4 v[92:95], v[64:65], off offset:528
	global_load_dwordx4 v[100:103], v[64:65], off offset:512
	v_lshl_add_u64 v[64:65], v[146:147], 0, v[152:153]
	global_load_dwordx4 v[88:91], v[64:65], off offset:16
	global_load_dwordx4 v[96:99], v[64:65], off
	global_load_dwordx4 v[76:79], v[64:65], off offset:528
	global_load_dwordx4 v[84:87], v[64:65], off offset:512
	v_lshl_add_u64 v[68:69], v[146:147], 0, v[150:151]
	global_load_dwordx4 v[72:75], v[68:69], off offset:16
	global_load_dwordx4 v[80:83], v[68:69], off
	global_load_dwordx4 v[64:67], v[68:69], off offset:528
	s_nop 0
	global_load_dwordx4 v[68:71], v[68:69], off offset:512
	v_lshl_add_u64 v[148:149], v[148:149], 0, s[6:7]
	v_lshl_add_u64 v[112:113], v[146:147], 0, v[148:149]
	global_load_dwordx4 v[116:119], v[112:113], off offset:16
	global_load_dwordx4 v[124:127], v[112:113], off
	global_load_dwordx4 v[104:107], v[112:113], off offset:528
	s_nop 0
	global_load_dwordx4 v[112:115], v[112:113], off offset:512
	s_waitcnt vmcnt(0)
	v_pk_add_f32 v[56:57], v[56:57], v[108:109]
	v_lshl_add_u64 v[108:109], s[54:55], 0, v[154:155]
	v_pk_add_f32 v[62:63], v[62:63], v[122:123]
	v_pk_add_f32 v[60:61], v[60:61], v[120:121]
	v_lshl_add_u64 v[108:109], v[108:109], 0, v[144:145]
	v_pk_add_f32 v[50:51], v[50:51], v[102:103]
	v_pk_add_f32 v[48:49], v[48:49], v[100:101]
	v_pk_add_f32 v[58:59], v[58:59], v[110:111]
	global_store_dwordx4 v[108:109], v[60:63], off
	global_store_dwordx4 v[108:109], v[56:59], off offset:16
	v_pk_add_f32 v[42:43], v[42:43], v[94:95]
	v_pk_add_f32 v[40:41], v[40:41], v[92:93]
	global_store_dwordx4 v[108:109], v[48:51], off offset:512
	global_store_dwordx4 v[108:109], v[40:43], off offset:528
	v_pk_add_f32 v[34:35], v[34:35], v[86:87]
	v_lshl_add_u64 v[48:49], s[54:55], 0, v[152:153]
	v_pk_add_f32 v[42:43], v[54:55], v[98:99]
	v_pk_add_f32 v[40:41], v[52:53], v[96:97]
	v_lshl_add_u64 v[48:49], v[48:49], 0, v[144:145]
	v_pk_add_f32 v[32:33], v[32:33], v[84:85]
	v_pk_add_f32 v[46:47], v[46:47], v[90:91]
	v_pk_add_f32 v[44:45], v[44:45], v[88:89]
	global_store_dwordx4 v[48:49], v[40:43], off
	global_store_dwordx4 v[48:49], v[44:47], off offset:16
	v_pk_add_f32 v[26:27], v[26:27], v[78:79]
	v_pk_add_f32 v[24:25], v[24:25], v[76:77]
	global_store_dwordx4 v[48:49], v[32:35], off offset:512
	global_store_dwordx4 v[48:49], v[24:27], off offset:528
	v_pk_add_f32 v[18:19], v[18:19], v[70:71]
	v_lshl_add_u64 v[32:33], s[54:55], 0, v[150:151]
	v_pk_add_f32 v[26:27], v[38:39], v[82:83]
	v_pk_add_f32 v[24:25], v[36:37], v[80:81]
	v_lshl_add_u64 v[32:33], v[32:33], 0, v[144:145]
	v_pk_add_f32 v[16:17], v[16:17], v[68:69]
	v_pk_add_f32 v[30:31], v[30:31], v[74:75]
	v_pk_add_f32 v[28:29], v[28:29], v[72:73]
	global_store_dwordx4 v[32:33], v[24:27], off
	global_store_dwordx4 v[32:33], v[28:31], off offset:16
	v_pk_add_f32 v[10:11], v[10:11], v[66:67]
	v_pk_add_f32 v[8:9], v[8:9], v[64:65]
	global_store_dwordx4 v[32:33], v[16:19], off offset:512
	global_store_dwordx4 v[32:33], v[8:11], off offset:528
	v_pk_add_f32 v[6:7], v[6:7], v[114:115]
	v_lshl_add_u64 v[16:17], s[54:55], 0, v[148:149]
	v_pk_add_f32 v[10:11], v[22:23], v[126:127]
	v_pk_add_f32 v[8:9], v[20:21], v[124:125]
	v_lshl_add_u64 v[16:17], v[16:17], 0, v[144:145]
	v_pk_add_f32 v[4:5], v[4:5], v[112:113]
	v_pk_add_f32 v[14:15], v[14:15], v[118:119]
	v_pk_add_f32 v[12:13], v[12:13], v[116:117]
	global_store_dwordx4 v[16:17], v[8:11], off
	global_store_dwordx4 v[16:17], v[12:15], off offset:16
	v_pk_add_f32 v[2:3], v[2:3], v[106:107]
	v_pk_add_f32 v[0:1], v[0:1], v[104:105]
	global_store_dwordx4 v[16:17], v[4:7], off offset:512
	global_store_dwordx4 v[16:17], v[0:3], off offset:528
	s_cbranch_vccz .LBB0_1417
	s_waitcnt vmcnt(0)
	s_cmpk_gt_u32 s23, 0xff
	s_cbranch_scc1 .LBB0_1428
	s_barrier
